# plus: seam-0 counter barrier in ws instead of cg grid.sync; attention K/V LDS fragments prefetched into unused VGPRs; PEER key-score fragments loaded 16 at once
# speedup vs baseline: 1.0238x; 1.0238x over previous
; #define RUN_PH(N, SYNC)                                                    \
;   _Pragma("unroll 1") for (int rep_ = 0; rep_ < (PROBE_DUP == N ? 2 : 1); rep_++) { \
;     run_phase<N>(p, vb, nvb, smem, rep_ == 0 ? 0 : PROBE_VAR);             \
;     if (SYNC || rep_ + 1 < (PROBE_DUP == N ? 2 : 1)) { if (N == 0) grid.sync(); else xcd_barrier(xb); } \
;   }
; __global__ void __launch_bounds__(256, 2) k_main(P p) {
;     ...
;   RUN_PH(0, true)
.LBB0_49:
	s_or_b64 exec, exec, s[0:1]
	v_lshrrev_b32_e32 v1, 20, v0
	v_lshrrev_b32_e32 v0, 10, v0
	v_or_b32_e32 v0, v0, v1
	s_movk_i32 s0, 0x3ff
	v_and_or_b32 v0, v0, s0, v178
	v_cmp_eq_u32_e32 vcc, 0, v0
	s_waitcnt vmcnt(0)
	s_barrier
	s_and_saveexec_b64 s[0:1], vcc
	s_cbranch_execz .LBB0_59
	buffer_wbl2 sc1
	s_waitcnt vmcnt(0)
	v_mov_b32_e32 v2, 0
	v_mov_b32_e32 v3, 1
	global_atomic_add v2, v3, s[26:27] offset:256
	s_mov_b64 s[8:9], exec
	s_mov_b64 s[6:7], 0
	s_mov_b32 s4, 0
.Lsync0_spin:
	s_sleep 1
	global_load_dword v0, v2, s[26:27] offset:256 sc1
	s_add_i32 s4, s4, 1
	s_cmp_gt_u32 s4, 0x40000
	s_cbranch_scc1 .Lsync0_done
	s_waitcnt vmcnt(0)
	v_cmp_eq_u32_e32 vcc, s82, v0
	s_or_b64 s[6:7], vcc, s[6:7]
	s_andn2_b64 exec, exec, s[6:7]
	s_cbranch_execnz .Lsync0_spin
.Lsync0_done:
	s_mov_b64 exec, s[8:9]
	s_waitcnt vmcnt(0)
	buffer_inv sc1
	s_waitcnt vmcnt(0)

; __device__ void phase_attn(const P& p, int vb, int nvb, char* smem) {
;     ...
;         for (int s = 0; s < 6; s++) {
;           const bf16x8 k0f = *(const bf16x8*)(kl + ((lr)*KP + 16 * s + 8 * lh) * 2);
;           const bf16x8 k1f = *(const bf16x8*)(kl + ((32 + lr) * KP + 16 * s + 8 * lh) * 2);
;           s0 = __builtin_amdgcn_mfma_f32_32x32x16_bf16(k0f, qf[s].v, s0, 0, 0, 0);
;           s1 = __builtin_amdgcn_mfma_f32_32x32x16_bf16(k1f, qf[s].v, s1, 0, 0, 0);
;         }
;         if (k0 + 63 > qlo) {
; #pragma unroll
;           for (int r = 0; r < 16; r++) {
;             const int key = k0 + (r & 3) + 8 * (r >> 2) + 4 * lh;
;             if (key > qrow) s0[r] = -INFINITY;
;             if (key + 32 > qrow) s1[r] = -INFINITY;
;           }
.LBB0_287:
	v_cmp_le_i32_e32 vcc, s51, v115
	s_and_b32 s28, s36, 1
	s_and_b64 s[42:43], s[30:31], vcc
	s_and_saveexec_b64 s[36:37], s[42:43]
	s_cbranch_execz .LBB0_293
	s_mul_i32 s42, s28, 0x5600
	s_add_i32 s66, s42, 16
	v_add_u32_e32 v126, s66, v137
	ds_read_b128 v[180:183], v126
	ds_read_b128 v[184:187], v126 offset:6656
	ds_read_b128 v[188:191], v126 offset:32
	ds_read_b128 v[192:195], v126 offset:6688
	ds_read_b128 v[196:199], v126 offset:64
	ds_read_b128 v[200:203], v126 offset:6720
	ds_read_b128 v[204:207], v126 offset:96
	ds_read_b128 v[208:211], v126 offset:6752
	ds_read_b128 v[212:215], v126 offset:128
	ds_read_b128 v[216:219], v126 offset:6784
	ds_read_b128 v[220:223], v126 offset:160
	ds_read_b128 v[224:227], v126 offset:6816
	v_add_u32_e32 v176, s66, v138
	s_add_i32 s42, s51, 63
	v_add_u32_e32 v177, 0x4000, v176
	v_add_u32_e32 v176, 0x3000, v176
	v_cmp_gt_i32_e32 vcc, s42, v145
	s_waitcnt lgkmcnt(11)
	v_mfma_f32_32x32x16_bf16 v[48:63], v[180:183], v[64:67], 0
	s_waitcnt lgkmcnt(10)
	v_mfma_f32_32x32x16_bf16 v[32:47], v[184:187], v[64:67], 0
	ds_read2_b64 v[228:231], v176 offset0:128 offset1:130
	s_waitcnt lgkmcnt(10)
	v_mfma_f32_32x32x16_bf16 v[48:63], v[188:191], v[68:71], v[48:63]
	ds_read2_b64 v[236:239], v177 offset0:160 offset1:162
	s_waitcnt lgkmcnt(10)
	v_mfma_f32_32x32x16_bf16 v[32:47], v[192:195], v[68:71], v[32:47]
	ds_read2_b64 v[232:235], v176 offset0:132 offset1:134
	s_waitcnt lgkmcnt(10)
	v_mfma_f32_32x32x16_bf16 v[48:63], v[196:199], v[72:75], v[48:63]
	ds_read2_b64 v[240:243], v177 offset0:164 offset1:166
	s_waitcnt lgkmcnt(10)
	v_mfma_f32_32x32x16_bf16 v[32:47], v[200:203], v[72:75], v[32:47]
	ds_read2_b64 v[244:247], v176 offset0:136 offset1:138
	s_waitcnt lgkmcnt(10)
	v_mfma_f32_32x32x16_bf16 v[48:63], v[204:207], v[76:79], v[48:63]
	ds_read2_b64 v[164:167], v177 offset0:168 offset1:170
	s_waitcnt lgkmcnt(10)
	v_mfma_f32_32x32x16_bf16 v[32:47], v[208:211], v[76:79], v[32:47]
	ds_read2_b64 v[168:171], v176 offset0:140 offset1:142
	s_waitcnt lgkmcnt(10)
	v_mfma_f32_32x32x16_bf16 v[48:63], v[212:215], v[80:83], v[48:63]
	ds_read2_b64 v[172:175], v177 offset0:172 offset1:174
	s_waitcnt lgkmcnt(10)
	v_mfma_f32_32x32x16_bf16 v[32:47], v[216:219], v[80:83], v[32:47]
	s_waitcnt lgkmcnt(9)
	v_mfma_f32_32x32x16_bf16 v[48:63], v[220:223], v[84:87], v[48:63]
	s_waitcnt lgkmcnt(8)
	v_mfma_f32_32x32x16_bf16 v[32:47], v[224:227], v[84:87], v[32:47]
	s_and_saveexec_b64 s[42:43], vcc
	s_cbranch_execz .LBB0_290
	v_add_u32_e32 v126, s51, v136
	v_add_u32_e32 v147, 32, v126
	v_cmp_le_i32_e32 vcc, v147, v146
	v_add_u32_e32 v147, 33, v126
	s_nop 5
	v_cndmask_b32_e32 v32, v144, v32, vcc
	v_cmp_lt_i32_e32 vcc, v126, v146
	s_nop 1
	v_cndmask_b32_e32 v49, v144, v49, vcc
	v_cmp_le_i32_e32 vcc, v126, v146
	s_nop 1
	v_cndmask_b32_e32 v48, v144, v48, vcc
	v_cmp_le_i32_e32 vcc, v147, v146
	v_add_u32_e32 v147, 2, v126
	s_nop 0
	v_cndmask_b32_e32 v33, v144, v33, vcc
	v_cmp_le_i32_e32 vcc, v147, v146
	v_add_u32_e32 v147, 34, v126
	s_nop 0
	v_cndmask_b32_e32 v50, v144, v50, vcc
	v_cmp_le_i32_e32 vcc, v147, v146
	v_add_u32_e32 v147, 3, v126
	s_nop 0
	v_cndmask_b32_e32 v34, v144, v34, vcc
	v_cmp_le_i32_e32 vcc, v147, v146
	v_add_u32_e32 v147, 35, v126
	s_nop 0
	v_cndmask_b32_e32 v51, v144, v51, vcc
	v_cmp_le_i32_e32 vcc, v147, v146
	v_add_u32_e32 v147, 8, v126
	s_nop 0
	v_cndmask_b32_e32 v35, v144, v35, vcc
	v_cmp_le_i32_e32 vcc, v147, v146
	v_add_u32_e32 v147, 40, v126
	s_nop 0
	v_cndmask_b32_e32 v52, v144, v52, vcc
	v_cmp_le_i32_e32 vcc, v147, v146
	v_add_u32_e32 v147, 9, v126
	s_nop 0
	v_cndmask_b32_e32 v36, v144, v36, vcc
	v_cmp_le_i32_e32 vcc, v147, v146
	v_add_u32_e32 v147, 41, v126
	s_nop 0
	v_cndmask_b32_e32 v53, v144, v53, vcc
	v_cmp_le_i32_e32 vcc, v147, v146
	v_add_u32_e32 v147, 10, v126
	s_nop 0
	v_cndmask_b32_e32 v37, v144, v37, vcc
	v_cmp_le_i32_e32 vcc, v147, v146
	v_add_u32_e32 v147, 42, v126
	s_nop 0
	v_cndmask_b32_e32 v54, v144, v54, vcc
	v_cmp_le_i32_e32 vcc, v147, v146
	v_add_u32_e32 v147, 11, v126
	s_nop 0
	v_cndmask_b32_e32 v38, v144, v38, vcc
	v_cmp_le_i32_e32 vcc, v147, v146
	v_add_u32_e32 v147, 43, v126
	s_nop 0
	v_cndmask_b32_e32 v55, v144, v55, vcc
	v_cmp_le_i32_e32 vcc, v147, v146
	v_add_u32_e32 v147, 16, v126
	s_nop 0
	v_cndmask_b32_e32 v39, v144, v39, vcc
	v_cmp_le_i32_e32 vcc, v147, v146
	v_add_u32_e32 v147, 48, v126
	s_nop 0
	v_cndmask_b32_e32 v56, v144, v56, vcc
	v_cmp_le_i32_e32 vcc, v147, v146
	v_add_u32_e32 v147, 17, v126
	s_nop 0
	v_cndmask_b32_e32 v40, v144, v40, vcc
	v_cmp_le_i32_e32 vcc, v147, v146
	v_add_u32_e32 v147, 49, v126
	s_nop 0
	v_cndmask_b32_e32 v57, v144, v57, vcc
	v_cmp_le_i32_e32 vcc, v147, v146
	v_add_u32_e32 v147, 18, v126
	s_nop 0
	v_cndmask_b32_e32 v41, v144, v41, vcc
	v_cmp_le_i32_e32 vcc, v147, v146
	v_add_u32_e32 v147, 50, v126
	s_nop 0
	v_cndmask_b32_e32 v58, v144, v58, vcc
	v_cmp_le_i32_e32 vcc, v147, v146
	v_add_u32_e32 v147, 19, v126
	s_nop 0
	v_cndmask_b32_e32 v42, v144, v42, vcc
	v_cmp_le_i32_e32 vcc, v147, v146
	v_add_u32_e32 v147, 51, v126
	s_nop 0
	v_cndmask_b32_e32 v59, v144, v59, vcc
	v_cmp_le_i32_e32 vcc, v147, v146
	v_add_u32_e32 v147, 24, v126
	s_nop 0
	v_cndmask_b32_e32 v43, v144, v43, vcc
	v_cmp_le_i32_e32 vcc, v147, v146
	v_add_u32_e32 v147, 56, v126
	s_nop 0
	v_cndmask_b32_e32 v60, v144, v60, vcc
	v_cmp_le_i32_e32 vcc, v147, v146
	v_add_u32_e32 v147, 25, v126
	s_nop 0
	v_cndmask_b32_e32 v44, v144, v44, vcc
	v_cmp_le_i32_e32 vcc, v147, v146
	v_add_u32_e32 v147, 57, v126
	s_nop 0
	v_cndmask_b32_e32 v61, v144, v61, vcc
	v_cmp_le_i32_e32 vcc, v147, v146
	v_add_u32_e32 v147, 26, v126
	s_nop 0
	v_cndmask_b32_e32 v45, v144, v45, vcc
	v_cmp_le_i32_e32 vcc, v147, v146
	v_add_u32_e32 v147, 58, v126
	s_nop 0
	v_cndmask_b32_e32 v62, v144, v62, vcc
	v_cmp_le_i32_e32 vcc, v147, v146
	v_add_u32_e32 v147, 27, v126
	v_add_u32_e32 v126, 59, v126
	v_cndmask_b32_e32 v46, v144, v46, vcc
	v_cmp_le_i32_e32 vcc, v147, v146
	s_nop 1
	v_cndmask_b32_e32 v63, v144, v63, vcc
	v_cmp_le_i32_e32 vcc, v126, v146
	s_nop 1
	v_cndmask_b32_e32 v47, v144, v47, vcc

; DEVI uint32_t pk(float a, float b) { const hwf32x2 v = {a, b}; return __builtin_bit_cast(uint32_t, __builtin_convertvector(v, hwbf16x2)); }
; __device__ void phase_attn(const P& p, int vb, int nvb, char* smem) {
;     ...
;         const float alpha = __builtin_amdgcn_exp2f(m - mn);
;         const bool moved = __builtin_amdgcn_ballot_w64(mn > m) != 0ull;
;         m = mn;
;         float psum = 0.f;
; #pragma unroll
;         for (int r = 0; r < 16; r++) {
;           s0[r] = __builtin_amdgcn_exp2f(s0[r] - mn); s1[r] = __builtin_amdgcn_exp2f(s1[r] - mn);
;           psum += s0[r] + s1[r];
;         }
;         l = l * alpha + psum;
;         if (moved) { o0 *= alpha; o1 *= alpha; }
; #pragma unroll
;         for (int kk = 0; kk < 2; kk++)
; #pragma unroll
;           for (int s2 = 0; s2 < 2; s2++) {
;             Frag pf;
; #pragma unroll
;             for (int e = 0; e < 4; e++) pf.u[e] = kk == 0 ? pk(s0[8 * s2 + 2 * e], s0[8 * s2 + 2 * e + 1]) : pk(s1[8 * s2 + 2 * e], s1[8 * s2 + 2 * e + 1]);
;             Frag v0f, v1f;
;             const char* vp0 = vl + ((lr)*VP + 32 * kk + 16 * s2 + 4 * lh) * 2;
;             const char* vp1 = vl + ((32 + lr) * VP + 32 * kk + 16 * s2 + 4 * lh) * 2;
;             v0f.d[0] = *(const uint2*)vp0; v0f.d[1] = *(const uint2*)(vp0 + 16);
;             v1f.d[0] = *(const uint2*)vp1; v1f.d[1] = *(const uint2*)(vp1 + 16);
;             o0 = __builtin_amdgcn_mfma_f32_32x32x16_bf16(v0f.v, pf.v, o0, 0, 0, 0);
;             o1 = __builtin_amdgcn_mfma_f32_32x32x16_bf16(v1f.v, pf.v, o1, 0, 0, 0);
;           }
.LBB0_292:
	v_sub_f32_e32 v48, v48, v147
	v_sub_f32_e32 v32, v32, v147
	v_exp_f32_e32 v48, v48
	v_exp_f32_e32 v149, v32
	v_sub_f32_e32 v49, v49, v147
	v_sub_f32_e32 v33, v33, v147
	v_exp_f32_e32 v49, v49
	v_exp_f32_e32 v150, v33
	v_add_f32_e32 v32, v149, v48
	v_add_f32_e32 v32, 0, v32
	v_sub_f32_e32 v34, v34, v147
	v_add_f32_e32 v33, v150, v49
	v_add_f32_e32 v32, v33, v32
	v_sub_f32_e32 v33, v50, v147
	v_exp_f32_e32 v33, v33
	v_exp_f32_e32 v50, v34
	v_sub_f32_e32 v35, v35, v147
	v_sub_f32_e32 v36, v36, v147
	v_sub_f32_e32 v37, v37, v147
	v_add_f32_e32 v34, v50, v33
	v_add_f32_e32 v32, v34, v32
	v_sub_f32_e32 v34, v51, v147
	v_exp_f32_e32 v34, v34
	v_exp_f32_e32 v51, v35
	v_sub_f32_e32 v38, v38, v147
	v_sub_f32_e32 v39, v39, v147
	v_cvt_pk_bf16_f32 v33, v33, v34
	v_add_f32_e32 v35, v51, v34
	v_add_f32_e32 v32, v35, v32
	v_sub_f32_e32 v35, v52, v147
	v_exp_f32_e32 v35, v35
	v_exp_f32_e32 v52, v36
	s_nop 0
	v_add_f32_e32 v36, v52, v35
	v_add_f32_e32 v32, v36, v32
	v_sub_f32_e32 v36, v53, v147
	v_exp_f32_e32 v36, v36
	v_exp_f32_e32 v53, v37
	v_cvt_pk_bf16_f32 v34, v35, v36
	v_add_f32_e32 v37, v53, v36
	v_add_f32_e32 v32, v37, v32
	v_sub_f32_e32 v37, v54, v147
	v_exp_f32_e32 v37, v37
	v_exp_f32_e32 v54, v38
	s_nop 0
	v_add_f32_e32 v38, v54, v37
	v_add_f32_e32 v32, v38, v32
	v_sub_f32_e32 v38, v55, v147
	v_exp_f32_e32 v38, v38
	v_exp_f32_e32 v55, v39
	v_cvt_pk_bf16_f32 v35, v37, v38
	v_add_f32_e32 v39, v55, v38
	v_add_f32_e32 v32, v39, v32
	v_sub_f32_e32 v39, v56, v147
	v_exp_f32_e32 v56, v39
	v_sub_f32_e32 v39, v40, v147
	v_exp_f32_e32 v151, v39
	s_nop 0
	v_add_f32_e32 v39, v151, v56
	v_add_f32_e32 v32, v39, v32
	v_sub_f32_e32 v39, v57, v147
	v_exp_f32_e32 v57, v39
	v_sub_f32_e32 v39, v41, v147
	v_exp_f32_e32 v152, v39
	s_nop 0
	v_add_f32_e32 v39, v152, v57
	v_add_f32_e32 v32, v39, v32
	v_sub_f32_e32 v39, v58, v147
	v_exp_f32_e32 v58, v39
	v_sub_f32_e32 v39, v42, v147
	v_exp_f32_e32 v153, v39
	s_nop 0
	v_add_f32_e32 v39, v153, v58
	v_add_f32_e32 v32, v39, v32
	v_sub_f32_e32 v39, v59, v147
	v_exp_f32_e32 v59, v39
	v_sub_f32_e32 v39, v43, v147
	v_exp_f32_e32 v154, v39
	s_nop 0
	v_add_f32_e32 v39, v154, v59
	v_add_f32_e32 v32, v39, v32
	v_sub_f32_e32 v39, v60, v147
	v_exp_f32_e32 v60, v39
	v_sub_f32_e32 v39, v44, v147
	v_exp_f32_e32 v155, v39
	v_add_u32_e32 v44, s66, v138
	v_add_f32_e32 v39, v155, v60
	v_add_f32_e32 v32, v39, v32
	v_sub_f32_e32 v39, v61, v147
	v_exp_f32_e32 v61, v39
	v_sub_f32_e32 v39, v45, v147
	v_exp_f32_e32 v156, v39
	s_nop 0
	v_add_f32_e32 v39, v156, v61
	v_add_f32_e32 v32, v39, v32
	v_sub_f32_e32 v39, v62, v147
	v_exp_f32_e32 v62, v39
	v_sub_f32_e32 v39, v46, v147
	v_exp_f32_e32 v157, v39
	s_nop 0
	v_add_f32_e32 v39, v157, v62
	v_add_f32_e32 v32, v39, v32
	v_sub_f32_e32 v39, v63, v147
	v_exp_f32_e32 v63, v39
	v_sub_f32_e32 v39, v47, v147
	v_exp_f32_e32 v158, v39
	s_nop 0
	v_add_f32_e32 v39, v158, v63
	v_add_f32_e32 v159, v39, v32
	v_cvt_pk_bf16_f32 v32, v48, v49
	s_waitcnt lgkmcnt(0)
	s_nop 0
	v_mfma_f32_32x32x16_bf16 v[16:31], v[228:231], v[32:35], v[16:31]
	v_fmac_f32_e32 v159, v148, v126
	v_mov_b32_e32 v148, v159
	v_mfma_f32_32x32x16_bf16 v[0:15], v[236:239], v[32:35], v[0:15]
	v_cvt_pk_bf16_f32 v32, v56, v57
	v_cvt_pk_bf16_f32 v33, v58, v59
	v_cvt_pk_bf16_f32 v34, v60, v61
	v_cvt_pk_bf16_f32 v35, v62, v63
	s_nop 1
	v_mfma_f32_32x32x16_bf16 v[16:31], v[232:235], v[32:35], v[16:31]
	v_mfma_f32_32x32x16_bf16 v[0:15], v[240:243], v[32:35], v[0:15]
	v_cvt_pk_bf16_f32 v32, v149, v150
	v_cvt_pk_bf16_f32 v33, v50, v51
	v_cvt_pk_bf16_f32 v34, v52, v53
	v_cvt_pk_bf16_f32 v35, v54, v55
	v_mov_b32_e32 v149, v147
	s_nop 0
	v_mfma_f32_32x32x16_bf16 v[16:31], v[244:247], v[32:35], v[16:31]
	v_mfma_f32_32x32x16_bf16 v[0:15], v[164:167], v[32:35], v[0:15]
	v_cvt_pk_bf16_f32 v32, v151, v152
	v_cvt_pk_bf16_f32 v33, v153, v154
	v_cvt_pk_bf16_f32 v34, v155, v156
	v_cvt_pk_bf16_f32 v35, v157, v158
	s_nop 1
	v_mfma_f32_32x32x16_bf16 v[16:31], v[168:171], v[32:35], v[16:31]
	v_mfma_f32_32x32x16_bf16 v[0:15], v[172:175], v[32:35], v[0:15]

; DEVI uint32_t f2sort(float f) { return __float_as_uint(f); }
; __device__ void phase_peer_q(const P& p, int vb, int nvb, char* smem) {
;     ...
;         for (int ks = 0; ks < 4; ks++) {
;           Frag qfr; qfr.q = *(const uint4*)(smem + tk * 272 + (pp * 64 + 16 * ks + 8 * lh2) * 2);
; #pragma unroll
;           for (int nt = 0; nt < 4; nt++) {
;             Frag kf; kf.q = *(const uint4*)(keys + ((size_t)((hd * 2 + pp) * 128 + 32 * nt + lr2)) * 64 + 16 * ks + 8 * lh2);
;             sc[nt] = __builtin_amdgcn_mfma_f32_32x32x16_bf16(kf.v, qfr.v, sc[nt], 0, 0, 0);
;           }
;           if (ks & 1) __builtin_amdgcn_sched_barrier(0);
;         }
;         uint32_t g0[16], g1[16], g2[16], g3[16];
; #pragma unroll
;         for (int r = 0; r < 16; r++) {
;           const uint32_t n = (uint32_t)((r & 3) + 8 * (r >> 2) + 4 * lh2);
;           g0[r] = (f2sort(sc[0][r]) & ~127u) | n;
;           g1[r] = (f2sort(sc[1][r]) & ~127u) | (n + 32u);
;           g2[r] = (f2sort(sc[2][r]) & ~127u) | (n + 64u);
;           g3[r] = (f2sort(sc[3][r]) & ~127u) | (n + 96u);
;         }
.LBB0_437:
	s_lshl_b32 s38, s39, 6
	s_or_b32 s39, s39, s47
	v_lshl_or_b32 v1, s39, 13, v79
	v_or_b32_e32 v0, s38, v64
	v_lshlrev_b32_e32 v144, 1, v1
	v_lshl_add_u32 v143, v0, 1, v77
	s_mov_b64 s[98:99], 0x1000
	s_mov_b64 s[100:101], 0x3000
	v_lshl_add_u64 v[158:159], v[66:67], 0, v[144:145]
	ds_read_b128 v[48:51], v143
	ds_read_b128 v[146:149], v143 offset:32
	ds_read_b128 v[150:153], v143 offset:64
	v_lshl_add_u64 v[154:155], v[158:159], 0, s[98:99]
	v_lshl_add_u64 v[156:157], v[158:159], 0, s[100:101]
	global_load_dwordx4 v[0:3], v[154:155], off offset:-4096
	global_load_dwordx4 v[16:19], v[154:155], off
	global_load_dwordx4 v[32:35], v[156:157], off offset:-4096
	global_load_dwordx4 v[52:55], v[156:157], off
	global_load_dwordx4 v[206:209], v[154:155], off offset:-4064
	global_load_dwordx4 v[210:213], v[154:155], off offset:32
	global_load_dwordx4 v[214:217], v[156:157], off offset:-4064
	global_load_dwordx4 v[218:221], v[156:157], off offset:32
	global_load_dwordx4 v[222:225], v[154:155], off offset:-4032
	global_load_dwordx4 v[226:229], v[154:155], off offset:64
	global_load_dwordx4 v[230:233], v[156:157], off offset:-4032
	global_load_dwordx4 v[234:237], v[156:157], off offset:64
	global_load_dwordx4 v[238:241], v[154:155], off offset:-4000
	global_load_dwordx4 v[242:245], v[154:155], off offset:96
	global_load_dwordx4 v[250:253], v[156:157], off offset:-4000
	global_load_dwordx4 v[166:169], v[156:157], off offset:96
	s_mov_b32 s39, 1
	s_waitcnt vmcnt(15) lgkmcnt(2)
	v_mfma_f32_32x32x16_bf16 v[0:15], v[0:3], v[48:51], 0
	s_waitcnt vmcnt(14)
	v_mfma_f32_32x32x16_bf16 v[16:31], v[16:19], v[48:51], 0
	s_waitcnt vmcnt(13)
	v_mfma_f32_32x32x16_bf16 v[32:47], v[32:35], v[48:51], 0
	s_waitcnt vmcnt(12)
	v_mfma_f32_32x32x16_bf16 v[48:63], v[52:55], v[48:51], 0
	s_waitcnt vmcnt(11) lgkmcnt(1)
	v_mfma_f32_32x32x16_bf16 v[0:15], v[206:209], v[146:149], v[0:15]
	s_waitcnt vmcnt(10)
	v_mfma_f32_32x32x16_bf16 v[16:31], v[210:213], v[146:149], v[16:31]
	s_waitcnt vmcnt(9)
	v_mfma_f32_32x32x16_bf16 v[32:47], v[214:217], v[146:149], v[32:47]
	s_waitcnt vmcnt(8)
	v_mfma_f32_32x32x16_bf16 v[48:63], v[218:221], v[146:149], v[48:63]
	ds_read_b128 v[146:149], v143 offset:96
	s_waitcnt vmcnt(7) lgkmcnt(1)
	v_mfma_f32_32x32x16_bf16 v[0:15], v[222:225], v[150:153], v[0:15]
	s_waitcnt vmcnt(6)
	v_mfma_f32_32x32x16_bf16 v[16:31], v[226:229], v[150:153], v[16:31]
	s_waitcnt vmcnt(5)
	v_mfma_f32_32x32x16_bf16 v[32:47], v[230:233], v[150:153], v[32:47]
	s_waitcnt vmcnt(4)
	v_mfma_f32_32x32x16_bf16 v[48:63], v[234:237], v[150:153], v[48:63]
	s_waitcnt vmcnt(3) lgkmcnt(0)
	v_mfma_f32_32x32x16_bf16 v[0:15], v[238:241], v[146:149], v[0:15]
	s_waitcnt vmcnt(2)
	v_mfma_f32_32x32x16_bf16 v[16:31], v[242:245], v[146:149], v[16:31]
	s_waitcnt vmcnt(1)
	v_mfma_f32_32x32x16_bf16 v[32:47], v[250:253], v[146:149], v[32:47]
	s_waitcnt vmcnt(0)
	v_mfma_f32_32x32x16_bf16 v[48:63], v[166:169], v[146:149], v[48:63]
	s_nop 4
	s_nop 0
	v_and_or_b32 v143, v0, s43, v78
	s_nop 2
	v_and_or_b32 v144, v16, s43, v80
	s_nop 2
	v_and_or_b32 v146, v32, s43, v81
	s_nop 1
	v_and_or_b32 v0, v48, s43, v82
	v_and_or_b32 v16, v1, s43, v83
	v_and_or_b32 v48, v17, s43, v84
	v_and_or_b32 v147, v33, s43, v85
	v_and_or_b32 v1, v49, s43, v86
	v_and_or_b32 v17, v2, s43, v87
	v_and_or_b32 v49, v18, s43, v88
	v_and_or_b32 v148, v34, s43, v89
	v_and_or_b32 v2, v50, s43, v90
	v_and_or_b32 v18, v3, s43, v91
	v_and_or_b32 v50, v19, s43, v92
	v_and_or_b32 v149, v35, s43, v93
	v_and_or_b32 v3, v51, s43, v94
	v_and_or_b32 v19, v4, s43, v95
	v_and_or_b32 v51, v20, s43, v96
	v_and_or_b32 v150, v36, s43, v97
	v_and_or_b32 v4, v52, s43, v98
	v_and_or_b32 v20, v5, s43, v99
	v_and_or_b32 v52, v21, s43, v100
	v_and_or_b32 v151, v37, s43, v101
	v_and_or_b32 v5, v53, s43, v102
	v_and_or_b32 v21, v6, s43, v103
	v_and_or_b32 v53, v22, s43, v104
	v_and_or_b32 v152, v38, s43, v105
	v_and_or_b32 v6, v54, s43, v106
	v_and_or_b32 v22, v7, s43, v107
	v_and_or_b32 v54, v23, s43, v108
	v_and_or_b32 v153, v39, s43, v109
	v_and_or_b32 v7, v55, s43, v110
	v_and_or_b32 v23, v8, s43, v111
	v_and_or_b32 v55, v24, s43, v112
	v_and_or_b32 v40, v40, s43, v113
	v_and_or_b32 v8, v56, s43, v114
	v_and_or_b32 v24, v9, s43, v115
	v_and_or_b32 v56, v25, s43, v116
	v_and_or_b32 v41, v41, s43, v117
	v_and_or_b32 v9, v57, s43, v118
	v_and_or_b32 v25, v10, s43, v119
	v_and_or_b32 v57, v26, s43, v120
	v_and_or_b32 v42, v42, s43, v121
	v_and_or_b32 v10, v58, s43, v122
	v_and_or_b32 v26, v11, s43, v123
	v_and_or_b32 v58, v27, s43, v124
	v_and_or_b32 v43, v43, s43, v125
	v_and_or_b32 v11, v59, s43, v126
	v_and_or_b32 v27, v12, s43, v127
	v_and_or_b32 v59, v28, s43, v128
	v_and_or_b32 v44, v44, s43, v129
	v_and_or_b32 v12, v60, s43, v130
	v_and_or_b32 v28, v13, s43, v131
	v_and_or_b32 v60, v29, s43, v132
	v_and_or_b32 v45, v45, s43, v133
	v_and_or_b32 v13, v61, s43, v134
	v_and_or_b32 v29, v14, s43, v135
	v_and_or_b32 v61, v30, s43, v136
	v_and_or_b32 v46, v46, s43, v137
	v_and_or_b32 v14, v62, s43, v138
	v_and_or_b32 v30, v15, s43, v139
	v_and_or_b32 v62, v31, s43, v140
	v_and_or_b32 v47, v47, s43, v141
	v_and_or_b32 v15, v63, s43, v142
	v_max_f32_e32 v16, v16, v16
	v_max_f32_e32 v31, v143, v143
	v_max_f32_e32 v17, v17, v17
	v_max_f32_e32 v18, v18, v18
	v_max_f32_e32 v48, v48, v48
	v_max_f32_e32 v63, v144, v144
	v_max_f32_e32 v49, v49, v49
	v_max_f32_e32 v50, v50, v50
	v_max_f32_e32 v32, v31, v16
	v_min_f32_e32 v16, v31, v16
	v_max_f32_e32 v31, v18, v17
	v_min_f32_e32 v17, v18, v17
	v_max_f32_e32 v18, v20, v20
	v_max_f32_e32 v19, v19, v19
	v_max_f32_e32 v143, v63, v48
	v_min_f32_e32 v48, v63, v48
	v_max_f32_e32 v63, v50, v49
	v_min_f32_e32 v49, v50, v49
; #define CE_DESC(x, y) { const float a_ = __uint_as_float(x), b_ = __uint_as_float(y); (x) = __float_as_uint(__builtin_fmaxf(a_, b_)); (y) = __float_as_uint(__builtin_fminf(a_, b_)); }
; DEVI void sort16_desc(uint32_t (&a)[16]) {
; #pragma unroll
;   for (int k = 2; k <= 16; k <<= 1) {
; #pragma unroll
;     for (int j = k >> 1; j > 0; j >>= 1) {
; #pragma unroll
;       for (int i = 0; i < 16; i++) {
;         const int l = i ^ j;
;         if (l > i) { if ((i & k) == 0) CE_DESC(a[i], a[l]) else CE_DESC(a[l], a[i]) }
;       }
;     }
;   }
; }
	v_max_f32_e32 v50, v52, v52
	v_max_f32_e32 v51, v51, v51
	v_max_f32_e32 v20, v19, v18
	v_min_f32_e32 v18, v19, v18
	v_max_f32_e32 v19, v21, v21
	v_max_f32_e32 v21, v22, v22
	v_max_f32_e32 v52, v51, v50
	v_min_f32_e32 v50, v51, v50
	v_max_f32_e32 v51, v53, v53
	v_max_f32_e32 v53, v54, v54
	v_max_f32_e32 v22, v21, v19
	v_min_f32_e32 v19, v21, v19
	v_max_f32_e32 v21, v24, v24
	v_max_f32_e32 v23, v23, v23
	v_max_f32_e32 v54, v53, v51
	v_min_f32_e32 v51, v53, v51
	v_max_f32_e32 v53, v56, v56
	v_max_f32_e32 v55, v55, v55
	v_max_f32_e32 v24, v23, v21
	v_min_f32_e32 v21, v23, v21
	v_max_f32_e32 v23, v25, v25
	v_max_f32_e32 v25, v26, v26
	v_max_f32_e32 v56, v55, v53
	v_min_f32_e32 v53, v55, v53
	v_max_f32_e32 v55, v57, v57
	v_max_f32_e32 v57, v58, v58
	v_max_f32_e32 v26, v25, v23
	v_min_f32_e32 v23, v25, v23
	v_max_f32_e32 v25, v28, v28
	v_max_f32_e32 v27, v27, v27
	v_max_f32_e32 v58, v57, v55
	v_min_f32_e32 v55, v57, v55
	v_max_f32_e32 v57, v60, v60
	v_max_f32_e32 v59, v59, v59
	v_max_f32_e32 v28, v27, v25
	v_min_f32_e32 v25, v27, v25
	v_max_f32_e32 v27, v29, v29
	v_max_f32_e32 v29, v30, v30
	v_max_f32_e32 v60, v59, v57
	v_min_f32_e32 v57, v59, v57
	v_max_f32_e32 v59, v61, v61
	v_max_f32_e32 v61, v62, v62
	v_max_f32_e32 v30, v29, v27
	v_min_f32_e32 v27, v29, v27
	v_max_f32_e32 v62, v61, v59
	v_min_f32_e32 v59, v61, v59
	v_max_f32_e32 v29, v32, v17
	v_min_f32_e32 v17, v32, v17
	v_max_f32_e32 v32, v16, v31
	v_min_f32_e32 v16, v16, v31
	v_max_f32_e32 v31, v19, v20
	v_min_f32_e32 v19, v19, v20
	v_max_f32_e32 v20, v22, v18
	v_min_f32_e32 v18, v22, v18
	v_max_f32_e32 v22, v24, v23
	v_min_f32_e32 v23, v24, v23
	v_max_f32_e32 v24, v21, v26
	v_min_f32_e32 v21, v21, v26
	v_max_f32_e32 v26, v27, v28
	v_min_f32_e32 v27, v27, v28
	v_max_f32_e32 v28, v30, v25
	v_min_f32_e32 v25, v30, v25
	v_max_f32_e32 v61, v143, v49
	v_min_f32_e32 v49, v143, v49
	v_max_f32_e32 v143, v48, v63
	v_min_f32_e32 v48, v48, v63
	v_max_f32_e32 v63, v51, v52
	v_min_f32_e32 v51, v51, v52
	v_max_f32_e32 v52, v54, v50
	v_min_f32_e32 v50, v54, v50
	v_max_f32_e32 v54, v56, v55
	v_min_f32_e32 v55, v56, v55
	v_max_f32_e32 v56, v53, v58
	v_min_f32_e32 v53, v53, v58
	v_max_f32_e32 v58, v59, v60
	v_min_f32_e32 v59, v59, v60
	v_max_f32_e32 v60, v62, v57
	v_min_f32_e32 v57, v62, v57
	v_max_f32_e32 v30, v29, v32
	v_min_f32_e32 v29, v29, v32
	v_max_f32_e32 v32, v17, v16
	v_min_f32_e32 v16, v17, v16
	v_max_f32_e32 v17, v18, v19
	v_min_f32_e32 v18, v18, v19
	v_max_f32_e32 v19, v20, v31
	v_min_f32_e32 v20, v20, v31
	v_max_f32_e32 v31, v22, v24
	v_min_f32_e32 v22, v22, v24
	v_max_f32_e32 v24, v23, v21
	v_min_f32_e32 v21, v23, v21
	v_max_f32_e32 v23, v25, v27
	v_min_f32_e32 v25, v25, v27
	v_max_f32_e32 v27, v28, v26
	v_min_f32_e32 v26, v28, v26
	v_max_f32_e32 v62, v61, v143
	v_min_f32_e32 v61, v61, v143
	v_max_f32_e32 v143, v49, v48
	v_min_f32_e32 v48, v49, v48
	v_max_f32_e32 v49, v50, v51
	v_min_f32_e32 v50, v50, v51
	v_max_f32_e32 v51, v52, v63
	v_min_f32_e32 v52, v52, v63
	v_max_f32_e32 v63, v54, v56
	v_min_f32_e32 v54, v54, v56
	v_max_f32_e32 v56, v55, v53
	v_min_f32_e32 v53, v55, v53
	v_max_f32_e32 v55, v57, v59
	v_min_f32_e32 v57, v57, v59
	v_max_f32_e32 v59, v60, v58
	v_min_f32_e32 v58, v60, v58
	v_max_f32_e32 v28, v30, v18
	v_min_f32_e32 v18, v30, v18
	v_max_f32_e32 v30, v29, v17
	v_min_f32_e32 v17, v29, v17
	v_max_f32_e32 v29, v32, v20
	v_min_f32_e32 v20, v32, v20
	v_max_f32_e32 v32, v16, v19
	v_min_f32_e32 v16, v16, v19
	v_max_f32_e32 v19, v25, v31
	v_min_f32_e32 v25, v25, v31
	v_max_f32_e32 v31, v23, v22
	v_min_f32_e32 v22, v23, v22
	v_max_f32_e32 v23, v26, v24
	v_min_f32_e32 v24, v26, v24
	v_max_f32_e32 v26, v27, v21
	v_min_f32_e32 v21, v27, v21
	v_max_f32_e32 v60, v62, v50
	v_min_f32_e32 v50, v62, v50
	v_max_f32_e32 v62, v61, v49
	v_min_f32_e32 v49, v61, v49
	v_max_f32_e32 v61, v143, v52
	v_min_f32_e32 v52, v143, v52
	v_max_f32_e32 v143, v48, v51
	v_min_f32_e32 v48, v48, v51
	v_max_f32_e32 v51, v57, v63
	v_min_f32_e32 v57, v57, v63
	v_max_f32_e32 v63, v55, v54
	v_min_f32_e32 v54, v55, v54
	v_max_f32_e32 v55, v58, v56
	v_min_f32_e32 v56, v58, v56
	v_max_f32_e32 v58, v59, v53
	v_min_f32_e32 v53, v59, v53
	v_max_f32_e32 v27, v28, v29
	v_min_f32_e32 v28, v28, v29
	v_max_f32_e32 v29, v30, v32
	v_min_f32_e32 v30, v30, v32
	v_max_f32_e32 v32, v18, v20
	v_min_f32_e32 v18, v18, v20
	v_max_f32_e32 v20, v17, v16
	v_min_f32_e32 v16, v17, v16
	v_max_f32_e32 v17, v24, v25
	v_min_f32_e32 v24, v24, v25
	v_max_f32_e32 v25, v21, v22
	v_min_f32_e32 v21, v21, v22
	v_max_f32_e32 v22, v23, v19
	v_min_f32_e32 v19, v23, v19
	v_max_f32_e32 v23, v26, v31
	v_min_f32_e32 v26, v26, v31
	v_max_f32_e32 v59, v60, v61
	v_min_f32_e32 v60, v60, v61
	v_max_f32_e32 v61, v62, v143
	v_min_f32_e32 v62, v62, v143
	v_max_f32_e32 v143, v50, v52
	v_min_f32_e32 v50, v50, v52
	v_max_f32_e32 v52, v49, v48
	v_min_f32_e32 v48, v49, v48
	v_max_f32_e32 v49, v56, v57
	v_min_f32_e32 v56, v56, v57
	v_max_f32_e32 v57, v53, v54
	v_min_f32_e32 v53, v53, v54
	v_max_f32_e32 v54, v55, v51
	v_min_f32_e32 v51, v55, v51
	v_max_f32_e32 v55, v58, v63
	v_min_f32_e32 v58, v58, v63
	v_max_f32_e32 v31, v27, v29
	v_min_f32_e32 v27, v27, v29
	v_max_f32_e32 v29, v28, v30
	v_min_f32_e32 v28, v28, v30
	v_max_f32_e32 v30, v32, v20
	v_min_f32_e32 v20, v32, v20
	v_max_f32_e32 v32, v18, v16
	v_min_f32_e32 v16, v18, v16
	v_max_f32_e32 v18, v21, v24
	v_min_f32_e32 v21, v21, v24
	v_max_f32_e32 v24, v25, v17
	v_min_f32_e32 v17, v25, v17
	v_max_f32_e32 v25, v26, v19
	v_min_f32_e32 v19, v26, v19
	v_max_f32_e32 v26, v23, v22
	v_min_f32_e32 v22, v23, v22
	v_max_f32_e32 v63, v59, v61
	v_min_f32_e32 v59, v59, v61
	v_max_f32_e32 v61, v60, v62
	v_min_f32_e32 v60, v60, v62
; #define CE_DESC(x, y) { const float a_ = __uint_as_float(x), b_ = __uint_as_float(y); (x) = __float_as_uint(__builtin_fmaxf(a_, b_)); (y) = __float_as_uint(__builtin_fminf(a_, b_)); }
; DEVI void sort16_desc(uint32_t (&a)[16]) {
; #pragma unroll
;   for (int k = 2; k <= 16; k <<= 1) {
; #pragma unroll
;     for (int j = k >> 1; j > 0; j >>= 1) {
; #pragma unroll
;       for (int i = 0; i < 16; i++) {
;         const int l = i ^ j;
;         if (l > i) { if ((i & k) == 0) CE_DESC(a[i], a[l]) else CE_DESC(a[l], a[i]) }
;       }
;     }
;   }
; }
; DEVI void merge16_desc(uint32_t (&x)[16], const uint32_t (&y)[16]) {
; #pragma unroll
;   for (int i = 0; i < 16; i++) x[i] = __float_as_uint(__builtin_fmaxf(__uint_as_float(x[i]), __uint_as_float(y[15 - i])));
; #pragma unroll
;   for (int j = 8; j > 0; j >>= 1) {
; #pragma unroll
;     for (int i = 0; i < 16; i++) {
;       const int l = i ^ j;
;       if (l > i) CE_DESC(x[i], x[l])
;     }
;   }
; }
	v_max_f32_e32 v62, v143, v52
	v_min_f32_e32 v52, v143, v52
	v_max_f32_e32 v143, v50, v48
	v_min_f32_e32 v48, v50, v48
	v_max_f32_e32 v50, v53, v56
	v_min_f32_e32 v53, v53, v56
	v_max_f32_e32 v56, v57, v49
	v_min_f32_e32 v49, v57, v49
	v_max_f32_e32 v57, v58, v51
	v_min_f32_e32 v51, v58, v51
	v_max_f32_e32 v58, v55, v54
	v_min_f32_e32 v54, v55, v54
	v_max_f32_e32 v23, v31, v21
	v_min_f32_e32 v21, v31, v21
	v_max_f32_e32 v31, v27, v18
	v_min_f32_e32 v18, v27, v18
	v_max_f32_e32 v27, v29, v17
	v_min_f32_e32 v17, v29, v17
	v_max_f32_e32 v29, v28, v24
	v_min_f32_e32 v24, v28, v24
	v_max_f32_e32 v28, v30, v19
	v_min_f32_e32 v19, v30, v19
	v_max_f32_e32 v30, v20, v25
	v_min_f32_e32 v20, v20, v25
	v_max_f32_e32 v25, v32, v22
	v_min_f32_e32 v22, v32, v22
	v_max_f32_e32 v32, v16, v26
	v_min_f32_e32 v16, v16, v26
	v_max_f32_e32 v55, v63, v53
	v_min_f32_e32 v53, v63, v53
	v_max_f32_e32 v63, v59, v50
	v_min_f32_e32 v50, v59, v50
	v_max_f32_e32 v59, v61, v49
	v_min_f32_e32 v49, v61, v49
	v_max_f32_e32 v61, v60, v56
	v_min_f32_e32 v56, v60, v56
	v_max_f32_e32 v60, v62, v51
	v_min_f32_e32 v51, v62, v51
	v_max_f32_e32 v62, v52, v57
	v_min_f32_e32 v52, v52, v57
	v_max_f32_e32 v57, v143, v54
	v_min_f32_e32 v54, v143, v54
	v_max_f32_e32 v143, v48, v58
	v_min_f32_e32 v48, v48, v58
	v_max_f32_e32 v26, v23, v28
	v_min_f32_e32 v23, v23, v28
	v_max_f32_e32 v33, v31, v30
	v_min_f32_e32 v30, v31, v30
	v_max_f32_e32 v28, v27, v25
	v_min_f32_e32 v25, v27, v25
	v_max_f32_e32 v27, v29, v32
	v_min_f32_e32 v31, v29, v32
	v_max_f32_e32 v32, v21, v19
	v_min_f32_e32 v19, v21, v19
	v_max_f32_e32 v34, v18, v20
	v_min_f32_e32 v35, v18, v20
	v_max_f32_e32 v18, v17, v22
	v_min_f32_e32 v36, v17, v22
	v_max_f32_e32 v37, v24, v16
	v_min_f32_e32 v38, v24, v16
	v_max_f32_e32 v58, v55, v60
	v_min_f32_e32 v55, v55, v60
	v_max_f32_e32 v60, v63, v62
	v_min_f32_e32 v62, v63, v62
	v_max_f32_e32 v63, v59, v57
	v_min_f32_e32 v57, v59, v57
	v_max_f32_e32 v59, v61, v143
	v_min_f32_e32 v61, v61, v143
	v_max_f32_e32 v143, v53, v51
	v_min_f32_e32 v51, v53, v51
	v_max_f32_e32 v53, v50, v52
	v_min_f32_e32 v50, v50, v52
	v_max_f32_e32 v52, v49, v54
	v_min_f32_e32 v49, v49, v54
	v_max_f32_e32 v54, v56, v48
	v_min_f32_e32 v48, v56, v48
	v_max_f32_e32 v20, v26, v28
	v_min_f32_e32 v16, v26, v28
	v_max_f32_e32 v28, v33, v27
	v_min_f32_e32 v24, v33, v27
	v_max_f32_e32 v21, v23, v25
	v_min_f32_e32 v17, v23, v25
	v_max_f32_e32 v29, v30, v31
	v_min_f32_e32 v25, v30, v31
	v_max_f32_e32 v22, v32, v18
	v_min_f32_e32 v18, v32, v18
	v_max_f32_e32 v30, v34, v37
	v_min_f32_e32 v26, v34, v37
	v_max_f32_e32 v23, v19, v36
	v_min_f32_e32 v19, v19, v36
	v_max_f32_e32 v31, v35, v38
	v_min_f32_e32 v27, v35, v38
	v_max_f32_e32 v56, v58, v63
	v_min_f32_e32 v58, v58, v63
	v_max_f32_e32 v63, v60, v59
	v_min_f32_e32 v59, v60, v59
	v_max_f32_e32 v60, v55, v57
	v_min_f32_e32 v55, v55, v57
	v_max_f32_e32 v57, v62, v61
	v_min_f32_e32 v61, v62, v61
	v_max_f32_e32 v62, v143, v52
	v_min_f32_e32 v52, v143, v52
	v_max_f32_e32 v143, v53, v54
	v_min_f32_e32 v53, v53, v54
	v_max_f32_e32 v54, v51, v49
	v_min_f32_e32 v49, v51, v49
	v_max_f32_e32 v51, v50, v48
	v_min_f32_e32 v48, v50, v48
	v_min_f32_e32 v39, v20, v28
	v_min_f32_e32 v38, v16, v24
	v_min_f32_e32 v37, v21, v29
	v_min_f32_e32 v36, v17, v25
	v_min_f32_e32 v35, v22, v30
	v_min_f32_e32 v34, v18, v26
	v_min_f32_e32 v33, v23, v31
	v_min_f32_e32 v32, v19, v27
	v_min_f32_e32 v50, v56, v63
	v_min_f32_e32 v144, v58, v59
	v_min_f32_e32 v154, v60, v57
	v_min_f32_e32 v155, v55, v61
	v_min_f32_e32 v156, v62, v143
	v_min_f32_e32 v157, v52, v53
	v_min_f32_e32 v158, v54, v51
	v_min_f32_e32 v159, v49, v48
	v_max_f32_e32 v1, v1, v1
	v_max_f32_e32 v0, v0, v0
	v_max_f32_e32 v147, v147, v147
	v_max_f32_e32 v146, v146, v146
	v_max_f32_e32 v171, v0, v1
	v_min_f32_e32 v0, v0, v1
	v_max_f32_e32 v1, v2, v2
	v_max_f32_e32 v2, v3, v3
	v_max_f32_e32 v160, v146, v147
	v_min_f32_e32 v146, v146, v147
	v_max_f32_e32 v147, v148, v148
	v_max_f32_e32 v148, v149, v149
	v_max_f32_e32 v3, v2, v1
	v_min_f32_e32 v1, v2, v1
	v_max_f32_e32 v2, v5, v5
	v_max_f32_e32 v4, v4, v4
	v_max_f32_e32 v149, v148, v147
	v_min_f32_e32 v147, v148, v147
	v_max_f32_e32 v148, v151, v151
	v_max_f32_e32 v150, v150, v150
	v_max_f32_e32 v5, v4, v2
	v_min_f32_e32 v2, v4, v2
	v_max_f32_e32 v4, v6, v6
	v_max_f32_e32 v6, v7, v7
	v_max_f32_e32 v151, v150, v148
	v_min_f32_e32 v148, v150, v148
	v_max_f32_e32 v150, v152, v152
	v_max_f32_e32 v152, v153, v153
	v_max_f32_e32 v41, v41, v41
	v_max_f32_e32 v40, v40, v40
	v_max_f32_e32 v7, v6, v4
	v_min_f32_e32 v4, v6, v4
	v_max_f32_e32 v6, v9, v9
	v_max_f32_e32 v8, v8, v8
	v_max_f32_e32 v153, v152, v150
	v_min_f32_e32 v150, v152, v150
	v_max_f32_e32 v152, v40, v41
	v_min_f32_e32 v40, v40, v41
	v_max_f32_e32 v41, v42, v42
	v_max_f32_e32 v42, v43, v43
	v_max_f32_e32 v9, v8, v6
	v_min_f32_e32 v6, v8, v6
	v_max_f32_e32 v8, v10, v10
	v_max_f32_e32 v10, v11, v11
	v_max_f32_e32 v43, v42, v41
	v_min_f32_e32 v41, v42, v41
	v_max_f32_e32 v42, v45, v45
	v_max_f32_e32 v44, v44, v44
	v_max_f32_e32 v11, v10, v8
	v_min_f32_e32 v8, v10, v8
	v_max_f32_e32 v10, v13, v13
	v_max_f32_e32 v12, v12, v12
	v_max_f32_e32 v45, v44, v42
	v_min_f32_e32 v42, v44, v42
	v_max_f32_e32 v44, v46, v46
	v_max_f32_e32 v46, v47, v47
	v_max_f32_e32 v13, v12, v10
	v_min_f32_e32 v10, v12, v10
	v_max_f32_e32 v12, v14, v14
	v_max_f32_e32 v14, v15, v15
	v_max_f32_e32 v47, v46, v44
	v_min_f32_e32 v44, v46, v44
	v_max_f32_e32 v15, v14, v12
	v_min_f32_e32 v12, v14, v12
	v_max_f32_e32 v46, v160, v147
	v_min_f32_e32 v147, v160, v147
	v_max_f32_e32 v160, v146, v149
	v_min_f32_e32 v146, v146, v149
	v_max_f32_e32 v149, v150, v151
	v_min_f32_e32 v150, v150, v151
; #define CE_DESC(x, y) { const float a_ = __uint_as_float(x), b_ = __uint_as_float(y); (x) = __float_as_uint(__builtin_fmaxf(a_, b_)); (y) = __float_as_uint(__builtin_fminf(a_, b_)); }
; DEVI void sort16_desc(uint32_t (&a)[16]) {
; #pragma unroll
;   for (int k = 2; k <= 16; k <<= 1) {
; #pragma unroll
;     for (int j = k >> 1; j > 0; j >>= 1) {
; #pragma unroll
;       for (int i = 0; i < 16; i++) {
;         const int l = i ^ j;
;         if (l > i) { if ((i & k) == 0) CE_DESC(a[i], a[l]) else CE_DESC(a[l], a[i]) }
;       }
;     }
;   }
; }
	v_max_f32_e32 v151, v153, v148
	v_min_f32_e32 v148, v153, v148
	v_max_f32_e32 v153, v152, v41
	v_min_f32_e32 v41, v152, v41
	v_max_f32_e32 v152, v40, v43
	v_min_f32_e32 v40, v40, v43
	v_max_f32_e32 v43, v44, v45
	v_min_f32_e32 v44, v44, v45
	v_max_f32_e32 v45, v47, v42
	v_min_f32_e32 v42, v47, v42
	v_max_f32_e32 v14, v171, v1
	v_min_f32_e32 v1, v171, v1
	v_max_f32_e32 v171, v0, v3
	v_min_f32_e32 v0, v0, v3
	v_max_f32_e32 v3, v4, v5
	v_min_f32_e32 v4, v4, v5
	v_max_f32_e32 v5, v7, v2
	v_min_f32_e32 v2, v7, v2
	v_max_f32_e32 v7, v9, v8
	v_min_f32_e32 v8, v9, v8
	v_max_f32_e32 v9, v6, v11
	v_min_f32_e32 v6, v6, v11
	v_max_f32_e32 v11, v12, v13
	v_min_f32_e32 v12, v12, v13
	v_max_f32_e32 v13, v15, v10
	v_min_f32_e32 v10, v15, v10
	v_max_f32_e32 v47, v46, v160
	v_min_f32_e32 v46, v46, v160
	v_max_f32_e32 v160, v147, v146
	v_min_f32_e32 v146, v147, v146
	v_max_f32_e32 v147, v148, v150
	v_min_f32_e32 v148, v148, v150
	v_max_f32_e32 v150, v151, v149
	v_min_f32_e32 v149, v151, v149
	v_max_f32_e32 v151, v153, v152
	v_min_f32_e32 v152, v153, v152
	v_max_f32_e32 v153, v41, v40
	v_min_f32_e32 v40, v41, v40
	v_max_f32_e32 v41, v42, v44
	v_min_f32_e32 v42, v42, v44
	v_max_f32_e32 v44, v45, v43
	v_min_f32_e32 v43, v45, v43
	v_max_f32_e32 v15, v14, v171
	v_min_f32_e32 v14, v14, v171
	v_max_f32_e32 v171, v1, v0
	v_min_f32_e32 v0, v1, v0
	v_max_f32_e32 v1, v2, v4
	v_min_f32_e32 v2, v2, v4
	v_max_f32_e32 v4, v5, v3
	v_min_f32_e32 v3, v5, v3
	v_max_f32_e32 v5, v7, v9
	v_min_f32_e32 v7, v7, v9
	v_max_f32_e32 v9, v8, v6
	v_min_f32_e32 v6, v8, v6
	v_max_f32_e32 v8, v10, v12
	v_min_f32_e32 v10, v10, v12
	v_max_f32_e32 v12, v13, v11
	v_min_f32_e32 v11, v13, v11
	v_max_f32_e32 v45, v47, v148
	v_min_f32_e32 v47, v47, v148
	v_max_f32_e32 v148, v46, v147
	v_min_f32_e32 v46, v46, v147
	v_max_f32_e32 v147, v160, v149
	v_min_f32_e32 v149, v160, v149
	v_max_f32_e32 v160, v146, v150
	v_min_f32_e32 v146, v146, v150
	v_max_f32_e32 v150, v42, v151
	v_min_f32_e32 v42, v42, v151
	v_max_f32_e32 v151, v41, v152
	v_min_f32_e32 v41, v41, v152
	v_max_f32_e32 v152, v43, v153
	v_min_f32_e32 v43, v43, v153
	v_max_f32_e32 v153, v44, v40
	v_min_f32_e32 v40, v44, v40
	v_max_f32_e32 v13, v15, v2
	v_min_f32_e32 v2, v15, v2
	v_max_f32_e32 v15, v14, v1
	v_min_f32_e32 v1, v14, v1
	v_max_f32_e32 v14, v171, v3
	v_min_f32_e32 v3, v171, v3
	v_max_f32_e32 v171, v0, v4
	v_min_f32_e32 v0, v0, v4
	v_max_f32_e32 v4, v10, v5
	v_min_f32_e32 v5, v10, v5
	v_max_f32_e32 v10, v8, v7
	v_min_f32_e32 v7, v8, v7
	v_max_f32_e32 v8, v11, v9
	v_min_f32_e32 v9, v11, v9
	v_max_f32_e32 v11, v12, v6
	v_min_f32_e32 v6, v12, v6
	v_max_f32_e32 v44, v45, v147
	v_min_f32_e32 v45, v45, v147
	v_max_f32_e32 v147, v148, v160
	v_min_f32_e32 v148, v148, v160
	v_max_f32_e32 v160, v47, v149
	v_min_f32_e32 v47, v47, v149
	v_max_f32_e32 v149, v46, v146
	v_min_f32_e32 v46, v46, v146
	v_max_f32_e32 v146, v43, v42
	v_min_f32_e32 v42, v43, v42
	v_max_f32_e32 v43, v40, v41
	v_min_f32_e32 v40, v40, v41
	v_max_f32_e32 v41, v152, v150
	v_min_f32_e32 v150, v152, v150
	v_max_f32_e32 v152, v153, v151
	v_min_f32_e32 v151, v153, v151
	v_max_f32_e32 v12, v13, v14
	v_min_f32_e32 v13, v13, v14
	v_max_f32_e32 v14, v15, v171
	v_min_f32_e32 v15, v15, v171
	v_max_f32_e32 v171, v2, v3
	v_min_f32_e32 v2, v2, v3
	v_max_f32_e32 v3, v1, v0
	v_min_f32_e32 v0, v1, v0
	v_max_f32_e32 v1, v9, v5
	v_min_f32_e32 v5, v9, v5
	v_max_f32_e32 v9, v6, v7
	v_min_f32_e32 v6, v6, v7
	v_max_f32_e32 v7, v8, v4
	v_min_f32_e32 v4, v8, v4
	v_max_f32_e32 v8, v11, v10
	v_min_f32_e32 v10, v11, v10
	v_max_f32_e32 v153, v44, v147
	v_min_f32_e32 v44, v44, v147
	v_max_f32_e32 v147, v45, v148
	v_min_f32_e32 v45, v45, v148
	v_max_f32_e32 v148, v160, v149
	v_min_f32_e32 v149, v160, v149
	v_max_f32_e32 v160, v47, v46
	v_min_f32_e32 v46, v47, v46
	v_max_f32_e32 v47, v40, v42
	v_min_f32_e32 v40, v40, v42
	v_max_f32_e32 v42, v43, v146
	v_min_f32_e32 v43, v43, v146
	v_max_f32_e32 v146, v151, v150
	v_min_f32_e32 v150, v151, v150
	v_max_f32_e32 v151, v152, v41
	v_min_f32_e32 v41, v152, v41
	v_max_f32_e32 v11, v12, v14
	v_min_f32_e32 v12, v12, v14
	v_max_f32_e32 v14, v13, v15
	v_min_f32_e32 v13, v13, v15
	v_max_f32_e32 v15, v171, v3
	v_min_f32_e32 v3, v171, v3
	v_max_f32_e32 v171, v2, v0
	v_min_f32_e32 v0, v2, v0
	v_max_f32_e32 v2, v6, v5
	v_min_f32_e32 v5, v6, v5
	v_max_f32_e32 v6, v9, v1
	v_min_f32_e32 v1, v9, v1
	v_max_f32_e32 v9, v10, v4
	v_min_f32_e32 v4, v10, v4
	v_max_f32_e32 v10, v8, v7
	v_min_f32_e32 v7, v8, v7
	v_max_f32_e32 v152, v153, v40
	v_min_f32_e32 v40, v153, v40
	v_max_f32_e32 v153, v44, v47
	v_min_f32_e32 v44, v44, v47
	v_max_f32_e32 v47, v147, v43
	v_min_f32_e32 v43, v147, v43
	v_max_f32_e32 v147, v45, v42
	v_min_f32_e32 v42, v45, v42
	v_max_f32_e32 v45, v148, v150
	v_min_f32_e32 v148, v148, v150
	v_max_f32_e32 v150, v149, v146
	v_min_f32_e32 v146, v149, v146
	v_max_f32_e32 v149, v160, v41
	v_min_f32_e32 v41, v160, v41
	v_max_f32_e32 v160, v46, v151
	v_min_f32_e32 v46, v46, v151
	v_max_f32_e32 v8, v11, v5
	v_min_f32_e32 v5, v11, v5
	v_max_f32_e32 v11, v12, v2
	v_min_f32_e32 v2, v12, v2
	v_max_f32_e32 v12, v14, v1
	v_min_f32_e32 v1, v14, v1
	v_max_f32_e32 v14, v13, v6
	v_min_f32_e32 v6, v13, v6
	v_max_f32_e32 v13, v15, v4
	v_min_f32_e32 v4, v15, v4
	v_max_f32_e32 v15, v3, v9
	v_min_f32_e32 v3, v3, v9
	v_max_f32_e32 v9, v171, v7
	v_min_f32_e32 v7, v171, v7
	v_max_f32_e32 v171, v0, v10
	v_min_f32_e32 v0, v0, v10
	v_max_f32_e32 v151, v152, v45
	v_min_f32_e32 v45, v152, v45
	v_max_f32_e32 v152, v153, v150
	v_min_f32_e32 v150, v153, v150
	v_max_f32_e32 v153, v47, v149
	v_min_f32_e32 v47, v47, v149
	v_max_f32_e32 v149, v147, v160
	v_min_f32_e32 v147, v147, v160
	v_max_f32_e32 v160, v40, v148
; #define CE_DESC(x, y) { const float a_ = __uint_as_float(x), b_ = __uint_as_float(y); (x) = __float_as_uint(__builtin_fmaxf(a_, b_)); (y) = __float_as_uint(__builtin_fminf(a_, b_)); }
; DEVI void merge16_desc(uint32_t (&x)[16], const uint32_t (&y)[16]) {
; #pragma unroll
;   for (int i = 0; i < 16; i++) x[i] = __float_as_uint(__builtin_fmaxf(__uint_as_float(x[i]), __uint_as_float(y[15 - i])));
; #pragma unroll
;   for (int j = 8; j > 0; j >>= 1) {
; #pragma unroll
;     for (int i = 0; i < 16; i++) {
;       const int l = i ^ j;
;       if (l > i) CE_DESC(x[i], x[l])
;     }
;   }
; }
	v_min_f32_e32 v40, v40, v148
	v_max_f32_e32 v148, v44, v146
	v_min_f32_e32 v44, v44, v146
	v_max_f32_e32 v146, v43, v41
	v_min_f32_e32 v41, v43, v41
	v_max_f32_e32 v43, v42, v46
	v_min_f32_e32 v42, v42, v46
	v_max_f32_e32 v10, v8, v13
	v_min_f32_e32 v8, v8, v13
	v_max_f32_e32 v13, v11, v15
	v_min_f32_e32 v11, v11, v15
	v_max_f32_e32 v15, v12, v9
	v_min_f32_e32 v9, v12, v9
	v_max_f32_e32 v12, v14, v171
	v_min_f32_e32 v14, v14, v171
	v_max_f32_e32 v171, v5, v4
	v_min_f32_e32 v4, v5, v4
	v_max_f32_e32 v5, v2, v3
	v_min_f32_e32 v2, v2, v3
	v_max_f32_e32 v3, v1, v7
	v_min_f32_e32 v1, v1, v7
	v_max_f32_e32 v7, v6, v0
	v_min_f32_e32 v0, v6, v0
	v_max_f32_e32 v46, v151, v153
	v_min_f32_e32 v151, v151, v153
	v_max_f32_e32 v153, v152, v149
	v_min_f32_e32 v149, v152, v149
	v_max_f32_e32 v152, v45, v47
	v_min_f32_e32 v45, v45, v47
	v_max_f32_e32 v47, v150, v147
	v_min_f32_e32 v147, v150, v147
	v_max_f32_e32 v150, v160, v146
	v_min_f32_e32 v146, v160, v146
	v_max_f32_e32 v160, v148, v43
	v_min_f32_e32 v43, v148, v43
	v_max_f32_e32 v148, v40, v41
	v_min_f32_e32 v40, v40, v41
	v_max_f32_e32 v41, v44, v42
	v_min_f32_e32 v42, v44, v42
	v_max_f32_e32 v6, v10, v15
	v_min_f32_e32 v10, v10, v15
	v_max_f32_e32 v15, v13, v12
	v_min_f32_e32 v12, v13, v12
	v_max_f32_e32 v13, v8, v9
	v_min_f32_e32 v8, v8, v9
	v_max_f32_e32 v9, v11, v14
	v_min_f32_e32 v11, v11, v14
	v_max_f32_e32 v14, v171, v3
	v_min_f32_e32 v3, v171, v3
	v_max_f32_e32 v171, v5, v7
	v_min_f32_e32 v5, v5, v7
	v_max_f32_e32 v7, v4, v1
	v_min_f32_e32 v1, v4, v1
	v_max_f32_e32 v4, v2, v0
	v_min_f32_e32 v0, v2, v0
	v_min_f32_e32 v44, v46, v153
	v_min_f32_e32 v161, v151, v149
	v_min_f32_e32 v165, v152, v47
	v_min_f32_e32 v166, v45, v147
	v_min_f32_e32 v167, v150, v160
	v_min_f32_e32 v168, v146, v43
	v_min_f32_e32 v169, v148, v41
	v_min_f32_e32 v170, v40, v42
	v_min_f32_e32 v2, v6, v15
	v_min_f32_e32 v172, v10, v12
	v_min_f32_e32 v173, v13, v9
	v_min_f32_e32 v174, v8, v11
	v_min_f32_e32 v175, v14, v171
	v_min_f32_e32 v176, v3, v5
	v_min_f32_e32 v177, v7, v4
	v_min_f32_e32 v179, v1, v0
	v_max3_f32 v20, v20, v28, v159
	v_max3_f32 v28, v39, v49, v48
	v_max3_f32 v16, v16, v24, v158
	v_max3_f32 v24, v38, v54, v51
	v_max3_f32 v21, v21, v29, v157
	v_max3_f32 v29, v37, v52, v53
	v_max3_f32 v17, v17, v25, v156
	v_max3_f32 v25, v36, v62, v143
	v_max3_f32 v22, v22, v30, v155
	v_max3_f32 v30, v35, v55, v61
	v_max3_f32 v18, v18, v26, v154
	v_max3_f32 v26, v34, v60, v57
	v_max3_f32 v23, v23, v31, v144
	v_max3_f32 v31, v33, v58, v59
	v_max3_f32 v19, v19, v27, v50
	v_max3_f32 v27, v32, v56, v63
	v_max3_f32 v46, v46, v153, v179
	v_max3_f32 v0, v44, v1, v0
	v_max3_f32 v1, v151, v149, v177
	v_max3_f32 v4, v161, v7, v4
	v_max3_f32 v7, v152, v47, v176
	v_max3_f32 v3, v165, v3, v5
	v_max3_f32 v5, v45, v147, v175
	v_max3_f32 v14, v166, v14, v171
	v_max3_f32 v44, v150, v160, v174
	v_max3_f32 v8, v167, v8, v11
	v_max3_f32 v11, v146, v43, v173
	v_max3_f32 v9, v168, v13, v9
	v_max3_f32 v13, v148, v41, v172
	v_max3_f32 v10, v169, v10, v12
	v_max3_f32 v2, v40, v42, v2
	v_max3_f32 v6, v170, v6, v15
	v_max_f32_e32 v32, v20, v22
	v_min_f32_e32 v20, v20, v22
	v_max_f32_e32 v22, v28, v30
	v_min_f32_e32 v28, v28, v30
	v_max_f32_e32 v30, v16, v18
	v_min_f32_e32 v16, v16, v18
	v_max_f32_e32 v18, v24, v26
	v_min_f32_e32 v24, v24, v26
	v_max_f32_e32 v26, v21, v23
	v_min_f32_e32 v21, v21, v23
	v_max_f32_e32 v23, v29, v31
	v_min_f32_e32 v29, v29, v31
	v_max_f32_e32 v31, v17, v19
	v_min_f32_e32 v17, v17, v19
	v_max_f32_e32 v19, v25, v27
	v_min_f32_e32 v25, v25, v27
	v_max_f32_e32 v12, v46, v44
	v_min_f32_e32 v15, v46, v44
	v_max_f32_e32 v40, v0, v8
	v_min_f32_e32 v0, v0, v8
	v_max_f32_e32 v8, v1, v11
	v_min_f32_e32 v1, v1, v11
	v_max_f32_e32 v11, v4, v9
	v_min_f32_e32 v4, v4, v9
	v_max_f32_e32 v9, v7, v13
	v_min_f32_e32 v7, v7, v13
	v_max_f32_e32 v13, v3, v10
	v_min_f32_e32 v3, v3, v10
	v_max_f32_e32 v10, v5, v2
	v_min_f32_e32 v2, v5, v2
	v_max_f32_e32 v5, v14, v6
	v_min_f32_e32 v6, v14, v6
	v_max_f32_e32 v27, v32, v26
	v_min_f32_e32 v26, v32, v26
	v_max_f32_e32 v32, v22, v23
	v_min_f32_e32 v22, v22, v23
	v_max_f32_e32 v23, v30, v31
	v_min_f32_e32 v30, v30, v31
	v_max_f32_e32 v31, v18, v19
	v_min_f32_e32 v18, v18, v19
	v_max_f32_e32 v19, v20, v21
	v_min_f32_e32 v20, v20, v21
	v_max_f32_e32 v21, v28, v29
	v_min_f32_e32 v28, v28, v29
	v_max_f32_e32 v29, v16, v17
	v_min_f32_e32 v16, v16, v17
	v_max_f32_e32 v17, v24, v25
	v_min_f32_e32 v24, v24, v25
	v_max_f32_e32 v14, v12, v9
	v_min_f32_e32 v9, v12, v9
	v_max_f32_e32 v12, v40, v13
	v_min_f32_e32 v13, v40, v13
	v_max_f32_e32 v40, v8, v10
	v_min_f32_e32 v8, v8, v10
	v_max_f32_e32 v10, v11, v5
	v_min_f32_e32 v5, v11, v5
	v_max_f32_e32 v11, v15, v7
	v_min_f32_e32 v7, v15, v7
	v_max_f32_e32 v15, v0, v3
	v_min_f32_e32 v0, v0, v3
	v_max_f32_e32 v3, v1, v2
	v_min_f32_e32 v1, v1, v2
	v_max_f32_e32 v2, v4, v6
	v_min_f32_e32 v4, v4, v6
	v_max_f32_e32 v25, v27, v23
	v_min_f32_e32 v23, v27, v23
	v_max_f32_e32 v27, v32, v31
	v_min_f32_e32 v31, v32, v31
	v_max_f32_e32 v32, v26, v30
	v_min_f32_e32 v26, v26, v30
	v_max_f32_e32 v30, v22, v18
	v_min_f32_e32 v18, v22, v18
	v_max_f32_e32 v22, v19, v29
	v_min_f32_e32 v19, v19, v29
	v_max_f32_e32 v29, v21, v17
	v_min_f32_e32 v17, v21, v17
	v_max_f32_e32 v21, v20, v16
	v_min_f32_e32 v16, v20, v16
	v_max_f32_e32 v20, v28, v24
	v_min_f32_e32 v24, v28, v24
	v_max_f32_e32 v6, v14, v40
	v_min_f32_e32 v14, v14, v40
	v_max_f32_e32 v40, v12, v10
	v_min_f32_e32 v10, v12, v10
	v_max_f32_e32 v12, v9, v8
	v_min_f32_e32 v8, v9, v8
	v_max_f32_e32 v9, v13, v5
	v_min_f32_e32 v5, v13, v5
	v_max_f32_e32 v13, v11, v3
	v_min_f32_e32 v3, v11, v3
	v_max_f32_e32 v11, v15, v2
	v_min_f32_e32 v2, v15, v2
; __device__ void phase_peer_q(const P& p, int vb, int nvb, char* smem) {
;     ...
;         merge16_desc(g0, g1); merge16_desc(g2, g3); merge16_desc(g0, g2);
;         uint32_t y[16];
; #pragma unroll
;         for (int e = 0; e < 16; e++) y[e] = (uint32_t)__shfl_xor((int)g0[e], 32);
;         merge16_desc(g0, y);
;         {
;           uint32_t* dst = svl + tk * 32 + pp * 16;
; #pragma unroll
;           for (int e = 0; e < 16; e += 4) *(uint4*)(dst + e) = make_uint4(g0[e], g0[e + 1], g0[e + 2], g0[e + 3]);
;         }
	v_max_f32_e32 v15, v7, v1
	v_min_f32_e32 v1, v7, v1
	v_max_f32_e32 v7, v0, v4
	v_min_f32_e32 v0, v0, v4
	v_min_f32_e32 v28, v25, v27
	v_min_f32_e32 v33, v23, v31
	v_min_f32_e32 v34, v32, v30
	v_min_f32_e32 v35, v26, v18
	v_min_f32_e32 v36, v22, v29
	v_min_f32_e32 v37, v19, v17
	v_min_f32_e32 v38, v21, v20
	v_min_f32_e32 v39, v16, v24
	v_min_f32_e32 v4, v6, v40
	v_min_f32_e32 v41, v14, v10
	v_min_f32_e32 v42, v12, v9
	v_min_f32_e32 v43, v8, v5
	v_min_f32_e32 v44, v13, v11
	v_min_f32_e32 v45, v3, v2
	v_min_f32_e32 v46, v15, v7
	v_min_f32_e32 v47, v1, v0
	v_max3_f32 v25, v25, v27, v47
	v_max3_f32 v0, v28, v1, v0
	v_max3_f32 v1, v23, v31, v46
	v_max3_f32 v7, v33, v15, v7
	v_max3_f32 v15, v32, v30, v45
	v_max3_f32 v2, v34, v3, v2
	v_max3_f32 v3, v26, v18, v44
	v_max3_f32 v11, v35, v13, v11
	v_max3_f32 v13, v22, v29, v43
	v_max3_f32 v5, v36, v8, v5
	v_max3_f32 v8, v19, v17, v42
	v_max3_f32 v9, v37, v12, v9
	v_max3_f32 v12, v21, v20, v41
	v_max3_f32 v10, v38, v14, v10
	v_max3_f32 v4, v16, v24, v4
	v_max3_f32 v6, v39, v6, v40
	v_max_f32_e32 v14, v25, v13
	v_min_f32_e32 v13, v25, v13
	v_max_f32_e32 v16, v0, v5
	v_min_f32_e32 v0, v0, v5
	v_max_f32_e32 v5, v1, v8
	v_min_f32_e32 v1, v1, v8
	v_max_f32_e32 v8, v7, v9
	v_min_f32_e32 v7, v7, v9
	v_max_f32_e32 v9, v15, v12
	v_min_f32_e32 v12, v15, v12
	v_max_f32_e32 v15, v2, v10
	v_min_f32_e32 v2, v2, v10
	v_max_f32_e32 v10, v3, v4
	v_min_f32_e32 v3, v3, v4
	v_max_f32_e32 v4, v11, v6
	v_min_f32_e32 v6, v11, v6
	v_max_f32_e32 v11, v14, v9
	v_min_f32_e32 v9, v14, v9
	v_max_f32_e32 v14, v16, v15
	v_min_f32_e32 v15, v16, v15
	v_max_f32_e32 v16, v5, v10
	v_min_f32_e32 v5, v5, v10
	v_max_f32_e32 v10, v8, v4
	v_min_f32_e32 v4, v8, v4
	v_max_f32_e32 v8, v13, v12
	v_min_f32_e32 v12, v13, v12
	v_max_f32_e32 v13, v0, v2
	v_min_f32_e32 v0, v0, v2
	v_max_f32_e32 v2, v1, v3
	v_min_f32_e32 v1, v1, v3
	v_max_f32_e32 v3, v7, v6
	v_min_f32_e32 v6, v7, v6
	v_max_f32_e32 v7, v11, v16
	v_min_f32_e32 v11, v11, v16
	v_max_f32_e32 v16, v14, v10
	v_min_f32_e32 v10, v14, v10
	v_max_f32_e32 v14, v9, v5
	v_min_f32_e32 v5, v9, v5
	v_max_f32_e32 v9, v15, v4
	v_min_f32_e32 v4, v15, v4
	v_max_f32_e32 v15, v8, v2
	v_min_f32_e32 v2, v8, v2
	v_max_f32_e32 v8, v13, v3
	v_min_f32_e32 v3, v13, v3
	v_max_f32_e32 v13, v12, v1
	v_min_f32_e32 v1, v12, v1
	v_max_f32_e32 v12, v0, v6
	v_min_f32_e32 v0, v0, v6
	v_max_f32_e32 v6, v7, v16
	v_min_f32_e32 v7, v7, v16
	v_max_f32_e32 v16, v11, v10
	v_min_f32_e32 v10, v11, v10
	v_max_f32_e32 v11, v14, v9
	v_min_f32_e32 v9, v14, v9
	v_max_f32_e32 v14, v5, v4
	v_min_f32_e32 v4, v5, v4
	v_max_f32_e32 v5, v15, v8
	v_min_f32_e32 v8, v15, v8
	v_max_f32_e32 v15, v2, v3
	v_min_f32_e32 v2, v2, v3
	v_max_f32_e32 v3, v13, v12
	v_min_f32_e32 v12, v13, v12
	v_max_f32_e32 v13, v1, v0
	v_min_f32_e32 v0, v1, v0
	ds_bpermute_b32 v27, v74, v0
	ds_bpermute_b32 v29, v74, v13
	ds_bpermute_b32 v31, v74, v12
	ds_bpermute_b32 v30, v74, v3
	ds_bpermute_b32 v1, v74, v6
	ds_bpermute_b32 v17, v74, v7
	ds_bpermute_b32 v18, v74, v16
	ds_bpermute_b32 v19, v74, v10
	ds_bpermute_b32 v20, v74, v11
	ds_bpermute_b32 v21, v74, v9
	ds_bpermute_b32 v22, v74, v14
	ds_bpermute_b32 v23, v74, v4
	ds_bpermute_b32 v24, v74, v5
	ds_bpermute_b32 v25, v74, v8
	ds_bpermute_b32 v26, v74, v15
	ds_bpermute_b32 v28, v74, v2
	s_waitcnt lgkmcnt(14)
	v_max_f32_e32 v27, v27, v27
	v_max_f32_e32 v6, v6, v27
	v_max_f32_e32 v27, v29, v29
	v_max_f32_e32 v7, v7, v27
	s_waitcnt lgkmcnt(13)
	v_max_f32_e32 v27, v31, v31
	v_max_f32_e32 v16, v16, v27
	s_waitcnt lgkmcnt(12)
	v_max_f32_e32 v27, v30, v30
	v_max_f32_e32 v10, v10, v27
	s_waitcnt lgkmcnt(0)
	v_max_f32_e32 v27, v28, v28
	v_max_f32_e32 v26, v26, v26
	v_max_f32_e32 v25, v25, v25
	v_max_f32_e32 v24, v24, v24
	v_max_f32_e32 v23, v23, v23
	v_max_f32_e32 v22, v22, v22
	v_max_f32_e32 v21, v21, v21
	v_max_f32_e32 v20, v20, v20
	v_max_f32_e32 v19, v19, v19
	v_max_f32_e32 v18, v18, v18
	v_max_f32_e32 v17, v17, v17
	v_max_f32_e32 v1, v1, v1
	v_max_f32_e32 v11, v11, v27
	v_max_f32_e32 v9, v9, v26
	v_max_f32_e32 v14, v14, v25
	v_max_f32_e32 v4, v4, v24
	v_max_f32_e32 v5, v5, v23
	v_max_f32_e32 v8, v8, v22
	v_max_f32_e32 v15, v15, v21
	v_max_f32_e32 v2, v2, v20
	v_max_f32_e32 v3, v3, v19
	v_max_f32_e32 v12, v12, v18
	v_max_f32_e32 v13, v13, v17
	v_max_f32_e32 v0, v0, v1
	v_max_f32_e32 v1, v6, v5
	v_min_f32_e32 v5, v6, v5
	v_max_f32_e32 v6, v7, v8
	v_min_f32_e32 v7, v7, v8
	v_max_f32_e32 v8, v16, v15
	v_min_f32_e32 v15, v16, v15
	v_max_f32_e32 v16, v10, v2
	v_min_f32_e32 v2, v10, v2
	v_max_f32_e32 v10, v11, v3
	v_min_f32_e32 v3, v11, v3
	v_max_f32_e32 v11, v9, v12
	v_min_f32_e32 v9, v9, v12
	v_max_f32_e32 v12, v14, v13
	v_min_f32_e32 v13, v14, v13
	v_max_f32_e32 v14, v4, v0
	v_min_f32_e32 v0, v4, v0
	v_max_f32_e32 v4, v1, v10
	v_min_f32_e32 v1, v1, v10
	v_max_f32_e32 v10, v6, v11
	v_min_f32_e32 v6, v6, v11
	v_max_f32_e32 v11, v8, v12
	v_min_f32_e32 v8, v8, v12
	v_max_f32_e32 v12, v16, v14
	v_min_f32_e32 v14, v16, v14
	v_max_f32_e32 v16, v5, v3
	v_min_f32_e32 v3, v5, v3
	v_max_f32_e32 v5, v7, v9
	v_min_f32_e32 v7, v7, v9
	v_max_f32_e32 v9, v15, v13
	v_min_f32_e32 v13, v15, v13
	v_max_f32_e32 v15, v2, v0
	v_min_f32_e32 v0, v2, v0
	v_max_f32_e32 v2, v4, v11
	v_min_f32_e32 v4, v4, v11
	v_max_f32_e32 v11, v10, v12
	v_min_f32_e32 v10, v10, v12
	v_max_f32_e32 v18, v16, v9
	v_min_f32_e32 v16, v16, v9
	v_max_f32_e32 v9, v5, v15
	v_min_f32_e32 v15, v5, v15
	v_max_f32_e32 v12, v1, v8
	v_min_f32_e32 v8, v1, v8
	v_max_f32_e32 v17, v6, v14
	v_min_f32_e32 v14, v6, v14
	v_max_f32_e32 v19, v3, v13
	v_min_f32_e32 v20, v3, v13
	v_max_f32_e32 v13, v7, v0
	v_min_f32_e32 v21, v7, v0
	v_max_f32_e32 v0, v2, v11
	v_min_f32_e32 v1, v2, v11
	v_max_f32_e32 v2, v4, v10
	v_min_f32_e32 v3, v4, v10
	v_max_f32_e32 v10, v16, v15
	v_min_f32_e32 v11, v16, v15
	v_add_u32_e32 v16, s38, v65
	s_andn2_b64 vcc, exec, s[0:1]
	s_mov_b64 s[0:1], 0
	v_max_f32_e32 v4, v12, v17
	v_min_f32_e32 v5, v12, v17
	v_max_f32_e32 v6, v8, v14
	v_min_f32_e32 v7, v8, v14
	v_max_f32_e32 v8, v18, v9
	v_min_f32_e32 v9, v18, v9
	v_max_f32_e32 v12, v19, v13
	v_min_f32_e32 v13, v19, v13
	v_max_f32_e32 v14, v20, v21
	v_min_f32_e32 v15, v20, v21
	ds_write_b128 v16, v[0:3] offset:34816
	ds_write_b128 v16, v[4:7] offset:34832
	ds_write_b128 v16, v[8:11] offset:34848
	ds_write_b128 v16, v[12:15] offset:34864
	s_cbranch_vccz .LBB0_437
; __device__ void phase_peer_q(const P& p, int vb, int nvb, char* smem) {
;     ...
;       asm volatile("s_waitcnt lgkmcnt(0)" ::: "memory");
; #pragma unroll
;       for (int e = 0; e < 16; e += 4) {
;         const uint4 a0 = *(const uint4*)(svl + tk * 32 + e), a1 = *(const uint4*)(svl + tk * 32 + 16 + e);
;         sv0[e] = a0.x; sv0[e + 1] = a0.y; sv0[e + 2] = a0.z; sv0[e + 3] = a0.w;
;         sv1[e] = a1.x; sv1[e + 1] = a1.y; sv1[e + 2] = a1.z; sv1[e + 3] = a1.w;
;       }
;       __builtin_amdgcn_sched_barrier(0);
;       float f0[16], f1[16];
; #pragma unroll
;       for (int e = 0; e < 16; e++) { f0[e] = sort2f(sv0[e] & ~127u); f1[e] = sort2f(sv1[e] & ~127u); }
;       uint32_t c[32];
;     ...
;       c[0] = lh2 ? CPK(f0[2] + f1[1], 33u) : CPK(f0[0] + f1[0], 0u);
;       c[1] = lh2 ? CPK(f0[2] + f1[2], 34u) : CPK(f0[0] + f1[1], 1u);
;       c[2] = lh2 ? CPK(f0[2] + f1[3], 35u) : CPK(f0[0] + f1[2], 2u);
;       c[3] = lh2 ? CPK(f0[2] + f1[4], 36u) : CPK(f0[0] + f1[3], 3u);
;       c[4] = lh2 ? CPK(f0[3] + f1[0], 48u) : CPK(f0[0] + f1[4], 4u);
;       c[5] = lh2 ? CPK(f0[3] + f1[1], 49u) : CPK(f0[0] + f1[5], 5u);
;       c[6] = lh2 ? CPK(f0[3] + f1[2], 50u) : CPK(f0[0] + f1[6], 6u);
;       c[7] = lh2 ? CPK(f0[3] + f1[3], 51u) : CPK(f0[0] + f1[7], 7u);
;       c[8] = lh2 ? CPK(f0[4] + f1[0], 64u) : CPK(f0[0] + f1[8], 8u);
;       c[9] = lh2 ? CPK(f0[4] + f1[1], 65u) : CPK(f0[0] + f1[9], 9u);
;       c[10] = lh2 ? CPK(f0[4] + f1[2], 66u) : CPK(f0[0] + f1[10], 10u);
;       c[11] = lh2 ? CPK(f0[5] + f1[0], 80u) : CPK(f0[0] + f1[11], 11u);
;       c[12] = lh2 ? CPK(f0[5] + f1[1], 81u) : CPK(f0[0] + f1[12], 12u);
;       c[13] = lh2 ? CPK(f0[6] + f1[0], 96u) : CPK(f0[0] + f1[13], 13u);
;       c[14] = lh2 ? CPK(f0[6] + f1[1], 97u) : CPK(f0[0] + f1[14], 14u);
;       c[15] = lh2 ? CPK(f0[7] + f1[0], 112u) : CPK(f0[0] + f1[15], 15u);
;       c[16] = lh2 ? CPK(f0[7] + f1[1], 113u) : CPK(f0[1] + f1[0], 16u);
;       c[17] = lh2 ? CPK(f0[8] + f1[0], 128u) : CPK(f0[1] + f1[1], 17u);
;       c[18] = lh2 ? CPK(f0[9] + f1[0], 144u) : CPK(f0[1] + f1[2], 18u);
;       c[19] = lh2 ? CPK(f0[10] + f1[0], 160u) : CPK(f0[1] + f1[3], 19u);
;       c[20] = lh2 ? CPK(f0[11] + f1[0], 176u) : CPK(f0[1] + f1[4], 20u);
;       c[21] = lh2 ? CPK(f0[12] + f1[0], 192u) : CPK(f0[1] + f1[5], 21u);
;       c[22] = lh2 ? CPK(f0[13] + f1[0], 208u) : CPK(f0[1] + f1[6], 22u);
	s_waitcnt lgkmcnt(0)
	ds_read_b128 v[24:27], v65 offset:34816
	ds_read_b128 v[16:19], v65 offset:34832
	ds_read_b128 v[8:11], v65 offset:34848
	ds_read_b128 v[0:3], v65 offset:34864
	ds_read_b128 v[28:31], v65 offset:34880
	ds_read_b128 v[20:23], v65 offset:34896
	ds_read_b128 v[12:15], v65 offset:34912
	ds_read_b128 v[4:7], v65 offset:34928
	s_waitcnt lgkmcnt(3)
	v_and_b32_e32 v29, 0xffffff80, v29
	v_and_b32_e32 v38, 0xffffff80, v26
	v_cmp_eq_u32_e64 s[38:39], 0, v76
	v_cmp_ne_u32_e32 vcc, 0, v76
	s_and_saveexec_b64 s[0:1], vcc
	s_xor_b64 s[0:1], exec, s[0:1]
	v_and_b32_e32 v32, 0xffffff80, v3
	v_add_f32_e32 v3, v38, v29
	v_and_or_b32 v26, v3, s44, 33
	s_or_saveexec_b64 s[0:1], s[0:1]
	v_and_b32_e32 v24, 0xffffff80, v24
	v_and_b32_e32 v3, 0xffffff80, v28
	v_mov_b32_e32 v56, 34
	v_mov_b32_e32 v55, 35
	v_mov_b32_e32 v54, 36
	v_mov_b32_e32 v53, 48
	v_mov_b32_e32 v52, 49
	v_mov_b32_e32 v51, 50
	v_mov_b32_e32 v50, 51
	v_mov_b32_e32 v49, 64
	v_mov_b32_e32 v48, 0x41
	v_mov_b32_e32 v46, 0x42
	v_mov_b32_e32 v45, 0x50
	v_mov_b32_e32 v44, 0x51
	v_mov_b32_e32 v43, 0x60
	v_mov_b32_e32 v42, 0x61
	v_mov_b32_e32 v41, 0x70
	v_mov_b32_e32 v40, 0x71
	v_mov_b32_e32 v39, 0x80
	v_mov_b32_e32 v37, 0x90
	v_mov_b32_e32 v36, 0xa0
	v_mov_b32_e32 v35, 0xb0
	v_mov_b32_e32 v34, 0xc0
	v_mov_b32_e32 v33, 0xd0
	v_mov_b32_e32 v28, 0xe0
	v_mov_b32_e32 v47, 0xf0
	s_xor_b64 exec, exec, s[0:1]
	s_cbranch_execz .LBB0_425
	v_add_f32_e32 v26, v24, v3
	v_and_b32_e32 v26, 0xffffff00, v26
	v_mov_b32_e32 v56, 1
	v_mov_b32_e32 v55, 2
	v_mov_b32_e32 v54, 3
	v_mov_b32_e32 v53, 4
	v_mov_b32_e32 v52, 5
	v_mov_b32_e32 v51, 6
	v_mov_b32_e32 v50, 7
	v_mov_b32_e32 v49, 8
	v_mov_b32_e32 v48, 9
	v_mov_b32_e32 v46, 10
	v_mov_b32_e32 v45, 11
	v_mov_b32_e32 v44, 12
	v_mov_b32_e32 v43, 13
	v_mov_b32_e32 v42, 14
	v_mov_b32_e32 v41, 15
	v_mov_b32_e32 v40, 16
	v_mov_b32_e32 v39, 17
	v_mov_b32_e32 v37, 18
	v_mov_b32_e32 v36, 19
	v_mov_b32_e32 v35, 20
	v_mov_b32_e32 v34, 21
	v_mov_b32_e32 v33, 22
	v_mov_b32_e32 v28, 23
	v_mov_b32_e32 v47, 32
	v_mov_b32_e32 v32, v38
	s_branch .LBB0_425

; DEVI int tid_opaque() { int t = threadIdx.x; asm volatile("" : "+v"(t)); return t; }
; DEVI float4 ldbf4(const uint16_t* p) { const uint2 v = *(const uint2*)p; return make_float4(bflo(v.x), bfhi(v.x), bflo(v.y), bfhi(v.y)); }
; __device__ void phase_gather(const P& p, int vb, int nvb, char* smem) {
;   const int t = tid_opaque(), wave = t >> 6, lane = t & 63, g = lane >> 4, j = lane & 15;
;   const uint16_t* h2 = (const uint16_t*)(p.ws + WS_HB);
;   const int* seli = (const int*)(p.ws + WS_SELI); const float* selg = (const float*)(p.ws + WS_SELG);
;   const uint8_t* U = (const uint8_t*)(p.ws + WS_U8); const uint8_t* V = (const uint8_t*)(p.ws + WS_V8);
;   const float* gf = p.in[15]; const float* gfin = p.in[20];
;   uint32_t* kl = (uint32_t*)smem + wave * 1024;
;   float* wl = (float*)(kl + 512);
;   for (int base = (vb * 4 + wave) * 4; base < NREAL; base += nvb * 16) {
;     const int rr = base + g;
;     const uint16_t* hr = h2 + (size_t)rr * DM;
;     f32x2 xf[32];
;     {
;       float ss = 0.f;
; #pragma unroll
;       for (int i = 0; i < 4; i++)
; #pragma unroll
;         for (int q = 0; q < 4; q++) {
;           const float4 a = ldbf4(hr + i * 256 + 16 * j + 4 * q);
;           ss += a.x * a.x + a.y * a.y + a.z * a.z + a.w * a.w;
;         }
;       const float rstd = rsqrtf(wsum16(ss) * (1.f / 1024.f) + EPS);
.LBB0_494:
	s_or_b64 exec, exec, s[0:1]
	s_waitcnt lgkmcnt(0)
	s_barrier
	s_lshl_b32 s0, s2, 4
	s_add_u32 s98, s80, 0x864000
	s_addc_u32 s99, s81, 0
	s_add_u32 s100, s80, 0x1864000
	s_addc_u32 s101, s81, 0
	s_nop 0
	v_ashrrev_i32_e32 v0, 6, v178
	s_mov_b32 s83, 0
	v_lshl_add_u32 v126, v0, 2, s0
	s_mov_b32 s0, 0x8000
	v_cmp_gt_i32_e32 vcc, s0, v126
	s_and_saveexec_b64 s[0:1], vcc
	s_cbranch_execz .LBB0_535
	v_and_b32_e32 v1, 64, v162
	v_lshlrev_b32_e32 v4, 12, v0
	v_xor_b32_e32 v0, 1, v162
	v_add_u32_e32 v1, 64, v1
	v_cmp_lt_i32_e32 vcc, v0, v1
	v_bfe_u32 v127, v178, 4, 2
	v_and_b32_e32 v6, 15, v178
	v_cndmask_b32_e32 v0, v162, v0, vcc
	v_lshlrev_b32_e32 v128, 2, v0
	v_xor_b32_e32 v0, 2, v162
	v_cmp_lt_i32_e32 vcc, v0, v1
	v_lshlrev_b32_e32 v12, 4, v6
	v_mov_b32_e32 v13, 0
	v_cndmask_b32_e32 v0, v162, v0, vcc
	v_lshlrev_b32_e32 v129, 2, v0
	v_xor_b32_e32 v0, 4, v162
	v_cmp_lt_i32_e32 vcc, v0, v1
	v_lshlrev_b32_e32 v5, 9, v127
	v_and_b32_e32 v8, 8, v178
	v_cndmask_b32_e32 v0, v162, v0, vcc
	v_lshlrev_b32_e32 v130, 2, v0
	v_xor_b32_e32 v0, 8, v162
	v_cmp_lt_i32_e32 vcc, v0, v1
	v_mov_b32_e32 v1, v13
	v_lshlrev_b32_e32 v2, 5, v6
	v_cndmask_b32_e32 v0, v162, v0, vcc
	v_lshlrev_b32_e32 v131, 2, v0
	v_lshlrev_b32_e32 v0, 6, v6
	v_add3_u32 v133, 16, v4, v5
	v_lshl_add_u64 v[4:5], s[80:81], 0, v[12:13]
	s_mov_b64 s[0:1], 0x864000
	v_cmp_eq_u32_e32 vcc, 0, v8
	v_and_b32_e32 v8, 4, v178
	v_and_b32_e32 v9, 2, v178
	v_and_b32_e32 v10, 1, v178
	s_mov_b64 s[6:7], 0x1864000
	v_lshl_add_u64 v[14:15], s[58:59], 0, v[0:1]
	v_lshlrev_b32_e32 v132, 3, v6
	v_mov_b32_e32 v3, v13
	v_add_u32_e32 v134, v133, v2
	v_mul_i32_i24_e32 v7, 0xffffffe4, v6
	v_lshl_add_u64 v[18:19], v[4:5], 0, s[0:1]
	v_cmp_eq_u32_e64 s[0:1], 0, v8
	v_cmp_eq_u32_e64 s[2:3], 0, v9
	v_cmp_eq_u32_e64 s[4:5], 0, v10
	v_lshl_add_u64 v[20:21], v[4:5], 0, s[6:7]
	v_lshl_add_u64 v[22:23], s[76:77], 0, v[0:1]
	v_cmp_ne_u32_e64 s[6:7], 0, v9
	v_cmp_ne_u32_e64 s[10:11], 0, v8
	v_cmp_lt_u32_e64 s[16:17], 7, v6
	v_lshl_add_u64 v[26:27], s[78:79], 0, v[0:1]
	v_lshlrev_b32_e32 v0, 1, v178
	s_lshl_b32 s28, s82, 4
	v_lshl_add_u64 v[16:17], s[24:25], 0, v[2:3]
	v_lshl_add_u64 v[24:25], s[52:53], 0, v[2:3]
	v_or_b32_e32 v135, 1, v132
	v_or_b32_e32 v136, 2, v132
	v_or_b32_e32 v137, 3, v132
	v_or_b32_e32 v138, 4, v132
	v_or_b32_e32 v139, 5, v132
	v_or_b32_e32 v140, 6, v132
	v_or_b32_e32 v141, 7, v132
	s_xor_b64 s[6:7], s[4:5], s[6:7]
	s_xor_b64 s[8:9], s[2:3], s[10:11]
	s_xor_b64 s[10:11], s[4:5], s[10:11]
	s_xor_b64 s[12:13], s[0:1], s[16:17]
	s_xor_b64 s[14:15], s[2:3], s[16:17]
	s_xor_b64 s[16:17], s[4:5], s[16:17]
	v_cmp_gt_u32_e64 s[18:19], 8, v6
	v_and_b32_e32 v142, 28, v0
	s_mov_b64 s[24:25], 0
	v_mov_b32_e32 v143, 0x358637bd
	s_mov_b32 s29, 0x800000
	s_movk_i32 s30, 0x7fff
	v_add_u32_e32 v144, v134, v7
	s_mov_b32 s31, 0x378e98ab
	s_mov_b32 s33, 0x3b7cd369
	s_mov_b32 s34, 0xbcc618b2
	s_mov_b32 s35, 0x3dda74e4
	s_mov_b32 s36, 0x3f228afd
	s_mov_b32 s37, 0x3e03c728
	s_mov_b32 s38, 0xbfb8aa3b
	s_mov_b32 s39, 0x42ce8ed0
	s_mov_b32 s40, 0xc2b17218
	v_mov_b32_e32 v145, 0x3ba10414
	s_brev_b32 s41, -2
	v_mov_b32_e32 v146, 1
	v_mov_b32_e32 v147, 0xb9c68948
	v_mov_b32_e32 v148, 0x7f800000
.LBB0_496:
	v_or_b32_e32 v0, v126, v127
	v_ashrrev_i32_e32 v1, 31, v0
	v_lshlrev_b64 v[2:3], 11, v[0:1]
	v_lshl_add_u64 v[28:29], v[24:25], 0, v[2:3]
	global_load_dwordx4 v[2:5], v[28:29], off
	global_load_dwordx4 v[6:9], v[28:29], off offset:16
	global_load_dwordx4 v[30:33], v[28:29], off offset:512
	global_load_dwordx4 v[34:37], v[28:29], off offset:528
	global_load_dwordx4 v[38:41], v[28:29], off offset:1024
	global_load_dwordx4 v[42:45], v[28:29], off offset:1040
	global_load_dwordx4 v[46:49], v[28:29], off offset:1536
	global_load_dwordx4 v[50:53], v[28:29], off offset:1552
	s_waitcnt vmcnt(7)
	v_lshlrev_b32_e32 v58, 16, v4
	v_and_b32_e32 v59, 0xffff0000, v4
	v_lshlrev_b32_e32 v60, 16, v5
	v_and_b32_e32 v61, 0xffff0000, v5
	s_waitcnt vmcnt(6)
	v_lshlrev_b32_e32 v62, 16, v6
	v_and_b32_e32 v63, 0xffff0000, v6
	v_lshlrev_b32_e32 v64, 16, v7
	v_and_b32_e32 v65, 0xffff0000, v7
	v_lshlrev_b32_e32 v6, 16, v8
	v_and_b32_e32 v7, 0xffff0000, v8
	v_lshlrev_b32_e32 v4, 16, v9
	v_and_b32_e32 v5, 0xffff0000, v9
	s_waitcnt vmcnt(2)
	v_and_b32_e32 v9, 0xffff0000, v44
	v_and_b32_e32 v8, 0xffff0000, v42
	v_lshlrev_b32_e32 v54, 16, v2
	v_and_b32_e32 v55, 0xffff0000, v2
	v_lshlrev_b32_e32 v56, 16, v3
	v_and_b32_e32 v57, 0xffff0000, v3
	v_lshlrev_b32_e32 v3, 16, v44
	v_lshlrev_b32_e32 v2, 16, v42
	v_pk_mul_f32 v[8:9], v[8:9], v[8:9]
	v_lshlrev_b32_e32 v69, 16, v32
	v_and_b32_e32 v32, 0xffff0000, v32
	v_lshlrev_b32_e32 v72, 16, v34
	v_and_b32_e32 v34, 0xffff0000, v34
	v_pk_fma_f32 v[2:3], v[2:3], v[2:3], v[8:9]
	s_waitcnt vmcnt(1)
; DEVI uint32_t f2bf(float f) { uint32_t u = __float_as_uint(f); return (u + 0x7fffu + ((u >> 16) & 1u)) >> 16; }
; DEVI float bf1(uint16_t h) { return __uint_as_float(((uint32_t)h) << 16); }
; DEVI float4 ldbf4(const uint16_t* p) { const uint2 v = *(const uint2*)p; return make_float4(bflo(v.x), bfhi(v.x), bflo(v.y), bfhi(v.y)); }
; __device__ void phase_gather(const P& p, int vb, int nvb, char* smem) {
;     ...
;       float ss = 0.f;
; #pragma unroll
;       for (int i = 0; i < 4; i++)
; #pragma unroll
;         for (int q = 0; q < 4; q++) {
;           const float4 a = ldbf4(hr + i * 256 + 16 * j + 4 * q);
;           ss += a.x * a.x + a.y * a.y + a.z * a.z + a.w * a.w;
;         }
;       const float rstd = rsqrtf(wsum16(ss) * (1.f / 1024.f) + EPS);
; #pragma unroll
;       for (int i = 0; i < 4; i++) {
; #pragma unroll
;         for (int q = 0; q < 4; q++) {
;           const float4 a = ldbf4(hr + i * 256 + 16 * j + 4 * q);
;           const float4 ga = *(const float4*)(gf + i * 256 + 16 * j + 4 * q);
;           xf[i * 8 + q * 2 + 0] = f32x2{bf1((uint16_t)f2bf(a.x * rstd * ga.x)), bf1((uint16_t)f2bf(a.y * rstd * ga.y))};
;           xf[i * 8 + q * 2 + 1] = f32x2{bf1((uint16_t)f2bf(a.z * rstd * ga.z)), bf1((uint16_t)f2bf(a.w * rstd * ga.w))};
	v_and_b32_e32 v9, 0xffff0000, v48
	v_and_b32_e32 v8, 0xffff0000, v46
	v_lshlrev_b32_e32 v70, 16, v33
	v_and_b32_e32 v71, 0xffff0000, v33
	v_lshlrev_b32_e32 v11, 16, v45
	v_lshlrev_b32_e32 v10, 16, v43
	v_lshlrev_b32_e32 v33, 16, v48
	v_mul_f32_e32 v81, v32, v32
	v_mul_f32_e32 v82, v34, v34
	v_lshlrev_b32_e32 v32, 16, v46
	v_pk_mul_f32 v[8:9], v[8:9], v[8:9]
	v_lshlrev_b32_e32 v12, 16, v30
	v_and_b32_e32 v66, 0xffff0000, v30
	v_lshlrev_b32_e32 v67, 16, v31
	v_and_b32_e32 v68, 0xffff0000, v31
	v_lshlrev_b32_e32 v73, 16, v35
	v_and_b32_e32 v31, 0xffff0000, v45
	v_and_b32_e32 v30, 0xffff0000, v43
	v_fmac_f32_e32 v82, v72, v72
	v_pk_fma_f32 v[2:3], v[10:11], v[10:11], v[2:3]
	v_lshlrev_b32_e32 v11, 16, v49
	v_lshlrev_b32_e32 v10, 16, v47
	v_pk_fma_f32 v[8:9], v[32:33], v[32:33], v[8:9]
	v_and_b32_e32 v35, 0xffff0000, v35
	v_fmac_f32_e32 v82, v73, v73
	v_pk_fma_f32 v[2:3], v[30:31], v[30:31], v[2:3]
	v_and_b32_e32 v31, 0xffff0000, v49
	v_and_b32_e32 v30, 0xffff0000, v47
	v_pk_fma_f32 v[8:9], v[10:11], v[10:11], v[8:9]
	v_fmac_f32_e32 v82, v35, v35
	v_pk_fma_f32 v[30:31], v[30:31], v[30:31], v[8:9]
	global_load_dwordx4 v[8:11], v[14:15], off offset:16
	global_load_dwordx4 v[32:35], v[14:15], off
	v_lshlrev_b32_e32 v76, 16, v38
	v_and_b32_e32 v38, 0xffff0000, v38
	v_lshlrev_b32_e32 v74, 16, v36
	v_and_b32_e32 v36, 0xffff0000, v36
	v_mul_f32_e32 v84, v38, v38
	v_lshlrev_b32_e32 v77, 16, v39
	v_lshlrev_b32_e32 v78, 16, v40
	v_and_b32_e32 v40, 0xffff0000, v40
	v_mul_f32_e32 v83, v36, v36
	v_fmac_f32_e32 v84, v76, v76
	v_lshlrev_b32_e32 v75, 16, v37
	v_and_b32_e32 v39, 0xffff0000, v39
	v_mul_f32_e32 v85, v40, v40
	v_fmac_f32_e32 v83, v74, v74
	v_fmac_f32_e32 v84, v77, v77
	v_and_b32_e32 v37, 0xffff0000, v37
	v_lshlrev_b32_e32 v79, 16, v41
	v_fmac_f32_e32 v85, v78, v78
	v_fmac_f32_e32 v83, v75, v75
	v_fmac_f32_e32 v84, v39, v39
	s_waitcnt vmcnt(2)
	v_and_b32_e32 v39, 0xffff0000, v52
	v_and_b32_e32 v38, 0xffff0000, v50
	v_and_b32_e32 v41, 0xffff0000, v41
	v_fmac_f32_e32 v85, v79, v79
	v_fmac_f32_e32 v83, v37, v37
	v_lshlrev_b32_e32 v37, 16, v52
	v_lshlrev_b32_e32 v36, 16, v50
	v_pk_mul_f32 v[38:39], v[38:39], v[38:39]
	v_fmac_f32_e32 v85, v41, v41
	v_lshlrev_b32_e32 v41, 16, v53
	v_lshlrev_b32_e32 v40, 16, v51
	v_pk_fma_f32 v[36:37], v[36:37], v[36:37], v[38:39]
	v_and_b32_e32 v43, 0xffff0000, v53
	v_and_b32_e32 v42, 0xffff0000, v51
	v_pk_fma_f32 v[36:37], v[40:41], v[40:41], v[36:37]
	v_mul_f32_e32 v80, v66, v66
	v_pk_fma_f32 v[36:37], v[42:43], v[42:43], v[36:37]
	global_load_dwordx4 v[40:43], v[14:15], off offset:32
	v_fmac_f32_e32 v80, v12, v12
	v_fmac_f32_e32 v80, v67, v67
	v_pk_mul_f32 v[52:53], v[58:59], v[58:59]
	v_fmac_f32_e32 v81, v69, v69
	v_fmac_f32_e32 v80, v68, v68
	v_pk_mul_f32 v[50:51], v[60:61], v[60:61]
	v_pk_mul_f32 v[68:69], v[54:55], v[54:55]
	v_add_f32_e32 v12, v52, v53
	v_pk_mul_f32 v[48:49], v[62:63], v[62:63]
	v_pk_mul_f32 v[66:67], v[56:57], v[56:57]
	v_add_f32_e32 v12, v12, v50
	v_add_f32_e32 v50, v68, v69
	v_pk_mul_f32 v[46:47], v[64:65], v[64:65]
	v_add_f32_e32 v50, v50, v66
	v_add_f32_e32 v48, v48, v49
	v_pk_mul_f32 v[44:45], v[6:7], v[6:7]
	v_add_f32_e32 v12, v51, v12
	v_add_f32_e32 v50, v67, v50
	v_add_f32_e32 v46, v48, v46
	v_pk_mul_f32 v[38:39], v[4:5], v[4:5]
	v_add_f32_e32 v12, v50, v12
	v_add_f32_e32 v46, v47, v46
	v_add_f32_e32 v44, v44, v45
	v_add_f32_e32 v12, v12, v46
	v_add_f32_e32 v38, v44, v38
	global_load_dwordx4 v[44:47], v[14:15], off offset:48
	v_add_f32_e32 v38, v39, v38
	v_fmac_f32_e32 v81, v70, v70
	v_add_f32_e32 v12, v12, v38
	v_fmac_f32_e32 v81, v71, v71
	v_add_f32_e32 v12, v12, v80
	v_add_f32_e32 v12, v12, v81
	v_add_f32_e32 v12, v12, v82
	v_add_f32_e32 v12, v12, v83
	v_add_f32_e32 v12, v12, v84
	v_add_f32_e32 v12, v12, v85
	v_add_f32_e32 v2, v12, v2
	v_add_f32_e32 v2, v2, v3
	v_add_f32_e32 v2, v2, v30
	v_add_f32_e32 v2, v2, v31
	v_add_f32_e32 v2, v2, v36
	v_add_f32_e32 v2, v2, v37
	ds_bpermute_b32 v3, v128, v2
	v_lshlrev_b64 v[30:31], 10, v[0:1]
	s_waitcnt lgkmcnt(0)
	v_add_f32_e32 v2, v2, v3
	ds_bpermute_b32 v3, v129, v2
	s_waitcnt lgkmcnt(0)
	v_add_f32_e32 v2, v2, v3
	ds_bpermute_b32 v3, v130, v2
	s_waitcnt lgkmcnt(0)
	v_add_f32_e32 v2, v2, v3
	ds_bpermute_b32 v3, v131, v2
	s_waitcnt lgkmcnt(0)
	v_add_f32_e32 v2, v2, v3
	v_fmamk_f32 v2, v2, 0x3a800000, v143
	v_mul_f32_e32 v3, 0x4b800000, v2
	v_cmp_gt_f32_e64 s[20:21], s29, v2
	s_nop 1
	v_cndmask_b32_e64 v2, v2, v3, s[20:21]
	v_rsq_f32_e32 v2, v2
	s_nop 0
	v_mul_f32_e32 v3, 0x45800000, v2
	v_cndmask_b32_e64 v2, v2, v3, s[20:21]
	v_pk_mul_f32 v[36:37], v[2:3], v[54:55] op_sel_hi:[0,1]
	s_waitcnt vmcnt(2)
	v_pk_mul_f32 v[32:33], v[32:33], v[36:37]
	s_nop 0
	v_and_b32_sdwa v3, v33, v146 dst_sel:DWORD dst_unused:UNUSED_PAD src0_sel:WORD_1 src1_sel:DWORD
	v_add3_u32 v3, v33, v3, s30
	v_pk_mul_f32 v[36:37], v[2:3], v[56:57] op_sel_hi:[0,1]
	v_pk_mul_f32 v[34:35], v[34:35], v[36:37]
	v_and_b32_sdwa v12, v32, v146 dst_sel:DWORD dst_unused:UNUSED_PAD src0_sel:WORD_1 src1_sel:DWORD
	v_and_b32_e32 v33, 0xffff0000, v3
	v_and_b32_sdwa v3, v35, v146 dst_sel:DWORD dst_unused:UNUSED_PAD src0_sel:WORD_1 src1_sel:DWORD
	v_add3_u32 v12, v32, v12, s30
	v_add3_u32 v3, v35, v3, s30
	v_and_b32_e32 v32, 0xffff0000, v12
	v_and_b32_sdwa v12, v34, v146 dst_sel:DWORD dst_unused:UNUSED_PAD src0_sel:WORD_1 src1_sel:DWORD
	v_pk_mul_f32 v[36:37], v[2:3], v[58:59] op_sel_hi:[0,1]
	v_add3_u32 v12, v34, v12, s30
	v_pk_mul_f32 v[8:9], v[8:9], v[36:37]
	v_and_b32_e32 v35, 0xffff0000, v3
	v_and_b32_e32 v34, 0xffff0000, v12
	v_and_b32_sdwa v3, v9, v146 dst_sel:DWORD dst_unused:UNUSED_PAD src0_sel:WORD_1 src1_sel:DWORD
	v_and_b32_sdwa v12, v8, v146 dst_sel:DWORD dst_unused:UNUSED_PAD src0_sel:WORD_1 src1_sel:DWORD
	v_add3_u32 v3, v9, v3, s30
	v_add3_u32 v8, v8, v12, s30
	v_and_b32_e32 v36, 0xffff0000, v8
	v_pk_mul_f32 v[8:9], v[2:3], v[60:61] op_sel_hi:[0,1]
	v_pk_mul_f32 v[8:9], v[10:11], v[8:9]
	v_and_b32_e32 v37, 0xffff0000, v3
	v_and_b32_sdwa v3, v9, v146 dst_sel:DWORD dst_unused:UNUSED_PAD src0_sel:WORD_1 src1_sel:DWORD
	v_and_b32_sdwa v10, v8, v146 dst_sel:DWORD dst_unused:UNUSED_PAD src0_sel:WORD_1 src1_sel:DWORD
	v_add3_u32 v3, v9, v3, s30
	v_add3_u32 v8, v8, v10, s30
	v_and_b32_e32 v38, 0xffff0000, v8
	v_pk_mul_f32 v[8:9], v[2:3], v[62:63] op_sel_hi:[0,1]
	s_waitcnt vmcnt(1)
; DEVI uint32_t f2bf(float f) { uint32_t u = __float_as_uint(f); return (u + 0x7fffu + ((u >> 16) & 1u)) >> 16; }
; DEVI float bf1(uint16_t h) { return __uint_as_float(((uint32_t)h) << 16); }
; DEVI float4 ldbf4(const uint16_t* p) { const uint2 v = *(const uint2*)p; return make_float4(bflo(v.x), bfhi(v.x), bflo(v.y), bfhi(v.y)); }
; __device__ void phase_gather(const P& p, int vb, int nvb, char* smem) {
;     ...
;       for (int i = 0; i < 4; i++) {
; #pragma unroll
;         for (int q = 0; q < 4; q++) {
;           const float4 a = ldbf4(hr + i * 256 + 16 * j + 4 * q);
;           const float4 ga = *(const float4*)(gf + i * 256 + 16 * j + 4 * q);
;           xf[i * 8 + q * 2 + 0] = f32x2{bf1((uint16_t)f2bf(a.x * rstd * ga.x)), bf1((uint16_t)f2bf(a.y * rstd * ga.y))};
;           xf[i * 8 + q * 2 + 1] = f32x2{bf1((uint16_t)f2bf(a.z * rstd * ga.z)), bf1((uint16_t)f2bf(a.w * rstd * ga.w))};
;         }
;         __builtin_amdgcn_sched_barrier(0);
	v_pk_mul_f32 v[8:9], v[40:41], v[8:9]
	v_and_b32_e32 v39, 0xffff0000, v3
	v_and_b32_sdwa v3, v9, v146 dst_sel:DWORD dst_unused:UNUSED_PAD src0_sel:WORD_1 src1_sel:DWORD
	v_and_b32_sdwa v10, v8, v146 dst_sel:DWORD dst_unused:UNUSED_PAD src0_sel:WORD_1 src1_sel:DWORD
	v_add3_u32 v3, v9, v3, s30
	v_add3_u32 v8, v8, v10, s30
	v_and_b32_e32 v40, 0xffff0000, v8
	v_pk_mul_f32 v[8:9], v[2:3], v[64:65] op_sel_hi:[0,1]
	v_pk_mul_f32 v[8:9], v[42:43], v[8:9]
	v_and_b32_e32 v41, 0xffff0000, v3
	v_and_b32_sdwa v3, v9, v146 dst_sel:DWORD dst_unused:UNUSED_PAD src0_sel:WORD_1 src1_sel:DWORD
	v_add3_u32 v3, v9, v3, s30
	v_pk_mul_f32 v[6:7], v[2:3], v[6:7] op_sel_hi:[0,1]
	s_waitcnt vmcnt(0)
	v_pk_mul_f32 v[6:7], v[44:45], v[6:7]
	v_and_b32_sdwa v10, v8, v146 dst_sel:DWORD dst_unused:UNUSED_PAD src0_sel:WORD_1 src1_sel:DWORD
	v_and_b32_e32 v43, 0xffff0000, v3
	v_and_b32_sdwa v3, v7, v146 dst_sel:DWORD dst_unused:UNUSED_PAD src0_sel:WORD_1 src1_sel:DWORD
	v_add3_u32 v8, v8, v10, s30
	v_add3_u32 v3, v7, v3, s30
	v_and_b32_e32 v42, 0xffff0000, v8
	v_and_b32_sdwa v8, v6, v146 dst_sel:DWORD dst_unused:UNUSED_PAD src0_sel:WORD_1 src1_sel:DWORD
	v_pk_mul_f32 v[4:5], v[2:3], v[4:5] op_sel_hi:[0,1]
	v_add3_u32 v6, v6, v8, s30
	v_pk_mul_f32 v[4:5], v[4:5], v[46:47]
	v_and_b32_e32 v45, 0xffff0000, v3
	v_and_b32_e32 v44, 0xffff0000, v6
	v_and_b32_sdwa v3, v5, v146 dst_sel:DWORD dst_unused:UNUSED_PAD src0_sel:WORD_1 src1_sel:DWORD
	v_and_b32_sdwa v6, v4, v146 dst_sel:DWORD dst_unused:UNUSED_PAD src0_sel:WORD_1 src1_sel:DWORD
	v_add3_u32 v3, v5, v3, s30
	v_add3_u32 v4, v4, v6, s30
	v_and_b32_e32 v47, 0xffff0000, v3
	v_and_b32_e32 v46, 0xffff0000, v4
	global_load_dwordx4 v[4:7], v[28:29], off offset:512
	global_load_dwordx4 v[8:11], v[28:29], off offset:528
	global_load_dwordx4 v[48:51], v[14:15], off offset:1024
	global_load_dwordx4 v[52:55], v[14:15], off offset:1040
	global_load_dwordx4 v[56:59], v[14:15], off offset:1056
	global_load_dwordx4 v[60:63], v[14:15], off offset:1072
	s_waitcnt vmcnt(5)
	v_lshlrev_b32_e32 v64, 16, v4
	v_and_b32_e32 v65, 0xffff0000, v4
	v_lshlrev_b32_e32 v4, 16, v5
	v_and_b32_e32 v5, 0xffff0000, v5
	v_lshlrev_b32_e32 v66, 16, v6
	v_and_b32_e32 v67, 0xffff0000, v6
	v_lshlrev_b32_e32 v6, 16, v7
	v_and_b32_e32 v7, 0xffff0000, v7
	s_waitcnt vmcnt(4)
	v_lshlrev_b32_e32 v68, 16, v8
	v_and_b32_e32 v69, 0xffff0000, v8
	v_lshlrev_b32_e32 v8, 16, v9
	v_and_b32_e32 v9, 0xffff0000, v9
	v_lshlrev_b32_e32 v70, 16, v10
	v_and_b32_e32 v71, 0xffff0000, v10
	v_lshlrev_b32_e32 v10, 16, v11
	v_and_b32_e32 v11, 0xffff0000, v11
	v_pk_mul_f32 v[64:65], v[2:3], v[64:65] op_sel_hi:[0,1]
	v_pk_mul_f32 v[4:5], v[2:3], v[4:5] op_sel_hi:[0,1]
	v_pk_mul_f32 v[66:67], v[2:3], v[66:67] op_sel_hi:[0,1]
	v_pk_mul_f32 v[6:7], v[2:3], v[6:7] op_sel_hi:[0,1]
	v_pk_mul_f32 v[68:69], v[2:3], v[68:69] op_sel_hi:[0,1]
	v_pk_mul_f32 v[8:9], v[2:3], v[8:9] op_sel_hi:[0,1]
	v_pk_mul_f32 v[70:71], v[2:3], v[70:71] op_sel_hi:[0,1]
	v_pk_mul_f32 v[10:11], v[2:3], v[10:11] op_sel_hi:[0,1]
	s_waitcnt vmcnt(3)
	v_pk_mul_f32 v[48:49], v[48:49], v[64:65]
	v_pk_mul_f32 v[4:5], v[4:5], v[50:51]
	s_waitcnt vmcnt(2)
	v_pk_mul_f32 v[50:51], v[52:53], v[66:67]
	v_pk_mul_f32 v[6:7], v[6:7], v[54:55]
	s_waitcnt vmcnt(1)
	v_pk_mul_f32 v[52:53], v[56:57], v[68:69]
	v_pk_mul_f32 v[8:9], v[8:9], v[58:59]
	s_waitcnt vmcnt(0)
	v_pk_mul_f32 v[54:55], v[60:61], v[70:71]
	v_pk_mul_f32 v[10:11], v[10:11], v[62:63]
	v_and_b32_sdwa v3, v49, v146 dst_sel:DWORD dst_unused:UNUSED_PAD src0_sel:WORD_1 src1_sel:DWORD
	v_and_b32_sdwa v12, v48, v146 dst_sel:DWORD dst_unused:UNUSED_PAD src0_sel:WORD_1 src1_sel:DWORD
	v_and_b32_sdwa v56, v5, v146 dst_sel:DWORD dst_unused:UNUSED_PAD src0_sel:WORD_1 src1_sel:DWORD
	v_and_b32_sdwa v57, v4, v146 dst_sel:DWORD dst_unused:UNUSED_PAD src0_sel:WORD_1 src1_sel:DWORD
	v_and_b32_sdwa v58, v51, v146 dst_sel:DWORD dst_unused:UNUSED_PAD src0_sel:WORD_1 src1_sel:DWORD
	v_and_b32_sdwa v59, v50, v146 dst_sel:DWORD dst_unused:UNUSED_PAD src0_sel:WORD_1 src1_sel:DWORD
	v_and_b32_sdwa v60, v7, v146 dst_sel:DWORD dst_unused:UNUSED_PAD src0_sel:WORD_1 src1_sel:DWORD
	v_and_b32_sdwa v61, v6, v146 dst_sel:DWORD dst_unused:UNUSED_PAD src0_sel:WORD_1 src1_sel:DWORD
	v_and_b32_sdwa v62, v53, v146 dst_sel:DWORD dst_unused:UNUSED_PAD src0_sel:WORD_1 src1_sel:DWORD
	v_and_b32_sdwa v63, v52, v146 dst_sel:DWORD dst_unused:UNUSED_PAD src0_sel:WORD_1 src1_sel:DWORD
	v_and_b32_sdwa v64, v9, v146 dst_sel:DWORD dst_unused:UNUSED_PAD src0_sel:WORD_1 src1_sel:DWORD
	v_and_b32_sdwa v65, v8, v146 dst_sel:DWORD dst_unused:UNUSED_PAD src0_sel:WORD_1 src1_sel:DWORD
	v_and_b32_sdwa v66, v55, v146 dst_sel:DWORD dst_unused:UNUSED_PAD src0_sel:WORD_1 src1_sel:DWORD
	v_and_b32_sdwa v67, v54, v146 dst_sel:DWORD dst_unused:UNUSED_PAD src0_sel:WORD_1 src1_sel:DWORD
	v_and_b32_sdwa v68, v11, v146 dst_sel:DWORD dst_unused:UNUSED_PAD src0_sel:WORD_1 src1_sel:DWORD
	v_and_b32_sdwa v69, v10, v146 dst_sel:DWORD dst_unused:UNUSED_PAD src0_sel:WORD_1 src1_sel:DWORD
	v_add3_u32 v3, v49, v3, s30
	v_add3_u32 v12, v48, v12, s30
	v_add3_u32 v5, v5, v56, s30
	v_add3_u32 v4, v4, v57, s30
	v_add3_u32 v56, v51, v58, s30
	v_add3_u32 v57, v50, v59, s30
	v_add3_u32 v7, v7, v60, s30
	v_add3_u32 v6, v6, v61, s30
	v_add3_u32 v58, v53, v62, s30
	v_add3_u32 v59, v52, v63, s30
	v_add3_u32 v9, v9, v64, s30
	v_add3_u32 v8, v8, v65, s30
	v_add3_u32 v60, v55, v66, s30
	v_add3_u32 v62, v54, v67, s30
	v_add3_u32 v11, v11, v68, s30
	v_add3_u32 v10, v10, v69, s30
	v_and_b32_e32 v49, 0xffff0000, v3
	v_and_b32_e32 v48, 0xffff0000, v12
	v_and_b32_e32 v51, 0xffff0000, v5
	v_and_b32_e32 v50, 0xffff0000, v4
	v_and_b32_e32 v53, 0xffff0000, v56
	v_and_b32_e32 v52, 0xffff0000, v57
	v_and_b32_e32 v55, 0xffff0000, v7
	v_and_b32_e32 v54, 0xffff0000, v6
	v_and_b32_e32 v57, 0xffff0000, v58
	v_and_b32_e32 v56, 0xffff0000, v59
	v_and_b32_e32 v59, 0xffff0000, v9
	v_and_b32_e32 v58, 0xffff0000, v8
	v_and_b32_e32 v61, 0xffff0000, v60
	v_and_b32_e32 v60, 0xffff0000, v62
	v_and_b32_e32 v63, 0xffff0000, v11
	v_and_b32_e32 v62, 0xffff0000, v10
	global_load_dwordx4 v[4:7], v[28:29], off offset:1024
	global_load_dwordx4 v[8:11], v[28:29], off offset:1040
	global_load_dwordx4 v[64:67], v[14:15], off offset:2048
	global_load_dwordx4 v[68:71], v[14:15], off offset:2064
	global_load_dwordx4 v[72:75], v[14:15], off offset:2080
	global_load_dwordx4 v[76:79], v[14:15], off offset:2096
	s_waitcnt vmcnt(5)
; DEVI uint32_t f2bf(float f) { uint32_t u = __float_as_uint(f); return (u + 0x7fffu + ((u >> 16) & 1u)) >> 16; }
; DEVI float bf1(uint16_t h) { return __uint_as_float(((uint32_t)h) << 16); }
; DEVI float4 ldbf4(const uint16_t* p) { const uint2 v = *(const uint2*)p; return make_float4(bflo(v.x), bfhi(v.x), bflo(v.y), bfhi(v.y)); }
; __device__ void phase_gather(const P& p, int vb, int nvb, char* smem) {
;     ...
;       for (int i = 0; i < 4; i++) {
; #pragma unroll
;         for (int q = 0; q < 4; q++) {
;           const float4 a = ldbf4(hr + i * 256 + 16 * j + 4 * q);
;           const float4 ga = *(const float4*)(gf + i * 256 + 16 * j + 4 * q);
;           xf[i * 8 + q * 2 + 0] = f32x2{bf1((uint16_t)f2bf(a.x * rstd * ga.x)), bf1((uint16_t)f2bf(a.y * rstd * ga.y))};
;           xf[i * 8 + q * 2 + 1] = f32x2{bf1((uint16_t)f2bf(a.z * rstd * ga.z)), bf1((uint16_t)f2bf(a.w * rstd * ga.w))};
;         }
;         __builtin_amdgcn_sched_barrier(0);
	v_lshlrev_b32_e32 v80, 16, v4
	v_and_b32_e32 v81, 0xffff0000, v4
	v_lshlrev_b32_e32 v4, 16, v5
	v_and_b32_e32 v5, 0xffff0000, v5
	v_lshlrev_b32_e32 v82, 16, v6
	v_and_b32_e32 v83, 0xffff0000, v6
	v_lshlrev_b32_e32 v6, 16, v7
	v_and_b32_e32 v7, 0xffff0000, v7
	s_waitcnt vmcnt(4)
	v_lshlrev_b32_e32 v84, 16, v8
	v_and_b32_e32 v85, 0xffff0000, v8
	v_lshlrev_b32_e32 v8, 16, v9
	v_and_b32_e32 v9, 0xffff0000, v9
	v_lshlrev_b32_e32 v86, 16, v10
	v_and_b32_e32 v87, 0xffff0000, v10
	v_lshlrev_b32_e32 v10, 16, v11
	v_and_b32_e32 v11, 0xffff0000, v11
	v_pk_mul_f32 v[80:81], v[2:3], v[80:81] op_sel_hi:[0,1]
	v_pk_mul_f32 v[4:5], v[2:3], v[4:5] op_sel_hi:[0,1]
	v_pk_mul_f32 v[82:83], v[2:3], v[82:83] op_sel_hi:[0,1]
	v_pk_mul_f32 v[6:7], v[2:3], v[6:7] op_sel_hi:[0,1]
	v_pk_mul_f32 v[84:85], v[2:3], v[84:85] op_sel_hi:[0,1]
	v_pk_mul_f32 v[8:9], v[2:3], v[8:9] op_sel_hi:[0,1]
	v_pk_mul_f32 v[86:87], v[2:3], v[86:87] op_sel_hi:[0,1]
	v_pk_mul_f32 v[10:11], v[2:3], v[10:11] op_sel_hi:[0,1]
	s_waitcnt vmcnt(3)
	v_pk_mul_f32 v[64:65], v[64:65], v[80:81]
	v_pk_mul_f32 v[4:5], v[4:5], v[66:67]
	s_waitcnt vmcnt(2)
	v_pk_mul_f32 v[66:67], v[68:69], v[82:83]
	v_pk_mul_f32 v[6:7], v[6:7], v[70:71]
	s_waitcnt vmcnt(1)
	v_pk_mul_f32 v[68:69], v[72:73], v[84:85]
	v_pk_mul_f32 v[8:9], v[8:9], v[74:75]
	s_waitcnt vmcnt(0)
	v_pk_mul_f32 v[70:71], v[76:77], v[86:87]
	v_pk_mul_f32 v[10:11], v[10:11], v[78:79]
	v_and_b32_sdwa v3, v65, v146 dst_sel:DWORD dst_unused:UNUSED_PAD src0_sel:WORD_1 src1_sel:DWORD
	v_and_b32_sdwa v12, v64, v146 dst_sel:DWORD dst_unused:UNUSED_PAD src0_sel:WORD_1 src1_sel:DWORD
	v_and_b32_sdwa v72, v5, v146 dst_sel:DWORD dst_unused:UNUSED_PAD src0_sel:WORD_1 src1_sel:DWORD
	v_and_b32_sdwa v73, v4, v146 dst_sel:DWORD dst_unused:UNUSED_PAD src0_sel:WORD_1 src1_sel:DWORD
	v_and_b32_sdwa v74, v67, v146 dst_sel:DWORD dst_unused:UNUSED_PAD src0_sel:WORD_1 src1_sel:DWORD
	v_and_b32_sdwa v75, v66, v146 dst_sel:DWORD dst_unused:UNUSED_PAD src0_sel:WORD_1 src1_sel:DWORD
	v_and_b32_sdwa v76, v7, v146 dst_sel:DWORD dst_unused:UNUSED_PAD src0_sel:WORD_1 src1_sel:DWORD
	v_and_b32_sdwa v77, v6, v146 dst_sel:DWORD dst_unused:UNUSED_PAD src0_sel:WORD_1 src1_sel:DWORD
	v_and_b32_sdwa v78, v69, v146 dst_sel:DWORD dst_unused:UNUSED_PAD src0_sel:WORD_1 src1_sel:DWORD
	v_and_b32_sdwa v79, v68, v146 dst_sel:DWORD dst_unused:UNUSED_PAD src0_sel:WORD_1 src1_sel:DWORD
	v_and_b32_sdwa v80, v9, v146 dst_sel:DWORD dst_unused:UNUSED_PAD src0_sel:WORD_1 src1_sel:DWORD
	v_and_b32_sdwa v81, v8, v146 dst_sel:DWORD dst_unused:UNUSED_PAD src0_sel:WORD_1 src1_sel:DWORD
	v_and_b32_sdwa v82, v71, v146 dst_sel:DWORD dst_unused:UNUSED_PAD src0_sel:WORD_1 src1_sel:DWORD
	v_and_b32_sdwa v83, v70, v146 dst_sel:DWORD dst_unused:UNUSED_PAD src0_sel:WORD_1 src1_sel:DWORD
	v_and_b32_sdwa v84, v11, v146 dst_sel:DWORD dst_unused:UNUSED_PAD src0_sel:WORD_1 src1_sel:DWORD
	v_and_b32_sdwa v85, v10, v146 dst_sel:DWORD dst_unused:UNUSED_PAD src0_sel:WORD_1 src1_sel:DWORD
	v_add3_u32 v3, v65, v3, s30
	v_add3_u32 v12, v64, v12, s30
	v_add3_u32 v5, v5, v72, s30
	v_add3_u32 v4, v4, v73, s30
	v_add3_u32 v72, v67, v74, s30
	v_add3_u32 v73, v66, v75, s30
	v_add3_u32 v7, v7, v76, s30
	v_add3_u32 v6, v6, v77, s30
	v_add3_u32 v74, v69, v78, s30
	v_add3_u32 v75, v68, v79, s30
	v_add3_u32 v9, v9, v80, s30
	v_add3_u32 v8, v8, v81, s30
	v_add3_u32 v76, v71, v82, s30
	v_add3_u32 v78, v70, v83, s30
	v_add3_u32 v11, v11, v84, s30
	v_add3_u32 v10, v10, v85, s30
	v_and_b32_e32 v65, 0xffff0000, v3
	v_and_b32_e32 v64, 0xffff0000, v12
	v_and_b32_e32 v67, 0xffff0000, v5
	v_and_b32_e32 v66, 0xffff0000, v4
	v_and_b32_e32 v69, 0xffff0000, v72
	v_and_b32_e32 v68, 0xffff0000, v73
	v_and_b32_e32 v71, 0xffff0000, v7
	v_and_b32_e32 v70, 0xffff0000, v6
	v_and_b32_e32 v73, 0xffff0000, v74
	v_and_b32_e32 v72, 0xffff0000, v75
	v_and_b32_e32 v75, 0xffff0000, v9
	v_and_b32_e32 v74, 0xffff0000, v8
	v_and_b32_e32 v77, 0xffff0000, v76
	v_and_b32_e32 v76, 0xffff0000, v78
	v_and_b32_e32 v79, 0xffff0000, v11
	v_and_b32_e32 v78, 0xffff0000, v10
	global_load_dwordx4 v[4:7], v[28:29], off offset:1536
	global_load_dwordx4 v[8:11], v[28:29], off offset:1552
	global_load_dwordx4 v[80:83], v[14:15], off offset:3072
	global_load_dwordx4 v[84:87], v[14:15], off offset:3088
	global_load_dwordx4 v[88:91], v[14:15], off offset:3104
	global_load_dwordx4 v[92:95], v[14:15], off offset:3120
	s_waitcnt vmcnt(5)
	v_lshlrev_b32_e32 v96, 16, v4
	v_and_b32_e32 v97, 0xffff0000, v4
	v_lshlrev_b32_e32 v4, 16, v5
	v_and_b32_e32 v5, 0xffff0000, v5
	v_lshlrev_b32_e32 v98, 16, v6
	v_and_b32_e32 v99, 0xffff0000, v6
	v_lshlrev_b32_e32 v6, 16, v7
	v_and_b32_e32 v7, 0xffff0000, v7
	s_waitcnt vmcnt(4)
	v_lshlrev_b32_e32 v100, 16, v8
	v_and_b32_e32 v101, 0xffff0000, v8
	v_lshlrev_b32_e32 v8, 16, v9
	v_and_b32_e32 v9, 0xffff0000, v9
	v_lshlrev_b32_e32 v102, 16, v10
	v_and_b32_e32 v103, 0xffff0000, v10
	v_lshlrev_b32_e32 v10, 16, v11
	v_and_b32_e32 v11, 0xffff0000, v11
	v_pk_mul_f32 v[96:97], v[2:3], v[96:97] op_sel_hi:[0,1]
	v_pk_mul_f32 v[4:5], v[2:3], v[4:5] op_sel_hi:[0,1]
	v_pk_mul_f32 v[98:99], v[2:3], v[98:99] op_sel_hi:[0,1]
	v_pk_mul_f32 v[6:7], v[2:3], v[6:7] op_sel_hi:[0,1]
	v_pk_mul_f32 v[100:101], v[2:3], v[100:101] op_sel_hi:[0,1]
	v_pk_mul_f32 v[8:9], v[2:3], v[8:9] op_sel_hi:[0,1]
	v_pk_mul_f32 v[102:103], v[2:3], v[102:103] op_sel_hi:[0,1]
	v_pk_mul_f32 v[2:3], v[2:3], v[10:11] op_sel_hi:[0,1]
	s_waitcnt vmcnt(3)
	v_pk_mul_f32 v[10:11], v[80:81], v[96:97]
	v_pk_mul_f32 v[4:5], v[4:5], v[82:83]
	s_waitcnt vmcnt(2)
	v_pk_mul_f32 v[80:81], v[84:85], v[98:99]
	v_pk_mul_f32 v[6:7], v[6:7], v[86:87]
	s_waitcnt vmcnt(1)
; __device__ void phase_gather(const P& p, int vb, int nvb, char* smem) {
;     ...
;       uint32_t ks[8];
;       {
;         const int4 a0 = *(const int4*)(seli + (size_t)rr * 128 + j * 8), a1 = *(const int4*)(seli + (size_t)rr * 128 + j * 8 + 4);
;         const int ev[8] = {a0.x, a0.y, a0.z, a0.w, a1.x, a1.y, a1.z, a1.w};
; #pragma unroll
;         for (int r = 0; r < 8; r++) ks[r] = ((uint32_t)ev[r] << 7) | (uint32_t)(j * 8 + r);
;       }
; #pragma unroll
;       for (int k = 2; k <= 128; k <<= 1) {
; #pragma unroll
;         for (int d = k >> 1; d > 0; d >>= 1) {
;           if (d >= 8) {
; #pragma unroll
;             for (int r = 0; r < 8; r++) {
;               const uint32_t o = (uint32_t)__shfl_xor((int)ks[r], d >> 3);
;               const bool up = (((j * 8 + r) & k) == 0), lower = (((j * 8) & d) == 0);
;               const uint32_t mn = ks[r] < o ? ks[r] : o, mx = ks[r] < o ? o : ks[r];
;               ks[r] = (lower == up) ? mn : mx;
;             }
;           } else {
; #pragma unroll
;             for (int r = 0; r < 8; r++) {
;               if ((r & d) == 0) {
;                 const bool up = (((j * 8 + r) & k) == 0);
;                 const uint32_t x0 = ks[r], x1 = ks[r | d];
;                 const uint32_t mn = x0 < x1 ? x0 : x1, mx = x0 < x1 ? x1 : x0;
;                 ks[r] = up ? mn : mx; ks[r | d] = up ? mx : mn;
;               }
;             }
;           }
;         }
;       }
	v_pk_mul_f32 v[82:83], v[88:89], v[100:101]
	v_pk_mul_f32 v[8:9], v[8:9], v[90:91]
	s_waitcnt vmcnt(0)
	v_pk_mul_f32 v[84:85], v[92:93], v[102:103]
	v_pk_mul_f32 v[2:3], v[2:3], v[94:95]
	v_and_b32_sdwa v12, v11, v146 dst_sel:DWORD dst_unused:UNUSED_PAD src0_sel:WORD_1 src1_sel:DWORD
	v_and_b32_sdwa v86, v10, v146 dst_sel:DWORD dst_unused:UNUSED_PAD src0_sel:WORD_1 src1_sel:DWORD
	v_and_b32_sdwa v87, v5, v146 dst_sel:DWORD dst_unused:UNUSED_PAD src0_sel:WORD_1 src1_sel:DWORD
	v_and_b32_sdwa v88, v4, v146 dst_sel:DWORD dst_unused:UNUSED_PAD src0_sel:WORD_1 src1_sel:DWORD
	v_and_b32_sdwa v89, v81, v146 dst_sel:DWORD dst_unused:UNUSED_PAD src0_sel:WORD_1 src1_sel:DWORD
	v_and_b32_sdwa v90, v80, v146 dst_sel:DWORD dst_unused:UNUSED_PAD src0_sel:WORD_1 src1_sel:DWORD
	v_and_b32_sdwa v91, v7, v146 dst_sel:DWORD dst_unused:UNUSED_PAD src0_sel:WORD_1 src1_sel:DWORD
	v_and_b32_sdwa v92, v6, v146 dst_sel:DWORD dst_unused:UNUSED_PAD src0_sel:WORD_1 src1_sel:DWORD
	v_and_b32_sdwa v93, v83, v146 dst_sel:DWORD dst_unused:UNUSED_PAD src0_sel:WORD_1 src1_sel:DWORD
	v_and_b32_sdwa v94, v82, v146 dst_sel:DWORD dst_unused:UNUSED_PAD src0_sel:WORD_1 src1_sel:DWORD
	v_and_b32_sdwa v95, v9, v146 dst_sel:DWORD dst_unused:UNUSED_PAD src0_sel:WORD_1 src1_sel:DWORD
	v_and_b32_sdwa v96, v8, v146 dst_sel:DWORD dst_unused:UNUSED_PAD src0_sel:WORD_1 src1_sel:DWORD
	v_and_b32_sdwa v97, v85, v146 dst_sel:DWORD dst_unused:UNUSED_PAD src0_sel:WORD_1 src1_sel:DWORD
	v_and_b32_sdwa v98, v84, v146 dst_sel:DWORD dst_unused:UNUSED_PAD src0_sel:WORD_1 src1_sel:DWORD
	v_and_b32_sdwa v99, v3, v146 dst_sel:DWORD dst_unused:UNUSED_PAD src0_sel:WORD_1 src1_sel:DWORD
	v_and_b32_sdwa v100, v2, v146 dst_sel:DWORD dst_unused:UNUSED_PAD src0_sel:WORD_1 src1_sel:DWORD
	v_add3_u32 v11, v11, v12, s30
	v_add3_u32 v10, v10, v86, s30
	v_add3_u32 v5, v5, v87, s30
	v_add3_u32 v4, v4, v88, s30
	v_add3_u32 v12, v81, v89, s30
	v_add3_u32 v86, v80, v90, s30
	v_add3_u32 v7, v7, v91, s30
	v_add3_u32 v6, v6, v92, s30
	v_add3_u32 v88, v83, v93, s30
	v_add3_u32 v90, v82, v94, s30
	v_add3_u32 v9, v9, v95, s30
	v_add3_u32 v8, v8, v96, s30
	v_add3_u32 v92, v85, v97, s30
	v_add3_u32 v94, v84, v98, s30
	v_add3_u32 v3, v3, v99, s30
	v_add3_u32 v2, v2, v100, s30
	v_and_b32_e32 v81, 0xffff0000, v11
	v_and_b32_e32 v80, 0xffff0000, v10
	v_and_b32_e32 v83, 0xffff0000, v5
	v_and_b32_e32 v82, 0xffff0000, v4
	v_and_b32_e32 v85, 0xffff0000, v12
	v_and_b32_e32 v84, 0xffff0000, v86
	v_and_b32_e32 v87, 0xffff0000, v7
	v_and_b32_e32 v86, 0xffff0000, v6
	v_and_b32_e32 v89, 0xffff0000, v88
	v_and_b32_e32 v88, 0xffff0000, v90
	v_and_b32_e32 v91, 0xffff0000, v9
	v_and_b32_e32 v90, 0xffff0000, v8
	v_and_b32_e32 v93, 0xffff0000, v92
	v_and_b32_e32 v92, 0xffff0000, v94
	v_and_b32_e32 v95, 0xffff0000, v3
	v_and_b32_e32 v94, 0xffff0000, v2
	v_lshlrev_b64 v[0:1], 9, v[0:1]
	v_lshl_add_u64 v[10:11], v[16:17], 0, v[0:1]
	global_load_dwordx4 v[2:5], v[10:11], off
	global_load_dwordx4 v[6:9], v[10:11], off offset:16
	v_lshl_add_u64 v[0:1], s[22:23], 0, v[0:1]
	s_mov_b32 s26, -8
	s_waitcnt vmcnt(1)
	v_lshl_or_b32 v2, v2, 7, v132
	v_lshl_or_b32 v3, v3, 7, v135
	v_lshl_or_b32 v4, v4, 7, v136
	v_lshl_or_b32 v5, v5, 7, v137
	s_waitcnt vmcnt(0)
	v_lshl_or_b32 v6, v6, 7, v138
	v_lshl_or_b32 v7, v7, 7, v139
	v_lshl_or_b32 v8, v8, 7, v140
	v_lshl_or_b32 v9, v9, 7, v141
	v_min_u32_e32 v10, v2, v3
	v_max_u32_e32 v2, v2, v3
	v_min_u32_e32 v3, v4, v5
	v_max_u32_e32 v4, v4, v5
	v_min_u32_e32 v5, v6, v7
	v_max_u32_e32 v6, v6, v7
	v_min_u32_e32 v7, v8, v9
	v_max_u32_e32 v8, v8, v9
	v_min_u32_e32 v9, v10, v4
	v_max_u32_e32 v4, v10, v4
	v_min_u32_e32 v10, v2, v3
	v_max_u32_e32 v2, v2, v3
	v_min_u32_e32 v3, v5, v8
	v_max_u32_e32 v5, v5, v8
	v_min_u32_e32 v8, v6, v7
	v_max_u32_e32 v6, v6, v7
	v_min_u32_e32 v7, v9, v10
	v_max_u32_e32 v9, v9, v10
	v_min_u32_e32 v10, v4, v2
	v_max_u32_e32 v2, v4, v2
	v_min_u32_e32 v4, v5, v6
	v_max_u32_e32 v5, v5, v6
	v_min_u32_e32 v6, v3, v8
	v_max_u32_e32 v3, v3, v8
	v_min_u32_e32 v8, v7, v5
	v_max_u32_e32 v5, v7, v5
	v_min_u32_e32 v7, v9, v4
	v_max_u32_e32 v4, v9, v4
	v_min_u32_e32 v9, v10, v3
	v_max_u32_e32 v3, v10, v3
	v_min_u32_e32 v10, v2, v6
	v_max_u32_e32 v2, v2, v6
	v_cndmask_b32_e64 v6, v5, v8, s[4:5]
	v_cndmask_b32_e64 v5, v8, v5, s[4:5]
	v_cndmask_b32_e64 v8, v4, v7, s[4:5]
	v_cndmask_b32_e64 v4, v7, v4, s[4:5]
	v_cndmask_b32_e64 v7, v3, v9, s[4:5]
	v_cndmask_b32_e64 v3, v9, v3, s[4:5]
	v_cndmask_b32_e64 v9, v2, v10, s[4:5]
	v_cndmask_b32_e64 v2, v10, v2, s[4:5]
	v_min_u32_e32 v10, v6, v7
	v_max_u32_e32 v6, v6, v7
	v_min_u32_e32 v7, v8, v9
	v_max_u32_e32 v8, v8, v9
	v_min_u32_e32 v9, v5, v3
	v_max_u32_e32 v3, v5, v3
	v_min_u32_e32 v5, v4, v2
	v_max_u32_e32 v2, v4, v2
	v_cndmask_b32_e64 v4, v6, v10, s[4:5]
	v_cndmask_b32_e64 v6, v10, v6, s[4:5]
	v_cndmask_b32_e64 v10, v8, v7, s[4:5]
	v_cndmask_b32_e64 v7, v7, v8, s[4:5]
	v_cndmask_b32_e64 v8, v3, v9, s[4:5]
	v_cndmask_b32_e64 v3, v9, v3, s[4:5]
	v_cndmask_b32_e64 v9, v2, v5, s[4:5]
	v_cndmask_b32_e64 v2, v5, v2, s[4:5]
	v_min_u32_e32 v5, v4, v10
	v_max_u32_e32 v4, v4, v10
	v_min_u32_e32 v10, v6, v7
	v_max_u32_e32 v6, v6, v7
	v_min_u32_e32 v7, v8, v9
	v_max_u32_e32 v8, v8, v9
	v_min_u32_e32 v9, v3, v2
	v_max_u32_e32 v2, v3, v2
	v_cndmask_b32_e64 v3, v4, v5, s[4:5]
	v_cndmask_b32_e64 v4, v5, v4, s[4:5]
	v_cndmask_b32_e64 v5, v6, v10, s[4:5]
	v_cndmask_b32_e64 v6, v10, v6, s[4:5]
	v_cndmask_b32_e64 v10, v8, v7, s[4:5]
	v_cndmask_b32_e64 v7, v7, v8, s[4:5]
	v_cndmask_b32_e64 v8, v2, v9, s[4:5]
	v_cndmask_b32_e64 v2, v9, v2, s[4:5]
	ds_bpermute_b32 v9, v128, v3
	ds_bpermute_b32 v11, v128, v4
	ds_bpermute_b32 v12, v128, v5
	ds_bpermute_b32 v96, v128, v6
	ds_bpermute_b32 v97, v128, v10
	s_waitcnt lgkmcnt(4)
; __device__ void phase_gather(const P& p, int vb, int nvb, char* smem) {
;     ...
; #pragma unroll
;       for (int k = 2; k <= 128; k <<= 1) {
; #pragma unroll
;         for (int d = k >> 1; d > 0; d >>= 1) {
;           if (d >= 8) {
; #pragma unroll
;             for (int r = 0; r < 8; r++) {
;               const uint32_t o = (uint32_t)__shfl_xor((int)ks[r], d >> 3);
;               const bool up = (((j * 8 + r) & k) == 0), lower = (((j * 8) & d) == 0);
;               const uint32_t mn = ks[r] < o ? ks[r] : o, mx = ks[r] < o ? o : ks[r];
;               ks[r] = (lower == up) ? mn : mx;
;             }
;           } else {
; #pragma unroll
;             for (int r = 0; r < 8; r++) {
;               if ((r & d) == 0) {
;                 const bool up = (((j * 8 + r) & k) == 0);
;                 const uint32_t x0 = ks[r], x1 = ks[r | d];
;                 const uint32_t mn = x0 < x1 ? x0 : x1, mx = x0 < x1 ? x1 : x0;
;                 ks[r] = up ? mn : mx; ks[r | d] = up ? mx : mn;
;               }
;             }
;           }
;         }
;       }
	v_min_u32_e32 v98, v3, v9
	v_max_u32_e32 v3, v3, v9
	s_waitcnt lgkmcnt(3)
	v_min_u32_e32 v9, v4, v11
	v_max_u32_e32 v4, v4, v11
	v_cndmask_b32_e64 v4, v4, v9, s[6:7]
	ds_bpermute_b32 v9, v128, v7
	s_waitcnt lgkmcnt(3)
	v_min_u32_e32 v11, v5, v12
	v_max_u32_e32 v5, v5, v12
	s_waitcnt lgkmcnt(2)
	v_min_u32_e32 v12, v6, v96
	v_cndmask_b32_e64 v5, v5, v11, s[6:7]
	v_max_u32_e32 v6, v6, v96
	s_waitcnt lgkmcnt(1)
	v_min_u32_e32 v11, v10, v97
	v_max_u32_e32 v10, v10, v97
	v_cndmask_b32_e64 v6, v6, v12, s[6:7]
	v_cndmask_b32_e64 v10, v10, v11, s[6:7]
	ds_bpermute_b32 v11, v128, v8
	s_waitcnt lgkmcnt(1)
	v_min_u32_e32 v12, v7, v9
	v_max_u32_e32 v7, v7, v9
	ds_bpermute_b32 v9, v128, v2
	v_cndmask_b32_e64 v3, v3, v98, s[6:7]
	v_cndmask_b32_e64 v7, v7, v12, s[6:7]
	s_waitcnt lgkmcnt(1)
	v_min_u32_e32 v12, v8, v11
	v_max_u32_e32 v8, v8, v11
	s_waitcnt lgkmcnt(0)
	v_min_u32_e32 v11, v2, v9
	v_max_u32_e32 v2, v2, v9
	v_min_u32_e32 v9, v3, v10
	v_max_u32_e32 v3, v3, v10
	v_cndmask_b32_e64 v8, v8, v12, s[6:7]
	v_cndmask_b32_e64 v10, v3, v9, s[2:3]
	v_cndmask_b32_e64 v3, v9, v3, s[2:3]
	v_min_u32_e32 v9, v4, v7
	v_max_u32_e32 v4, v4, v7
	v_cndmask_b32_e64 v2, v2, v11, s[6:7]
	v_cndmask_b32_e64 v7, v4, v9, s[2:3]
	v_cndmask_b32_e64 v4, v9, v4, s[2:3]
	v_min_u32_e32 v9, v5, v8
	v_max_u32_e32 v5, v5, v8
	v_cndmask_b32_e64 v8, v5, v9, s[2:3]
	v_cndmask_b32_e64 v5, v9, v5, s[2:3]
	v_min_u32_e32 v9, v6, v2
	v_max_u32_e32 v2, v6, v2
	v_cndmask_b32_e64 v6, v2, v9, s[2:3]
	v_cndmask_b32_e64 v2, v9, v2, s[2:3]
	v_min_u32_e32 v9, v10, v8
	v_max_u32_e32 v8, v10, v8
	v_cndmask_b32_e64 v10, v8, v9, s[2:3]
	v_cndmask_b32_e64 v8, v9, v8, s[2:3]
	v_min_u32_e32 v9, v7, v6
	v_max_u32_e32 v6, v7, v6
	v_cndmask_b32_e64 v7, v6, v9, s[2:3]
	v_cndmask_b32_e64 v6, v9, v6, s[2:3]
	v_min_u32_e32 v9, v3, v5
	v_max_u32_e32 v3, v3, v5
	v_cndmask_b32_e64 v5, v3, v9, s[2:3]
	v_cndmask_b32_e64 v3, v9, v3, s[2:3]
	v_min_u32_e32 v9, v4, v2
	v_max_u32_e32 v2, v4, v2
	v_cndmask_b32_e64 v4, v2, v9, s[2:3]
	v_cndmask_b32_e64 v2, v9, v2, s[2:3]
	v_min_u32_e32 v9, v10, v7
	v_max_u32_e32 v7, v10, v7
	v_cndmask_b32_e64 v10, v7, v9, s[2:3]
	v_cndmask_b32_e64 v7, v9, v7, s[2:3]
	v_min_u32_e32 v9, v8, v6
	v_max_u32_e32 v6, v8, v6
	v_cndmask_b32_e64 v8, v6, v9, s[2:3]
	v_cndmask_b32_e64 v6, v9, v6, s[2:3]
	v_min_u32_e32 v9, v5, v4
	v_max_u32_e32 v4, v5, v4
	v_cndmask_b32_e64 v5, v4, v9, s[2:3]
	v_cndmask_b32_e64 v4, v9, v4, s[2:3]
	v_min_u32_e32 v9, v3, v2
	ds_bpermute_b32 v11, v129, v10
	v_max_u32_e32 v2, v3, v2
	v_cndmask_b32_e64 v3, v2, v9, s[2:3]
	v_cndmask_b32_e64 v2, v9, v2, s[2:3]
	ds_bpermute_b32 v9, v129, v7
	s_waitcnt lgkmcnt(1)
	v_min_u32_e32 v12, v10, v11
	v_max_u32_e32 v10, v10, v11
	ds_bpermute_b32 v11, v129, v8
	v_cndmask_b32_e64 v10, v10, v12, s[8:9]
	s_waitcnt lgkmcnt(1)
	v_min_u32_e32 v12, v7, v9
	v_max_u32_e32 v7, v7, v9
	ds_bpermute_b32 v9, v129, v6
	v_cndmask_b32_e64 v7, v7, v12, s[8:9]
	s_waitcnt lgkmcnt(1)
	v_min_u32_e32 v12, v8, v11
	v_max_u32_e32 v8, v8, v11
	ds_bpermute_b32 v11, v129, v5
	v_cndmask_b32_e64 v8, v8, v12, s[8:9]
	s_waitcnt lgkmcnt(1)
	v_min_u32_e32 v12, v6, v9
	v_max_u32_e32 v6, v6, v9
	ds_bpermute_b32 v9, v129, v4
	v_cndmask_b32_e64 v6, v6, v12, s[8:9]
	s_waitcnt lgkmcnt(1)
	v_min_u32_e32 v12, v5, v11
	v_max_u32_e32 v5, v5, v11
	ds_bpermute_b32 v11, v129, v3
	v_cndmask_b32_e64 v5, v5, v12, s[8:9]
	s_waitcnt lgkmcnt(1)
	v_min_u32_e32 v12, v4, v9
	v_max_u32_e32 v4, v4, v9
	ds_bpermute_b32 v9, v129, v2
	v_cndmask_b32_e64 v4, v4, v12, s[8:9]
	s_waitcnt lgkmcnt(1)
	v_min_u32_e32 v12, v3, v11
	v_max_u32_e32 v3, v3, v11
	ds_bpermute_b32 v11, v128, v10
	v_cndmask_b32_e64 v3, v3, v12, s[8:9]
	s_waitcnt lgkmcnt(1)
	v_min_u32_e32 v12, v2, v9
	v_max_u32_e32 v2, v2, v9
	ds_bpermute_b32 v9, v128, v7
	v_cndmask_b32_e64 v2, v2, v12, s[8:9]
	s_waitcnt lgkmcnt(1)
	v_min_u32_e32 v12, v10, v11
	v_max_u32_e32 v10, v10, v11
	ds_bpermute_b32 v11, v128, v8
	v_cndmask_b32_e64 v10, v10, v12, s[10:11]
	s_waitcnt lgkmcnt(1)
	v_min_u32_e32 v12, v7, v9
	v_max_u32_e32 v7, v7, v9
	ds_bpermute_b32 v9, v128, v6
	v_cndmask_b32_e64 v7, v7, v12, s[10:11]
	s_waitcnt lgkmcnt(1)
	v_min_u32_e32 v12, v8, v11
	v_max_u32_e32 v8, v8, v11
	ds_bpermute_b32 v11, v128, v5
	v_cndmask_b32_e64 v8, v8, v12, s[10:11]
	s_waitcnt lgkmcnt(1)
	v_min_u32_e32 v12, v6, v9
	v_max_u32_e32 v6, v6, v9
	ds_bpermute_b32 v9, v128, v4
	v_cndmask_b32_e64 v6, v6, v12, s[10:11]
	s_waitcnt lgkmcnt(1)
	v_min_u32_e32 v12, v5, v11
	v_max_u32_e32 v5, v5, v11
	v_cndmask_b32_e64 v5, v5, v12, s[10:11]
	ds_bpermute_b32 v11, v128, v3
	s_waitcnt lgkmcnt(1)
	v_min_u32_e32 v12, v4, v9
	v_max_u32_e32 v4, v4, v9
	ds_bpermute_b32 v9, v128, v2
	v_cndmask_b32_e64 v4, v4, v12, s[10:11]
	s_waitcnt lgkmcnt(1)
	v_min_u32_e32 v12, v3, v11
	v_max_u32_e32 v3, v3, v11
	v_cndmask_b32_e64 v3, v3, v12, s[10:11]
	s_waitcnt lgkmcnt(0)
; __device__ void phase_gather(const P& p, int vb, int nvb, char* smem) {
;     ...
; #pragma unroll
;       for (int k = 2; k <= 128; k <<= 1) {
; #pragma unroll
;         for (int d = k >> 1; d > 0; d >>= 1) {
;           if (d >= 8) {
; #pragma unroll
;             for (int r = 0; r < 8; r++) {
;               const uint32_t o = (uint32_t)__shfl_xor((int)ks[r], d >> 3);
;               const bool up = (((j * 8 + r) & k) == 0), lower = (((j * 8) & d) == 0);
;               const uint32_t mn = ks[r] < o ? ks[r] : o, mx = ks[r] < o ? o : ks[r];
;               ks[r] = (lower == up) ? mn : mx;
;             }
;           } else {
; #pragma unroll
;             for (int r = 0; r < 8; r++) {
;               if ((r & d) == 0) {
;                 const bool up = (((j * 8 + r) & k) == 0);
;                 const uint32_t x0 = ks[r], x1 = ks[r | d];
;                 const uint32_t mn = x0 < x1 ? x0 : x1, mx = x0 < x1 ? x1 : x0;
;                 ks[r] = up ? mn : mx; ks[r | d] = up ? mx : mn;
;               }
;             }
;           }
;         }
;       }
	v_min_u32_e32 v11, v2, v9
	v_max_u32_e32 v2, v2, v9
	v_min_u32_e32 v9, v10, v5
	v_max_u32_e32 v5, v10, v5
	v_cndmask_b32_e64 v10, v5, v9, s[0:1]
	v_cndmask_b32_e64 v5, v9, v5, s[0:1]
	v_min_u32_e32 v9, v7, v4
	v_max_u32_e32 v4, v7, v4
	v_cndmask_b32_e64 v2, v2, v11, s[10:11]
	v_cndmask_b32_e64 v7, v4, v9, s[0:1]
	v_cndmask_b32_e64 v4, v9, v4, s[0:1]
	v_min_u32_e32 v9, v8, v3
	v_max_u32_e32 v3, v8, v3
	v_cndmask_b32_e64 v8, v3, v9, s[0:1]
	v_cndmask_b32_e64 v3, v9, v3, s[0:1]
	v_min_u32_e32 v9, v6, v2
	v_max_u32_e32 v2, v6, v2
	v_cndmask_b32_e64 v6, v2, v9, s[0:1]
	v_cndmask_b32_e64 v2, v9, v2, s[0:1]
	v_min_u32_e32 v9, v10, v8
	v_max_u32_e32 v8, v10, v8
	v_cndmask_b32_e64 v10, v8, v9, s[0:1]
	v_cndmask_b32_e64 v8, v9, v8, s[0:1]
	v_min_u32_e32 v9, v7, v6
	v_max_u32_e32 v6, v7, v6
	v_cndmask_b32_e64 v7, v6, v9, s[0:1]
	v_cndmask_b32_e64 v6, v9, v6, s[0:1]
	v_min_u32_e32 v9, v5, v3
	v_max_u32_e32 v3, v5, v3
	v_cndmask_b32_e64 v5, v3, v9, s[0:1]
	v_cndmask_b32_e64 v3, v9, v3, s[0:1]
	v_min_u32_e32 v9, v4, v2
	v_max_u32_e32 v2, v4, v2
	v_cndmask_b32_e64 v4, v2, v9, s[0:1]
	v_cndmask_b32_e64 v2, v9, v2, s[0:1]
	v_min_u32_e32 v9, v10, v7
	v_max_u32_e32 v7, v10, v7
	v_cndmask_b32_e64 v10, v7, v9, s[0:1]
	v_cndmask_b32_e64 v7, v9, v7, s[0:1]
	v_min_u32_e32 v9, v8, v6
	v_max_u32_e32 v6, v8, v6
	v_cndmask_b32_e64 v8, v6, v9, s[0:1]
	v_cndmask_b32_e64 v6, v9, v6, s[0:1]
	v_min_u32_e32 v9, v5, v4
	v_max_u32_e32 v4, v5, v4
	v_cndmask_b32_e64 v5, v4, v9, s[0:1]
	v_cndmask_b32_e64 v4, v9, v4, s[0:1]
	v_min_u32_e32 v9, v3, v2
	ds_bpermute_b32 v11, v130, v10
	v_max_u32_e32 v2, v3, v2
	v_cndmask_b32_e64 v3, v2, v9, s[0:1]
	v_cndmask_b32_e64 v2, v9, v2, s[0:1]
	ds_bpermute_b32 v9, v130, v7
	s_waitcnt lgkmcnt(1)
	v_min_u32_e32 v12, v10, v11
	v_max_u32_e32 v10, v10, v11
	ds_bpermute_b32 v11, v130, v8
	v_cndmask_b32_e64 v10, v10, v12, s[12:13]
	s_waitcnt lgkmcnt(1)
	v_min_u32_e32 v12, v7, v9
	v_max_u32_e32 v7, v7, v9
	ds_bpermute_b32 v9, v130, v6
	v_cndmask_b32_e64 v7, v7, v12, s[12:13]
	s_waitcnt lgkmcnt(1)
	v_min_u32_e32 v12, v8, v11
	v_max_u32_e32 v8, v8, v11
	ds_bpermute_b32 v11, v130, v5
	v_cndmask_b32_e64 v8, v8, v12, s[12:13]
	s_waitcnt lgkmcnt(1)
	v_min_u32_e32 v12, v6, v9
	v_max_u32_e32 v6, v6, v9
	ds_bpermute_b32 v9, v130, v4
	v_cndmask_b32_e64 v6, v6, v12, s[12:13]
	s_waitcnt lgkmcnt(1)
	v_min_u32_e32 v12, v5, v11
	v_max_u32_e32 v5, v5, v11
	ds_bpermute_b32 v11, v130, v3
	v_cndmask_b32_e64 v5, v5, v12, s[12:13]
	s_waitcnt lgkmcnt(1)
	v_min_u32_e32 v12, v4, v9
	v_max_u32_e32 v4, v4, v9
	ds_bpermute_b32 v9, v130, v2
	v_cndmask_b32_e64 v4, v4, v12, s[12:13]
	s_waitcnt lgkmcnt(1)
	v_min_u32_e32 v12, v3, v11
	v_max_u32_e32 v3, v3, v11
	ds_bpermute_b32 v11, v129, v10
	v_cndmask_b32_e64 v3, v3, v12, s[12:13]
	s_waitcnt lgkmcnt(1)
	v_min_u32_e32 v12, v2, v9
	v_max_u32_e32 v2, v2, v9
	ds_bpermute_b32 v9, v129, v7
	v_cndmask_b32_e64 v2, v2, v12, s[12:13]
	s_waitcnt lgkmcnt(1)
	v_min_u32_e32 v12, v10, v11
	v_max_u32_e32 v10, v10, v11
	ds_bpermute_b32 v11, v129, v8
	v_cndmask_b32_e64 v10, v10, v12, s[14:15]
	s_waitcnt lgkmcnt(1)
	v_min_u32_e32 v12, v7, v9
	v_max_u32_e32 v7, v7, v9
	ds_bpermute_b32 v9, v129, v6
	v_cndmask_b32_e64 v7, v7, v12, s[14:15]
	s_waitcnt lgkmcnt(1)
	v_min_u32_e32 v12, v8, v11
	v_max_u32_e32 v8, v8, v11
	ds_bpermute_b32 v11, v129, v5
	v_cndmask_b32_e64 v8, v8, v12, s[14:15]
	s_waitcnt lgkmcnt(1)
	v_min_u32_e32 v12, v6, v9
	v_max_u32_e32 v6, v6, v9
	ds_bpermute_b32 v9, v129, v4
	v_cndmask_b32_e64 v6, v6, v12, s[14:15]
	s_waitcnt lgkmcnt(1)
	v_min_u32_e32 v12, v5, v11
	v_max_u32_e32 v5, v5, v11
	ds_bpermute_b32 v11, v129, v3
	v_cndmask_b32_e64 v5, v5, v12, s[14:15]
	s_waitcnt lgkmcnt(1)
	v_min_u32_e32 v12, v4, v9
	v_max_u32_e32 v4, v4, v9
	ds_bpermute_b32 v9, v129, v2
	v_cndmask_b32_e64 v4, v4, v12, s[14:15]
	s_waitcnt lgkmcnt(1)
	v_min_u32_e32 v12, v3, v11
	v_max_u32_e32 v3, v3, v11
	ds_bpermute_b32 v11, v128, v10
	v_cndmask_b32_e64 v3, v3, v12, s[14:15]
	s_waitcnt lgkmcnt(1)
	v_min_u32_e32 v12, v2, v9
	v_max_u32_e32 v2, v2, v9
	ds_bpermute_b32 v9, v128, v7
	v_cndmask_b32_e64 v2, v2, v12, s[14:15]
	s_waitcnt lgkmcnt(1)
	v_min_u32_e32 v12, v10, v11
	v_max_u32_e32 v10, v10, v11
	ds_bpermute_b32 v11, v128, v8
	v_cndmask_b32_e64 v10, v10, v12, s[16:17]
	s_waitcnt lgkmcnt(1)
	v_min_u32_e32 v12, v7, v9
	v_max_u32_e32 v7, v7, v9
	ds_bpermute_b32 v9, v128, v6
	v_cndmask_b32_e64 v7, v7, v12, s[16:17]
	s_waitcnt lgkmcnt(1)
	v_min_u32_e32 v12, v8, v11
	v_max_u32_e32 v8, v8, v11
	ds_bpermute_b32 v11, v128, v5
	v_cndmask_b32_e64 v8, v8, v12, s[16:17]
	s_waitcnt lgkmcnt(1)
	v_min_u32_e32 v12, v6, v9
	v_max_u32_e32 v6, v6, v9
	ds_bpermute_b32 v9, v128, v4
	v_cndmask_b32_e64 v6, v6, v12, s[16:17]
	s_waitcnt lgkmcnt(1)
	v_min_u32_e32 v12, v5, v11
	v_max_u32_e32 v5, v5, v11
	v_cndmask_b32_e64 v5, v5, v12, s[16:17]
	ds_bpermute_b32 v11, v128, v3
	s_waitcnt lgkmcnt(1)
	v_min_u32_e32 v12, v4, v9
	v_max_u32_e32 v4, v4, v9
	ds_bpermute_b32 v9, v128, v2
	v_cndmask_b32_e64 v4, v4, v12, s[16:17]
	s_waitcnt lgkmcnt(1)
	v_min_u32_e32 v12, v3, v11
	v_max_u32_e32 v3, v3, v11
	v_cndmask_b32_e64 v3, v3, v12, s[16:17]
	s_waitcnt lgkmcnt(0)
; __device__ void phase_gather(const P& p, int vb, int nvb, char* smem) {
;     ...
; #pragma unroll
;       for (int k = 2; k <= 128; k <<= 1) {
; #pragma unroll
;         for (int d = k >> 1; d > 0; d >>= 1) {
;           if (d >= 8) {
; #pragma unroll
;             for (int r = 0; r < 8; r++) {
;               const uint32_t o = (uint32_t)__shfl_xor((int)ks[r], d >> 3);
;               const bool up = (((j * 8 + r) & k) == 0), lower = (((j * 8) & d) == 0);
;               const uint32_t mn = ks[r] < o ? ks[r] : o, mx = ks[r] < o ? o : ks[r];
;               ks[r] = (lower == up) ? mn : mx;
;             }
;           } else {
; #pragma unroll
;             for (int r = 0; r < 8; r++) {
;               if ((r & d) == 0) {
;                 const bool up = (((j * 8 + r) & k) == 0);
;                 const uint32_t x0 = ks[r], x1 = ks[r | d];
;                 const uint32_t mn = x0 < x1 ? x0 : x1, mx = x0 < x1 ? x1 : x0;
;                 ks[r] = up ? mn : mx; ks[r | d] = up ? mx : mn;
;               }
;             }
;           }
;         }
;       }
	v_min_u32_e32 v11, v2, v9
	v_max_u32_e32 v2, v2, v9
	v_min_u32_e32 v9, v10, v5
	v_max_u32_e32 v5, v10, v5
	v_cndmask_b32_e64 v10, v5, v9, s[18:19]
	v_cndmask_b32_e64 v5, v9, v5, s[18:19]
	v_min_u32_e32 v9, v7, v4
	v_max_u32_e32 v4, v7, v4
	v_cndmask_b32_e64 v2, v2, v11, s[16:17]
	v_cndmask_b32_e64 v7, v4, v9, s[18:19]
	v_cndmask_b32_e64 v4, v9, v4, s[18:19]
	v_min_u32_e32 v9, v8, v3
	v_max_u32_e32 v3, v8, v3
	v_cndmask_b32_e64 v8, v3, v9, s[18:19]
	v_cndmask_b32_e64 v3, v9, v3, s[18:19]
	v_min_u32_e32 v9, v6, v2
	v_max_u32_e32 v2, v6, v2
	v_cndmask_b32_e64 v6, v2, v9, s[18:19]
	v_cndmask_b32_e64 v2, v9, v2, s[18:19]
	v_min_u32_e32 v9, v10, v8
	v_max_u32_e32 v8, v10, v8
	v_cndmask_b32_e64 v10, v8, v9, s[18:19]
	v_cndmask_b32_e64 v8, v9, v8, s[18:19]
	v_min_u32_e32 v9, v7, v6
	v_max_u32_e32 v6, v7, v6
	v_cndmask_b32_e64 v7, v6, v9, s[18:19]
	v_cndmask_b32_e64 v6, v9, v6, s[18:19]
	v_min_u32_e32 v9, v5, v3
	v_max_u32_e32 v3, v5, v3
	v_cndmask_b32_e64 v5, v3, v9, s[18:19]
	v_cndmask_b32_e64 v3, v9, v3, s[18:19]
	v_min_u32_e32 v9, v4, v2
	v_max_u32_e32 v2, v4, v2
	v_cndmask_b32_e64 v4, v2, v9, s[18:19]
	v_cndmask_b32_e64 v2, v9, v2, s[18:19]
	v_min_u32_e32 v9, v10, v7
	v_max_u32_e32 v7, v10, v7
	v_cndmask_b32_e64 v10, v7, v9, s[18:19]
	v_cndmask_b32_e64 v7, v9, v7, s[18:19]
	v_min_u32_e32 v9, v8, v6
	v_max_u32_e32 v6, v8, v6
	v_cndmask_b32_e64 v8, v6, v9, s[18:19]
	v_cndmask_b32_e64 v6, v9, v6, s[18:19]
	v_min_u32_e32 v9, v5, v4
	v_max_u32_e32 v4, v5, v4
	v_cndmask_b32_e64 v5, v4, v9, s[18:19]
	v_cndmask_b32_e64 v4, v9, v4, s[18:19]
	v_min_u32_e32 v9, v3, v2
	ds_bpermute_b32 v11, v131, v10
	v_max_u32_e32 v2, v3, v2
	v_cndmask_b32_e64 v3, v2, v9, s[18:19]
	v_cndmask_b32_e64 v2, v9, v2, s[18:19]
	ds_bpermute_b32 v9, v131, v7
	s_waitcnt lgkmcnt(1)
	v_min_u32_e32 v12, v10, v11
	v_max_u32_e32 v10, v10, v11
	ds_bpermute_b32 v11, v131, v8
	v_cndmask_b32_e64 v10, v10, v12, s[18:19]
	s_waitcnt lgkmcnt(1)
	v_min_u32_e32 v12, v7, v9
	v_max_u32_e32 v7, v7, v9
	ds_bpermute_b32 v9, v131, v6
	v_cndmask_b32_e64 v7, v7, v12, s[18:19]
	s_waitcnt lgkmcnt(1)
	v_min_u32_e32 v12, v8, v11
	v_max_u32_e32 v8, v8, v11
	ds_bpermute_b32 v11, v131, v5
	v_cndmask_b32_e64 v8, v8, v12, s[18:19]
	s_waitcnt lgkmcnt(1)
	v_min_u32_e32 v12, v6, v9
	v_max_u32_e32 v6, v6, v9
	ds_bpermute_b32 v9, v131, v4
	v_cndmask_b32_e64 v6, v6, v12, s[18:19]
	s_waitcnt lgkmcnt(1)
	v_min_u32_e32 v12, v5, v11
	v_max_u32_e32 v5, v5, v11
	ds_bpermute_b32 v11, v131, v3
	v_cndmask_b32_e64 v5, v5, v12, s[18:19]
	s_waitcnt lgkmcnt(1)
	v_min_u32_e32 v12, v4, v9
	v_max_u32_e32 v4, v4, v9
	ds_bpermute_b32 v9, v131, v2
	v_cndmask_b32_e64 v4, v4, v12, s[18:19]
	s_waitcnt lgkmcnt(1)
	v_min_u32_e32 v12, v3, v11
	v_max_u32_e32 v3, v3, v11
	ds_bpermute_b32 v11, v130, v10
	v_cndmask_b32_e64 v3, v3, v12, s[18:19]
	s_waitcnt lgkmcnt(1)
	v_min_u32_e32 v12, v2, v9
	v_max_u32_e32 v2, v2, v9
	ds_bpermute_b32 v9, v130, v7
	v_cndmask_b32_e64 v2, v2, v12, s[18:19]
	s_waitcnt lgkmcnt(1)
	v_min_u32_e32 v12, v10, v11
	v_max_u32_e32 v10, v10, v11
	ds_bpermute_b32 v11, v130, v8
	v_cndmask_b32_e64 v10, v10, v12, s[0:1]
	s_waitcnt lgkmcnt(1)
	v_min_u32_e32 v12, v7, v9
	v_max_u32_e32 v7, v7, v9
	ds_bpermute_b32 v9, v130, v6
	v_cndmask_b32_e64 v7, v7, v12, s[0:1]
	s_waitcnt lgkmcnt(1)
	v_min_u32_e32 v12, v8, v11
	v_max_u32_e32 v8, v8, v11
	ds_bpermute_b32 v11, v130, v5
	v_cndmask_b32_e64 v8, v8, v12, s[0:1]
	s_waitcnt lgkmcnt(1)
	v_min_u32_e32 v12, v6, v9
	v_max_u32_e32 v6, v6, v9
	ds_bpermute_b32 v9, v130, v4
	v_cndmask_b32_e64 v6, v6, v12, s[0:1]
	s_waitcnt lgkmcnt(1)
	v_min_u32_e32 v12, v5, v11
	v_max_u32_e32 v5, v5, v11
	ds_bpermute_b32 v11, v130, v3
	v_cndmask_b32_e64 v5, v5, v12, s[0:1]
	s_waitcnt lgkmcnt(1)
	v_min_u32_e32 v12, v4, v9
	v_max_u32_e32 v4, v4, v9
	ds_bpermute_b32 v9, v130, v2
	v_cndmask_b32_e64 v4, v4, v12, s[0:1]
	s_waitcnt lgkmcnt(1)
	v_min_u32_e32 v12, v3, v11
	v_max_u32_e32 v3, v3, v11
	ds_bpermute_b32 v11, v129, v10
	v_cndmask_b32_e64 v3, v3, v12, s[0:1]
	s_waitcnt lgkmcnt(1)
	v_min_u32_e32 v12, v2, v9
	v_max_u32_e32 v2, v2, v9
	ds_bpermute_b32 v9, v129, v7
	v_cndmask_b32_e64 v2, v2, v12, s[0:1]
	s_waitcnt lgkmcnt(1)
	v_min_u32_e32 v12, v10, v11
	v_max_u32_e32 v10, v10, v11
	ds_bpermute_b32 v11, v129, v8
	v_cndmask_b32_e64 v10, v10, v12, s[2:3]
	s_waitcnt lgkmcnt(1)
	v_min_u32_e32 v12, v7, v9
	v_max_u32_e32 v7, v7, v9
	ds_bpermute_b32 v9, v129, v6
	v_cndmask_b32_e64 v7, v7, v12, s[2:3]
	s_waitcnt lgkmcnt(1)
	v_min_u32_e32 v12, v8, v11
	v_max_u32_e32 v8, v8, v11
	ds_bpermute_b32 v11, v129, v5
	v_cndmask_b32_e64 v8, v8, v12, s[2:3]
	s_waitcnt lgkmcnt(1)
	v_min_u32_e32 v12, v6, v9
	v_max_u32_e32 v6, v6, v9
	ds_bpermute_b32 v9, v129, v4
	v_cndmask_b32_e64 v6, v6, v12, s[2:3]
	s_waitcnt lgkmcnt(1)
	v_min_u32_e32 v12, v5, v11
	v_max_u32_e32 v5, v5, v11
	ds_bpermute_b32 v11, v129, v3
	v_cndmask_b32_e64 v5, v5, v12, s[2:3]
	s_waitcnt lgkmcnt(1)
	v_min_u32_e32 v12, v4, v9
	v_max_u32_e32 v4, v4, v9
	ds_bpermute_b32 v9, v129, v2
	v_cndmask_b32_e64 v4, v4, v12, s[2:3]
	s_waitcnt lgkmcnt(1)
; __device__ void phase_gather(const P& p, int vb, int nvb, char* smem) {
;     ...
;       *(uint4*)(kl + g * 128 + j * 8) = make_uint4(ks[0], ks[1], ks[2], ks[3]);
;       *(uint4*)(kl + g * 128 + j * 8 + 4) = make_uint4(ks[4], ks[5], ks[6], ks[7]);
;     }
;     asm volatile("s_waitcnt lgkmcnt(0)" ::: "memory");
;     const float* sgp = selg + (size_t)rr * 128;
;     const uint32_t* mykl = kl + g * 128;
;     float* mywl = wl + g * 128;
;     float gpre[8];
; #pragma unroll
;     for (int m = 0; m < 8; m++) gpre[m] = sgp[mykl[j + 16 * m] & 127u];
	v_min_u32_e32 v12, v3, v11
	v_max_u32_e32 v3, v3, v11
	ds_bpermute_b32 v11, v128, v10
	v_cndmask_b32_e64 v3, v3, v12, s[2:3]
	s_waitcnt lgkmcnt(1)
	v_min_u32_e32 v12, v2, v9
	v_max_u32_e32 v2, v2, v9
	ds_bpermute_b32 v9, v128, v7
	v_cndmask_b32_e64 v2, v2, v12, s[2:3]
	s_waitcnt lgkmcnt(1)
	v_min_u32_e32 v12, v10, v11
	v_max_u32_e32 v10, v10, v11
	ds_bpermute_b32 v11, v128, v8
	v_cndmask_b32_e64 v10, v10, v12, s[4:5]
	s_waitcnt lgkmcnt(1)
	v_min_u32_e32 v12, v7, v9
	v_max_u32_e32 v7, v7, v9
	ds_bpermute_b32 v9, v128, v6
	v_cndmask_b32_e64 v7, v7, v12, s[4:5]
	s_waitcnt lgkmcnt(1)
	v_min_u32_e32 v12, v8, v11
	v_max_u32_e32 v8, v8, v11
	ds_bpermute_b32 v11, v128, v5
	v_cndmask_b32_e64 v8, v8, v12, s[4:5]
	s_waitcnt lgkmcnt(1)
	v_min_u32_e32 v12, v6, v9
	v_max_u32_e32 v6, v6, v9
	ds_bpermute_b32 v9, v128, v4
	v_cndmask_b32_e64 v6, v6, v12, s[4:5]
	s_waitcnt lgkmcnt(1)
	v_min_u32_e32 v12, v5, v11
	v_max_u32_e32 v5, v5, v11
	v_cndmask_b32_e64 v5, v5, v12, s[4:5]
	ds_bpermute_b32 v11, v128, v3
	s_waitcnt lgkmcnt(1)
	v_min_u32_e32 v12, v4, v9
	v_max_u32_e32 v4, v4, v9
	ds_bpermute_b32 v9, v128, v2
	v_cndmask_b32_e64 v4, v4, v12, s[4:5]
	s_waitcnt lgkmcnt(1)
	v_min_u32_e32 v12, v3, v11
	v_max_u32_e32 v3, v3, v11
	v_cndmask_b32_e64 v3, v3, v12, s[4:5]
	s_waitcnt lgkmcnt(0)
	v_min_u32_e32 v11, v2, v9
	v_max_u32_e32 v2, v2, v9
	v_cndmask_b32_e64 v2, v2, v11, s[4:5]
	v_min_u32_e32 v9, v10, v5
	v_max_u32_e32 v5, v10, v5
	v_min_u32_e32 v10, v7, v4
	v_max_u32_e32 v4, v7, v4
	v_min_u32_e32 v7, v8, v3
	v_max_u32_e32 v3, v8, v3
	v_min_u32_e32 v8, v6, v2
	v_max_u32_e32 v2, v6, v2
	v_min_u32_e32 v6, v9, v7
	v_max_u32_e32 v7, v9, v7
	v_min_u32_e32 v9, v10, v8
	v_max_u32_e32 v8, v10, v8
	v_min_u32_e32 v10, v5, v3
	v_max_u32_e32 v11, v5, v3
	v_min_u32_e32 v12, v4, v2
	v_max_u32_e32 v96, v4, v2
	v_min_u32_e32 v2, v6, v9
	v_max_u32_e32 v3, v6, v9
	v_min_u32_e32 v4, v7, v8
	v_max_u32_e32 v5, v7, v8
	v_min_u32_e32 v6, v10, v12
	v_max_u32_e32 v7, v10, v12
	v_min_u32_e32 v8, v11, v96
	v_max_u32_e32 v9, v11, v96
	ds_write_b128 v134, v[2:5]
	ds_write_b128 v134, v[6:9] offset:16
	s_waitcnt lgkmcnt(0)
	ds_read2_b32 v[2:3], v144 offset1:16
	ds_read2_b32 v[4:5], v144 offset0:32 offset1:48
	ds_read2_b32 v[8:9], v144 offset0:64 offset1:80
	ds_read2_b32 v[96:97], v144 offset0:96 offset1:112
	s_waitcnt lgkmcnt(3)
	v_and_b32_e32 v2, 0x7f, v2
	v_lshlrev_b32_e32 v12, 2, v2
	v_and_b32_e32 v2, 0x7f, v3
	v_lshl_add_u64 v[6:7], v[0:1], 0, v[12:13]
	v_lshlrev_b32_e32 v12, 2, v2
	s_waitcnt lgkmcnt(2)
	v_and_b32_e32 v4, 0x7f, v4
	v_lshl_add_u64 v[2:3], v[0:1], 0, v[12:13]
	v_lshlrev_b32_e32 v12, 2, v4
	v_and_b32_e32 v4, 0x7f, v5
	v_lshl_add_u64 v[10:11], v[0:1], 0, v[12:13]
	v_lshlrev_b32_e32 v12, 2, v4
	s_waitcnt lgkmcnt(1)
	v_and_b32_e32 v8, 0x7f, v8
	v_lshl_add_u64 v[4:5], v[0:1], 0, v[12:13]
	v_lshlrev_b32_e32 v12, 2, v8
	v_and_b32_e32 v8, 0x7f, v9
	v_lshl_add_u64 v[104:105], v[0:1], 0, v[12:13]
	v_lshlrev_b32_e32 v12, 2, v8
	v_lshl_add_u64 v[8:9], v[0:1], 0, v[12:13]
	s_waitcnt lgkmcnt(0)
	v_and_b32_e32 v12, 0x7f, v96
	v_lshlrev_b32_e32 v12, 2, v12
	v_lshl_add_u64 v[106:107], v[0:1], 0, v[12:13]
	v_and_b32_e32 v12, 0x7f, v97
	v_lshlrev_b32_e32 v12, 2, v12
	v_lshl_add_u64 v[0:1], v[0:1], 0, v[12:13]
	global_load_dword v103, v[6:7], off
	global_load_dword v102, v[2:3], off
	global_load_dword v101, v[10:11], off
	global_load_dword v100, v[4:5], off
	global_load_dword v99, v[104:105], off
	global_load_dword v98, v[8:9], off
	global_load_dword v97, v[106:107], off
	global_load_dword v96, v[0:1], off
	v_lshlrev_b32_e32 v250, 1, v132
	v_mov_b32_e32 v104, 0
	v_mov_b32_e32 v105, 0
	v_mov_b32_e32 v106, 0
	v_mov_b32_e32 v107, 0
	ds_read_b128 v[0:3], v133
	ds_read_b128 v[4:7], v133 offset:16
	ds_write_b128 v134, v[104:107] offset:2048
	ds_write_b128 v134, v[104:107] offset:2064
	s_lshl_b32 s27, s83, 8
	v_add_u32_e32 v230, s27, v250
	v_add_u32_e32 v231, v133, v142
	v_add_u32_e32 v251, v133, v142
	v_add_u32_e32 v254, 64, v133
	s_mov_b32 s26, 0
	s_mov_b32 s27, s83
	s_cmp_eq_u32 s27, 0
	s_cbranch_scc1 .Lgu_p_0
	s_cmp_eq_u32 s27, 1
	s_cbranch_scc1 .Lgu_p_1
	s_cmp_eq_u32 s27, 2
	s_cbranch_scc1 .Lgu_p_2
	v_mov_b32_e32 v214, v80
	v_mov_b32_e32 v215, v81
	v_mov_b32_e32 v216, v82
	v_mov_b32_e32 v217, v83
	v_mov_b32_e32 v218, v84
	v_mov_b32_e32 v219, v85
	v_mov_b32_e32 v220, v86
	v_mov_b32_e32 v221, v87
	v_mov_b32_e32 v222, v88
	v_mov_b32_e32 v223, v89
	v_mov_b32_e32 v224, v90
	v_mov_b32_e32 v225, v91
	v_mov_b32_e32 v226, v92
	v_mov_b32_e32 v227, v93
	v_mov_b32_e32 v228, v94
	v_mov_b32_e32 v229, v95
	s_branch .Lgu_p_x
.Lgu_p_0:
	v_mov_b32_e32 v214, v32
	v_mov_b32_e32 v215, v33
	v_mov_b32_e32 v216, v34
	v_mov_b32_e32 v217, v35
	v_mov_b32_e32 v218, v36
	v_mov_b32_e32 v219, v37
	v_mov_b32_e32 v220, v38
	v_mov_b32_e32 v221, v39
	v_mov_b32_e32 v222, v40
	v_mov_b32_e32 v223, v41
	v_mov_b32_e32 v224, v42
	v_mov_b32_e32 v225, v43
	v_mov_b32_e32 v226, v44
	v_mov_b32_e32 v227, v45
	v_mov_b32_e32 v228, v46
	v_mov_b32_e32 v229, v47
	s_branch .Lgu_p_x

; __device__ void phase_gather(const P& p, int vb, int nvb, char* smem) {
;     ...
;     for (int b0 = 0; b0 < 128; b0 += 8) {
;       float dp[8];
; #pragma unroll
;       for (int u = 0; u < 8; u++) {
;         const uint32_t key = mykl[b0 + u];
;         const int e = (int)(key >> 7);
;         const uint4* up = (const uint4*)(U + (size_t)e * 1024 + 16 * j);
;         uint4 uu[4];
; #pragma unroll
;         for (int i = 0; i < 4; i++) uu[i] = up[i * 16];
.Lgu_p_x:
	s_waitcnt lgkmcnt(0)
	v_and_b32_e32 v8, 0xffffff80, v0
	v_lshl_add_u32 v8, v8, 3, v230
	global_load_dwordx4 v[150:153], v8, s[98:99]
	v_and_b32_e32 v9, 0xffffff80, v1
	v_lshl_add_u32 v9, v9, 3, v230
	global_load_dwordx4 v[154:157], v9, s[98:99]
	v_and_b32_e32 v8, 0xffffff80, v2
	v_lshl_add_u32 v8, v8, 3, v230
	global_load_dwordx4 v[158:161], v8, s[98:99]
	v_and_b32_e32 v9, 0xffffff80, v3
	v_lshl_add_u32 v9, v9, 3, v230
	global_load_dwordx4 v[162:165], v9, s[98:99]
	v_and_b32_e32 v8, 0xffffff80, v4
	v_lshl_add_u32 v8, v8, 3, v230
	global_load_dwordx4 v[166:169], v8, s[98:99]
	v_and_b32_e32 v9, 0xffffff80, v5
	v_lshl_add_u32 v9, v9, 3, v230
	global_load_dwordx4 v[170:173], v9, s[98:99]
	v_and_b32_e32 v8, 0xffffff80, v6
	v_lshl_add_u32 v8, v8, 3, v230
	global_load_dwordx4 v[174:177], v8, s[98:99]
	v_and_b32_e32 v9, 0xffffff80, v7
	v_lshl_add_u32 v9, v9, 3, v230
	global_load_dwordx4 v[178:181], v9, s[98:99]
	ds_read_b128 v[0:3], v133 offset:32
	ds_read_b128 v[4:7], v133 offset:48
	s_waitcnt lgkmcnt(0)
	v_and_b32_e32 v8, 0xffffff80, v0
	v_lshl_add_u32 v8, v8, 3, v230
	global_load_dwordx4 v[182:185], v8, s[98:99]
	v_and_b32_e32 v9, 0xffffff80, v1
	v_lshl_add_u32 v9, v9, 3, v230
	global_load_dwordx4 v[186:189], v9, s[98:99]
	v_and_b32_e32 v8, 0xffffff80, v2
	v_lshl_add_u32 v8, v8, 3, v230
	global_load_dwordx4 v[190:193], v8, s[98:99]
	v_and_b32_e32 v9, 0xffffff80, v3
	v_lshl_add_u32 v9, v9, 3, v230
	global_load_dwordx4 v[194:197], v9, s[98:99]
	v_and_b32_e32 v8, 0xffffff80, v4
	v_lshl_add_u32 v8, v8, 3, v230
	global_load_dwordx4 v[198:201], v8, s[98:99]
	v_and_b32_e32 v9, 0xffffff80, v5
	v_lshl_add_u32 v9, v9, 3, v230
	global_load_dwordx4 v[202:205], v9, s[98:99]
	v_and_b32_e32 v8, 0xffffff80, v6
	v_lshl_add_u32 v8, v8, 3, v230
	global_load_dwordx4 v[206:209], v8, s[98:99]
	v_and_b32_e32 v9, 0xffffff80, v7
	v_lshl_add_u32 v9, v9, 3, v230
	global_load_dwordx4 v[210:213], v9, s[98:99]
	ds_read_b128 v[0:3], v133 offset:64
	s_branch .Lgu_body
.Lgu_iter:
	s_and_b32 s27, s26, 7
	s_cmp_lg_u32 s27, 0
	s_cbranch_scc1 .Lgu_body
	s_lshr_b32 s27, s26, 3
	s_add_i32 s27, s27, s83
	s_and_b32 s27, s27, 3
	s_cmp_eq_u32 s27, 0
	s_cbranch_scc1 .Lgu_s_0
	s_cmp_eq_u32 s27, 1
	s_cbranch_scc1 .Lgu_s_1
	s_cmp_eq_u32 s27, 2
	s_cbranch_scc1 .Lgu_s_2
	v_mov_b32_e32 v214, v80
	v_mov_b32_e32 v215, v81
	v_mov_b32_e32 v216, v82
	v_mov_b32_e32 v217, v83
	v_mov_b32_e32 v218, v84
	v_mov_b32_e32 v219, v85
	v_mov_b32_e32 v220, v86
	v_mov_b32_e32 v221, v87
	v_mov_b32_e32 v222, v88
	v_mov_b32_e32 v223, v89
	v_mov_b32_e32 v224, v90
	v_mov_b32_e32 v225, v91
	v_mov_b32_e32 v226, v92
	v_mov_b32_e32 v227, v93
	v_mov_b32_e32 v228, v94
	v_mov_b32_e32 v229, v95
	s_branch .Lgu_s_x

; __device__ void phase_gather(const P& p, int vb, int nvb, char* smem) {
;     ...
;       for (int u = 0; u < 8; u++) {
;         const uint32_t key = mykl[b0 + u];
;         const int e = (int)(key >> 7);
;         const uint4* up = (const uint4*)(U + (size_t)e * 1024 + 16 * j);
;         uint4 uu[4];
; #pragma unroll
;         for (int i = 0; i < 4; i++) uu[i] = up[i * 16];
;         f32x2 d2 = f32x2{0.f, 0.f};
; #pragma unroll
;         for (int i = 0; i < 4; i++) {
;           const uint32_t w[4] = {uu[i].x, uu[i].y, uu[i].z, uu[i].w};
; #pragma unroll
;           for (int q = 0; q < 4; q++) {
;             d2 += __builtin_amdgcn_cvt_pk_f32_fp8((int)w[q], false) * xf[i * 8 + q * 2 + 0];
;             d2 += __builtin_amdgcn_cvt_pk_f32_fp8((int)w[q], true) * xf[i * 8 + q * 2 + 1];
;           }
;         }
;         dp[u] = d2.x + d2.y;
.Lgu_s_x:
.Lgu_body:
	s_cmp_eq_u32 s26, 31
	s_cbranch_scc1 .Lgu_last
	s_waitcnt lgkmcnt(0)
	v_and_b32_e32 v8, 0xffffff80, v0
	s_waitcnt vmcnt(15)
	v_cvt_pk_f32_fp8_e32 v[104:105], v150
	v_cvt_pk_f32_fp8_sdwa v[106:107], v150 src0_sel:WORD_1
	v_pk_mul_f32 v[112:113], v[104:105], v[214:215]
	v_pk_mul_f32 v[114:115], v[106:107], v[216:217]
	v_cvt_pk_f32_fp8_e32 v[108:109], v151
	v_cvt_pk_f32_fp8_sdwa v[110:111], v151 src0_sel:WORD_1
	v_pk_fma_f32 v[112:113], v[108:109], v[218:219], v[112:113]
	v_pk_fma_f32 v[114:115], v[110:111], v[220:221], v[114:115]
	v_cvt_pk_f32_fp8_e32 v[104:105], v152
	v_cvt_pk_f32_fp8_sdwa v[106:107], v152 src0_sel:WORD_1
	v_pk_fma_f32 v[112:113], v[104:105], v[222:223], v[112:113]
	v_pk_fma_f32 v[114:115], v[106:107], v[224:225], v[114:115]
	v_cvt_pk_f32_fp8_e32 v[108:109], v153
	v_cvt_pk_f32_fp8_sdwa v[110:111], v153 src0_sel:WORD_1
	v_pk_fma_f32 v[112:113], v[108:109], v[226:227], v[112:113]
	v_pk_fma_f32 v[114:115], v[110:111], v[228:229], v[114:115]
	v_lshl_add_u32 v8, v8, 3, v230
	v_pk_add_f32 v[112:113], v[112:113], v[114:115]
	global_load_dwordx4 v[150:153], v8, s[98:99]
	v_add_f32_e32 v116, v112, v113
	v_and_b32_e32 v9, 0xffffff80, v1
	s_waitcnt vmcnt(15)
	v_cvt_pk_f32_fp8_e32 v[104:105], v154
	v_cvt_pk_f32_fp8_sdwa v[106:107], v154 src0_sel:WORD_1
	v_pk_mul_f32 v[112:113], v[104:105], v[214:215]
	v_pk_mul_f32 v[114:115], v[106:107], v[216:217]
	v_cvt_pk_f32_fp8_e32 v[108:109], v155
	v_cvt_pk_f32_fp8_sdwa v[110:111], v155 src0_sel:WORD_1
	v_pk_fma_f32 v[112:113], v[108:109], v[218:219], v[112:113]
	v_pk_fma_f32 v[114:115], v[110:111], v[220:221], v[114:115]
	v_cvt_pk_f32_fp8_e32 v[104:105], v156
	v_cvt_pk_f32_fp8_sdwa v[106:107], v156 src0_sel:WORD_1
	v_pk_fma_f32 v[112:113], v[104:105], v[222:223], v[112:113]
	v_pk_fma_f32 v[114:115], v[106:107], v[224:225], v[114:115]
	v_cvt_pk_f32_fp8_e32 v[108:109], v157
	v_cvt_pk_f32_fp8_sdwa v[110:111], v157 src0_sel:WORD_1
	v_pk_fma_f32 v[112:113], v[108:109], v[226:227], v[112:113]
	v_pk_fma_f32 v[114:115], v[110:111], v[228:229], v[114:115]
	v_lshl_add_u32 v9, v9, 3, v230
	v_pk_add_f32 v[112:113], v[112:113], v[114:115]
	global_load_dwordx4 v[154:157], v9, s[98:99]
	v_add_f32_e32 v117, v112, v113
	ds_read_b128 v[4:7], v254 offset:16
	v_and_b32_e32 v8, 0xffffff80, v2
	s_waitcnt vmcnt(15)
	v_cvt_pk_f32_fp8_e32 v[104:105], v158
	v_cvt_pk_f32_fp8_sdwa v[106:107], v158 src0_sel:WORD_1
	v_pk_mul_f32 v[112:113], v[104:105], v[214:215]
	v_pk_mul_f32 v[114:115], v[106:107], v[216:217]
	v_cvt_pk_f32_fp8_e32 v[108:109], v159
	v_cvt_pk_f32_fp8_sdwa v[110:111], v159 src0_sel:WORD_1
	v_pk_fma_f32 v[112:113], v[108:109], v[218:219], v[112:113]
	v_pk_fma_f32 v[114:115], v[110:111], v[220:221], v[114:115]
	v_cvt_pk_f32_fp8_e32 v[104:105], v160
	v_cvt_pk_f32_fp8_sdwa v[106:107], v160 src0_sel:WORD_1
	v_pk_fma_f32 v[112:113], v[104:105], v[222:223], v[112:113]
	v_pk_fma_f32 v[114:115], v[106:107], v[224:225], v[114:115]
	v_cvt_pk_f32_fp8_e32 v[108:109], v161
	v_cvt_pk_f32_fp8_sdwa v[110:111], v161 src0_sel:WORD_1
	v_pk_fma_f32 v[112:113], v[108:109], v[226:227], v[112:113]
	v_pk_fma_f32 v[114:115], v[110:111], v[228:229], v[114:115]
	v_lshl_add_u32 v8, v8, 3, v230
	v_pk_add_f32 v[112:113], v[112:113], v[114:115]
	global_load_dwordx4 v[158:161], v8, s[98:99]
	v_add_f32_e32 v118, v112, v113
	v_and_b32_e32 v9, 0xffffff80, v3
	s_waitcnt vmcnt(15)
	v_cvt_pk_f32_fp8_e32 v[104:105], v162
	v_cvt_pk_f32_fp8_sdwa v[106:107], v162 src0_sel:WORD_1
	v_pk_mul_f32 v[112:113], v[104:105], v[214:215]
	v_pk_mul_f32 v[114:115], v[106:107], v[216:217]
	v_cvt_pk_f32_fp8_e32 v[108:109], v163
	v_cvt_pk_f32_fp8_sdwa v[110:111], v163 src0_sel:WORD_1
	v_pk_fma_f32 v[112:113], v[108:109], v[218:219], v[112:113]
	v_pk_fma_f32 v[114:115], v[110:111], v[220:221], v[114:115]
	v_cvt_pk_f32_fp8_e32 v[104:105], v164
	v_cvt_pk_f32_fp8_sdwa v[106:107], v164 src0_sel:WORD_1
	v_pk_fma_f32 v[112:113], v[104:105], v[222:223], v[112:113]
	v_pk_fma_f32 v[114:115], v[106:107], v[224:225], v[114:115]
	v_cvt_pk_f32_fp8_e32 v[108:109], v165
	v_cvt_pk_f32_fp8_sdwa v[110:111], v165 src0_sel:WORD_1
	v_pk_fma_f32 v[112:113], v[108:109], v[226:227], v[112:113]
	v_pk_fma_f32 v[114:115], v[110:111], v[228:229], v[114:115]
	v_lshl_add_u32 v9, v9, 3, v230
	v_pk_add_f32 v[112:113], v[112:113], v[114:115]
	global_load_dwordx4 v[162:165], v9, s[98:99]
	v_add_f32_e32 v119, v112, v113
	s_waitcnt lgkmcnt(0)
	v_and_b32_e32 v8, 0xffffff80, v4
	s_waitcnt vmcnt(15)
	v_cvt_pk_f32_fp8_e32 v[104:105], v166
	v_cvt_pk_f32_fp8_sdwa v[106:107], v166 src0_sel:WORD_1
	v_pk_mul_f32 v[112:113], v[104:105], v[214:215]
	v_pk_mul_f32 v[114:115], v[106:107], v[216:217]
	v_cvt_pk_f32_fp8_e32 v[108:109], v167
	v_cvt_pk_f32_fp8_sdwa v[110:111], v167 src0_sel:WORD_1
	v_pk_fma_f32 v[112:113], v[108:109], v[218:219], v[112:113]
	v_pk_fma_f32 v[114:115], v[110:111], v[220:221], v[114:115]
	v_cvt_pk_f32_fp8_e32 v[104:105], v168
	v_cvt_pk_f32_fp8_sdwa v[106:107], v168 src0_sel:WORD_1
	v_pk_fma_f32 v[112:113], v[104:105], v[222:223], v[112:113]
	v_pk_fma_f32 v[114:115], v[106:107], v[224:225], v[114:115]
	v_cvt_pk_f32_fp8_e32 v[108:109], v169
	v_cvt_pk_f32_fp8_sdwa v[110:111], v169 src0_sel:WORD_1
	v_pk_fma_f32 v[112:113], v[108:109], v[226:227], v[112:113]
	v_pk_fma_f32 v[114:115], v[110:111], v[228:229], v[114:115]
	v_lshl_add_u32 v8, v8, 3, v230
	v_pk_add_f32 v[112:113], v[112:113], v[114:115]
	global_load_dwordx4 v[166:169], v8, s[98:99]
	v_add_f32_e32 v120, v112, v113
	v_and_b32_e32 v9, 0xffffff80, v5
	s_waitcnt vmcnt(15)
; __device__ void phase_gather(const P& p, int vb, int nvb, char* smem) {
;     ...
; #pragma unroll
;         for (int i = 0; i < 4; i++) {
;           const uint32_t w[4] = {uu[i].x, uu[i].y, uu[i].z, uu[i].w};
; #pragma unroll
;           for (int q = 0; q < 4; q++) {
;             d2 += __builtin_amdgcn_cvt_pk_f32_fp8((int)w[q], false) * xf[i * 8 + q * 2 + 0];
;             d2 += __builtin_amdgcn_cvt_pk_f32_fp8((int)w[q], true) * xf[i * 8 + q * 2 + 1];
;           }
;         }
;         dp[u] = d2.x + d2.y;
;       }
;       const bool h8 = (j & 8) != 0, h4 = (j & 4) != 0, h2b = (j & 2) != 0;
;       float q4[4], q2[2];
; #pragma unroll
;       for (int k = 0; k < 4; k++) { const float snd = h8 ? dp[k] : dp[k + 4], kp = h8 ? dp[k + 4] : dp[k]; q4[k] = kp + __shfl_xor(snd, 8); }
; #pragma unroll
;       for (int k = 0; k < 2; k++) { const float snd = h4 ? q4[k] : q4[k + 2], kp = h4 ? q4[k + 2] : q4[k]; q2[k] = kp + __shfl_xor(snd, 4); }
;       const float snd1 = h2b ? q2[0] : q2[1], kp1 = h2b ? q2[1] : q2[0];
;       float q1 = kp1 + __shfl_xor(snd1, 2);
;       q1 += __shfl_xor(q1, 1);
;       if ((j & 1) == 0) mywl[b0 + (j >> 1)] = q1;
	v_cvt_pk_f32_fp8_e32 v[104:105], v170
	v_cvt_pk_f32_fp8_sdwa v[106:107], v170 src0_sel:WORD_1
	v_pk_mul_f32 v[112:113], v[104:105], v[214:215]
	v_pk_mul_f32 v[114:115], v[106:107], v[216:217]
	v_cvt_pk_f32_fp8_e32 v[108:109], v171
	v_cvt_pk_f32_fp8_sdwa v[110:111], v171 src0_sel:WORD_1
	v_pk_fma_f32 v[112:113], v[108:109], v[218:219], v[112:113]
	v_pk_fma_f32 v[114:115], v[110:111], v[220:221], v[114:115]
	v_cvt_pk_f32_fp8_e32 v[104:105], v172
	v_cvt_pk_f32_fp8_sdwa v[106:107], v172 src0_sel:WORD_1
	v_pk_fma_f32 v[112:113], v[104:105], v[222:223], v[112:113]
	v_pk_fma_f32 v[114:115], v[106:107], v[224:225], v[114:115]
	v_cvt_pk_f32_fp8_e32 v[108:109], v173
	v_cvt_pk_f32_fp8_sdwa v[110:111], v173 src0_sel:WORD_1
	v_pk_fma_f32 v[112:113], v[108:109], v[226:227], v[112:113]
	v_pk_fma_f32 v[114:115], v[110:111], v[228:229], v[114:115]
	v_lshl_add_u32 v9, v9, 3, v230
	v_pk_add_f32 v[112:113], v[112:113], v[114:115]
	global_load_dwordx4 v[170:173], v9, s[98:99]
	v_add_f32_e32 v121, v112, v113
	ds_read_b128 v[0:3], v254 offset:32
	v_and_b32_e32 v8, 0xffffff80, v6
	s_waitcnt vmcnt(15)
	v_cvt_pk_f32_fp8_e32 v[104:105], v174
	v_cvt_pk_f32_fp8_sdwa v[106:107], v174 src0_sel:WORD_1
	v_pk_mul_f32 v[112:113], v[104:105], v[214:215]
	v_pk_mul_f32 v[114:115], v[106:107], v[216:217]
	v_cvt_pk_f32_fp8_e32 v[108:109], v175
	v_cvt_pk_f32_fp8_sdwa v[110:111], v175 src0_sel:WORD_1
	v_pk_fma_f32 v[112:113], v[108:109], v[218:219], v[112:113]
	v_pk_fma_f32 v[114:115], v[110:111], v[220:221], v[114:115]
	v_cvt_pk_f32_fp8_e32 v[104:105], v176
	v_cvt_pk_f32_fp8_sdwa v[106:107], v176 src0_sel:WORD_1
	v_pk_fma_f32 v[112:113], v[104:105], v[222:223], v[112:113]
	v_pk_fma_f32 v[114:115], v[106:107], v[224:225], v[114:115]
	v_cvt_pk_f32_fp8_e32 v[108:109], v177
	v_cvt_pk_f32_fp8_sdwa v[110:111], v177 src0_sel:WORD_1
	v_pk_fma_f32 v[112:113], v[108:109], v[226:227], v[112:113]
	v_pk_fma_f32 v[114:115], v[110:111], v[228:229], v[114:115]
	v_lshl_add_u32 v8, v8, 3, v230
	v_pk_add_f32 v[112:113], v[112:113], v[114:115]
	global_load_dwordx4 v[174:177], v8, s[98:99]
	v_add_f32_e32 v122, v112, v113
	v_and_b32_e32 v9, 0xffffff80, v7
	s_waitcnt vmcnt(15)
	v_cvt_pk_f32_fp8_e32 v[104:105], v178
	v_cvt_pk_f32_fp8_sdwa v[106:107], v178 src0_sel:WORD_1
	v_pk_mul_f32 v[112:113], v[104:105], v[214:215]
	v_pk_mul_f32 v[114:115], v[106:107], v[216:217]
	v_cvt_pk_f32_fp8_e32 v[108:109], v179
	v_cvt_pk_f32_fp8_sdwa v[110:111], v179 src0_sel:WORD_1
	v_pk_fma_f32 v[112:113], v[108:109], v[218:219], v[112:113]
	v_pk_fma_f32 v[114:115], v[110:111], v[220:221], v[114:115]
	v_cvt_pk_f32_fp8_e32 v[104:105], v180
	v_cvt_pk_f32_fp8_sdwa v[106:107], v180 src0_sel:WORD_1
	v_pk_fma_f32 v[112:113], v[104:105], v[222:223], v[112:113]
	v_pk_fma_f32 v[114:115], v[106:107], v[224:225], v[114:115]
	v_cvt_pk_f32_fp8_e32 v[108:109], v181
	v_cvt_pk_f32_fp8_sdwa v[110:111], v181 src0_sel:WORD_1
	v_pk_fma_f32 v[112:113], v[108:109], v[226:227], v[112:113]
	v_pk_fma_f32 v[114:115], v[110:111], v[228:229], v[114:115]
	v_lshl_add_u32 v9, v9, 3, v230
	v_pk_add_f32 v[112:113], v[112:113], v[114:115]
	global_load_dwordx4 v[178:181], v9, s[98:99]
	v_add_f32_e32 v123, v112, v113
	v_add_f32_dpp v10, v116, v116 row_ror:8 row_mask:0xf bank_mask:0x3
	v_add_f32_dpp v11, v117, v117 row_ror:8 row_mask:0xf bank_mask:0x3
	v_add_f32_dpp v12, v118, v118 row_ror:8 row_mask:0xf bank_mask:0x3
	v_add_f32_dpp v124, v119, v119 row_ror:8 row_mask:0xf bank_mask:0x3
	v_add_f32_dpp v10, v120, v120 row_ror:8 row_mask:0xf bank_mask:0xc
	v_add_f32_dpp v11, v121, v121 row_ror:8 row_mask:0xf bank_mask:0xc
	v_add_f32_dpp v12, v122, v122 row_ror:8 row_mask:0xf bank_mask:0xc
	v_add_f32_dpp v124, v123, v123 row_ror:8 row_mask:0xf bank_mask:0xc
	s_nop 0
	v_add_f32_dpp v125, v10, v10 row_shl:4 row_mask:0xf bank_mask:0x5
	v_add_f32_dpp v246, v11, v11 row_shl:4 row_mask:0xf bank_mask:0x5
	v_add_f32_dpp v125, v12, v12 row_shr:4 row_mask:0xf bank_mask:0xa
	v_add_f32_dpp v246, v124, v124 row_shr:4 row_mask:0xf bank_mask:0xa
	s_nop 1
	v_add_f32_dpp v247, v125, v125 quad_perm:[2,3,0,1] row_mask:0xf bank_mask:0xf
	v_add_f32_dpp v249, v246, v246 quad_perm:[2,3,0,1] row_mask:0xf bank_mask:0xf
	s_nop 0
	v_cndmask_b32_e64 v252, v249, v247, s[2:3]
	s_nop 1
	v_add_f32_dpp v253, v252, v252 quad_perm:[1,0,3,2] row_mask:0xf bank_mask:0xf
	s_and_saveexec_b64 s[20:21], s[4:5]
	ds_add_f32 v251, v253 offset:2048
	s_mov_b64 exec, s[20:21]
	s_waitcnt lgkmcnt(0)
	v_and_b32_e32 v8, 0xffffff80, v0
	s_waitcnt vmcnt(15)
	v_cvt_pk_f32_fp8_e32 v[104:105], v182
	v_cvt_pk_f32_fp8_sdwa v[106:107], v182 src0_sel:WORD_1
	v_pk_mul_f32 v[112:113], v[104:105], v[214:215]
	v_pk_mul_f32 v[114:115], v[106:107], v[216:217]
	v_cvt_pk_f32_fp8_e32 v[108:109], v183
	v_cvt_pk_f32_fp8_sdwa v[110:111], v183 src0_sel:WORD_1
	v_pk_fma_f32 v[112:113], v[108:109], v[218:219], v[112:113]
	v_pk_fma_f32 v[114:115], v[110:111], v[220:221], v[114:115]
	v_cvt_pk_f32_fp8_e32 v[104:105], v184
	v_cvt_pk_f32_fp8_sdwa v[106:107], v184 src0_sel:WORD_1
	v_pk_fma_f32 v[112:113], v[104:105], v[222:223], v[112:113]
	v_pk_fma_f32 v[114:115], v[106:107], v[224:225], v[114:115]
	v_cvt_pk_f32_fp8_e32 v[108:109], v185
	v_cvt_pk_f32_fp8_sdwa v[110:111], v185 src0_sel:WORD_1
	v_pk_fma_f32 v[112:113], v[108:109], v[226:227], v[112:113]
	v_pk_fma_f32 v[114:115], v[110:111], v[228:229], v[114:115]
	v_lshl_add_u32 v8, v8, 3, v230
	v_pk_add_f32 v[112:113], v[112:113], v[114:115]
	global_load_dwordx4 v[182:185], v8, s[98:99]
	v_add_f32_e32 v116, v112, v113
	v_and_b32_e32 v9, 0xffffff80, v1
	s_waitcnt vmcnt(15)
; __device__ void phase_gather(const P& p, int vb, int nvb, char* smem) {
;     ...
;       for (int u = 0; u < 8; u++) {
;         const uint32_t key = mykl[b0 + u];
;         const int e = (int)(key >> 7);
;         const uint4* up = (const uint4*)(U + (size_t)e * 1024 + 16 * j);
;         uint4 uu[4];
; #pragma unroll
;         for (int i = 0; i < 4; i++) uu[i] = up[i * 16];
;         f32x2 d2 = f32x2{0.f, 0.f};
; #pragma unroll
;         for (int i = 0; i < 4; i++) {
;           const uint32_t w[4] = {uu[i].x, uu[i].y, uu[i].z, uu[i].w};
; #pragma unroll
;           for (int q = 0; q < 4; q++) {
;             d2 += __builtin_amdgcn_cvt_pk_f32_fp8((int)w[q], false) * xf[i * 8 + q * 2 + 0];
;             d2 += __builtin_amdgcn_cvt_pk_f32_fp8((int)w[q], true) * xf[i * 8 + q * 2 + 1];
;           }
;         }
;         dp[u] = d2.x + d2.y;
	v_cvt_pk_f32_fp8_e32 v[104:105], v186
	v_cvt_pk_f32_fp8_sdwa v[106:107], v186 src0_sel:WORD_1
	v_pk_mul_f32 v[112:113], v[104:105], v[214:215]
	v_pk_mul_f32 v[114:115], v[106:107], v[216:217]
	v_cvt_pk_f32_fp8_e32 v[108:109], v187
	v_cvt_pk_f32_fp8_sdwa v[110:111], v187 src0_sel:WORD_1
	v_pk_fma_f32 v[112:113], v[108:109], v[218:219], v[112:113]
	v_pk_fma_f32 v[114:115], v[110:111], v[220:221], v[114:115]
	v_cvt_pk_f32_fp8_e32 v[104:105], v188
	v_cvt_pk_f32_fp8_sdwa v[106:107], v188 src0_sel:WORD_1
	v_pk_fma_f32 v[112:113], v[104:105], v[222:223], v[112:113]
	v_pk_fma_f32 v[114:115], v[106:107], v[224:225], v[114:115]
	v_cvt_pk_f32_fp8_e32 v[108:109], v189
	v_cvt_pk_f32_fp8_sdwa v[110:111], v189 src0_sel:WORD_1
	v_pk_fma_f32 v[112:113], v[108:109], v[226:227], v[112:113]
	v_pk_fma_f32 v[114:115], v[110:111], v[228:229], v[114:115]
	v_lshl_add_u32 v9, v9, 3, v230
	v_pk_add_f32 v[112:113], v[112:113], v[114:115]
	global_load_dwordx4 v[186:189], v9, s[98:99]
	v_add_f32_e32 v117, v112, v113
	ds_read_b128 v[4:7], v254 offset:48
	v_and_b32_e32 v8, 0xffffff80, v2
	s_waitcnt vmcnt(15)
	v_cvt_pk_f32_fp8_e32 v[104:105], v190
	v_cvt_pk_f32_fp8_sdwa v[106:107], v190 src0_sel:WORD_1
	v_pk_mul_f32 v[112:113], v[104:105], v[214:215]
	v_pk_mul_f32 v[114:115], v[106:107], v[216:217]
	v_cvt_pk_f32_fp8_e32 v[108:109], v191
	v_cvt_pk_f32_fp8_sdwa v[110:111], v191 src0_sel:WORD_1
	v_pk_fma_f32 v[112:113], v[108:109], v[218:219], v[112:113]
	v_pk_fma_f32 v[114:115], v[110:111], v[220:221], v[114:115]
	v_cvt_pk_f32_fp8_e32 v[104:105], v192
	v_cvt_pk_f32_fp8_sdwa v[106:107], v192 src0_sel:WORD_1
	v_pk_fma_f32 v[112:113], v[104:105], v[222:223], v[112:113]
	v_pk_fma_f32 v[114:115], v[106:107], v[224:225], v[114:115]
	v_cvt_pk_f32_fp8_e32 v[108:109], v193
	v_cvt_pk_f32_fp8_sdwa v[110:111], v193 src0_sel:WORD_1
	v_pk_fma_f32 v[112:113], v[108:109], v[226:227], v[112:113]
	v_pk_fma_f32 v[114:115], v[110:111], v[228:229], v[114:115]
	v_lshl_add_u32 v8, v8, 3, v230
	v_pk_add_f32 v[112:113], v[112:113], v[114:115]
	global_load_dwordx4 v[190:193], v8, s[98:99]
	v_add_f32_e32 v118, v112, v113
	v_and_b32_e32 v9, 0xffffff80, v3
	s_waitcnt vmcnt(15)
	v_cvt_pk_f32_fp8_e32 v[104:105], v194
	v_cvt_pk_f32_fp8_sdwa v[106:107], v194 src0_sel:WORD_1
	v_pk_mul_f32 v[112:113], v[104:105], v[214:215]
	v_pk_mul_f32 v[114:115], v[106:107], v[216:217]
	v_cvt_pk_f32_fp8_e32 v[108:109], v195
	v_cvt_pk_f32_fp8_sdwa v[110:111], v195 src0_sel:WORD_1
	v_pk_fma_f32 v[112:113], v[108:109], v[218:219], v[112:113]
	v_pk_fma_f32 v[114:115], v[110:111], v[220:221], v[114:115]
	v_cvt_pk_f32_fp8_e32 v[104:105], v196
	v_cvt_pk_f32_fp8_sdwa v[106:107], v196 src0_sel:WORD_1
	v_pk_fma_f32 v[112:113], v[104:105], v[222:223], v[112:113]
	v_pk_fma_f32 v[114:115], v[106:107], v[224:225], v[114:115]
	v_cvt_pk_f32_fp8_e32 v[108:109], v197
	v_cvt_pk_f32_fp8_sdwa v[110:111], v197 src0_sel:WORD_1
	v_pk_fma_f32 v[112:113], v[108:109], v[226:227], v[112:113]
	v_pk_fma_f32 v[114:115], v[110:111], v[228:229], v[114:115]
	v_lshl_add_u32 v9, v9, 3, v230
	v_pk_add_f32 v[112:113], v[112:113], v[114:115]
	global_load_dwordx4 v[194:197], v9, s[98:99]
	v_add_f32_e32 v119, v112, v113
	s_waitcnt lgkmcnt(0)
	v_and_b32_e32 v8, 0xffffff80, v4
	s_waitcnt vmcnt(15)
	v_cvt_pk_f32_fp8_e32 v[104:105], v198
	v_cvt_pk_f32_fp8_sdwa v[106:107], v198 src0_sel:WORD_1
	v_pk_mul_f32 v[112:113], v[104:105], v[214:215]
	v_pk_mul_f32 v[114:115], v[106:107], v[216:217]
	v_cvt_pk_f32_fp8_e32 v[108:109], v199
	v_cvt_pk_f32_fp8_sdwa v[110:111], v199 src0_sel:WORD_1
	v_pk_fma_f32 v[112:113], v[108:109], v[218:219], v[112:113]
	v_pk_fma_f32 v[114:115], v[110:111], v[220:221], v[114:115]
	v_cvt_pk_f32_fp8_e32 v[104:105], v200
	v_cvt_pk_f32_fp8_sdwa v[106:107], v200 src0_sel:WORD_1
	v_pk_fma_f32 v[112:113], v[104:105], v[222:223], v[112:113]
	v_pk_fma_f32 v[114:115], v[106:107], v[224:225], v[114:115]
	v_cvt_pk_f32_fp8_e32 v[108:109], v201
	v_cvt_pk_f32_fp8_sdwa v[110:111], v201 src0_sel:WORD_1
	v_pk_fma_f32 v[112:113], v[108:109], v[226:227], v[112:113]
	v_pk_fma_f32 v[114:115], v[110:111], v[228:229], v[114:115]
	v_lshl_add_u32 v8, v8, 3, v230
	v_pk_add_f32 v[112:113], v[112:113], v[114:115]
	global_load_dwordx4 v[198:201], v8, s[98:99]
	v_add_f32_e32 v120, v112, v113
	s_add_i32 s27, s26, 2
	s_and_b32 s27, s27, 7
	s_lshl_b32 s27, s27, 6
	v_add_u32_e32 v254, s27, v133
	v_and_b32_e32 v9, 0xffffff80, v5
	s_waitcnt vmcnt(15)
; __device__ void phase_gather(const P& p, int vb, int nvb, char* smem) {
;     ...
;     for (int b0 = 0; b0 < 128; b0 += 8) {
;       float dp[8];
; #pragma unroll
;       for (int u = 0; u < 8; u++) {
;         const uint32_t key = mykl[b0 + u];
;         const int e = (int)(key >> 7);
;         const uint4* up = (const uint4*)(U + (size_t)e * 1024 + 16 * j);
;         uint4 uu[4];
; #pragma unroll
;         for (int i = 0; i < 4; i++) uu[i] = up[i * 16];
;         f32x2 d2 = f32x2{0.f, 0.f};
; #pragma unroll
;         for (int i = 0; i < 4; i++) {
;           const uint32_t w[4] = {uu[i].x, uu[i].y, uu[i].z, uu[i].w};
; #pragma unroll
;           for (int q = 0; q < 4; q++) {
;             d2 += __builtin_amdgcn_cvt_pk_f32_fp8((int)w[q], false) * xf[i * 8 + q * 2 + 0];
;             d2 += __builtin_amdgcn_cvt_pk_f32_fp8((int)w[q], true) * xf[i * 8 + q * 2 + 1];
;           }
;         }
;         dp[u] = d2.x + d2.y;
;       }
;       const bool h8 = (j & 8) != 0, h4 = (j & 4) != 0, h2b = (j & 2) != 0;
;       float q4[4], q2[2];
; #pragma unroll
;       for (int k = 0; k < 4; k++) { const float snd = h8 ? dp[k] : dp[k + 4], kp = h8 ? dp[k + 4] : dp[k]; q4[k] = kp + __shfl_xor(snd, 8); }
; #pragma unroll
;       for (int k = 0; k < 2; k++) { const float snd = h4 ? q4[k] : q4[k + 2], kp = h4 ? q4[k + 2] : q4[k]; q2[k] = kp + __shfl_xor(snd, 4); }
;       const float snd1 = h2b ? q2[0] : q2[1], kp1 = h2b ? q2[1] : q2[0];
;       float q1 = kp1 + __shfl_xor(snd1, 2);
;       q1 += __shfl_xor(q1, 1);
;       if ((j & 1) == 0) mywl[b0 + (j >> 1)] = q1;
	v_cvt_pk_f32_fp8_e32 v[104:105], v202
	v_cvt_pk_f32_fp8_sdwa v[106:107], v202 src0_sel:WORD_1
	v_pk_mul_f32 v[112:113], v[104:105], v[214:215]
	v_pk_mul_f32 v[114:115], v[106:107], v[216:217]
	v_cvt_pk_f32_fp8_e32 v[108:109], v203
	v_cvt_pk_f32_fp8_sdwa v[110:111], v203 src0_sel:WORD_1
	v_pk_fma_f32 v[112:113], v[108:109], v[218:219], v[112:113]
	v_pk_fma_f32 v[114:115], v[110:111], v[220:221], v[114:115]
	v_cvt_pk_f32_fp8_e32 v[104:105], v204
	v_cvt_pk_f32_fp8_sdwa v[106:107], v204 src0_sel:WORD_1
	v_pk_fma_f32 v[112:113], v[104:105], v[222:223], v[112:113]
	v_pk_fma_f32 v[114:115], v[106:107], v[224:225], v[114:115]
	v_cvt_pk_f32_fp8_e32 v[108:109], v205
	v_cvt_pk_f32_fp8_sdwa v[110:111], v205 src0_sel:WORD_1
	v_pk_fma_f32 v[112:113], v[108:109], v[226:227], v[112:113]
	v_pk_fma_f32 v[114:115], v[110:111], v[228:229], v[114:115]
	v_lshl_add_u32 v9, v9, 3, v230
	v_pk_add_f32 v[112:113], v[112:113], v[114:115]
	global_load_dwordx4 v[202:205], v9, s[98:99]
	v_add_f32_e32 v121, v112, v113
	ds_read_b128 v[0:3], v254
	v_and_b32_e32 v8, 0xffffff80, v6
	s_waitcnt vmcnt(15)
	v_cvt_pk_f32_fp8_e32 v[104:105], v206
	v_cvt_pk_f32_fp8_sdwa v[106:107], v206 src0_sel:WORD_1
	v_pk_mul_f32 v[112:113], v[104:105], v[214:215]
	v_pk_mul_f32 v[114:115], v[106:107], v[216:217]
	v_cvt_pk_f32_fp8_e32 v[108:109], v207
	v_cvt_pk_f32_fp8_sdwa v[110:111], v207 src0_sel:WORD_1
	v_pk_fma_f32 v[112:113], v[108:109], v[218:219], v[112:113]
	v_pk_fma_f32 v[114:115], v[110:111], v[220:221], v[114:115]
	v_cvt_pk_f32_fp8_e32 v[104:105], v208
	v_cvt_pk_f32_fp8_sdwa v[106:107], v208 src0_sel:WORD_1
	v_pk_fma_f32 v[112:113], v[104:105], v[222:223], v[112:113]
	v_pk_fma_f32 v[114:115], v[106:107], v[224:225], v[114:115]
	v_cvt_pk_f32_fp8_e32 v[108:109], v209
	v_cvt_pk_f32_fp8_sdwa v[110:111], v209 src0_sel:WORD_1
	v_pk_fma_f32 v[112:113], v[108:109], v[226:227], v[112:113]
	v_pk_fma_f32 v[114:115], v[110:111], v[228:229], v[114:115]
	v_lshl_add_u32 v8, v8, 3, v230
	v_pk_add_f32 v[112:113], v[112:113], v[114:115]
	global_load_dwordx4 v[206:209], v8, s[98:99]
	v_add_f32_e32 v122, v112, v113
	v_and_b32_e32 v9, 0xffffff80, v7
	s_waitcnt vmcnt(15)
	v_cvt_pk_f32_fp8_e32 v[104:105], v210
	v_cvt_pk_f32_fp8_sdwa v[106:107], v210 src0_sel:WORD_1
	v_pk_mul_f32 v[112:113], v[104:105], v[214:215]
	v_pk_mul_f32 v[114:115], v[106:107], v[216:217]
	v_cvt_pk_f32_fp8_e32 v[108:109], v211
	v_cvt_pk_f32_fp8_sdwa v[110:111], v211 src0_sel:WORD_1
	v_pk_fma_f32 v[112:113], v[108:109], v[218:219], v[112:113]
	v_pk_fma_f32 v[114:115], v[110:111], v[220:221], v[114:115]
	v_cvt_pk_f32_fp8_e32 v[104:105], v212
	v_cvt_pk_f32_fp8_sdwa v[106:107], v212 src0_sel:WORD_1
	v_pk_fma_f32 v[112:113], v[104:105], v[222:223], v[112:113]
	v_pk_fma_f32 v[114:115], v[106:107], v[224:225], v[114:115]
	v_cvt_pk_f32_fp8_e32 v[108:109], v213
	v_cvt_pk_f32_fp8_sdwa v[110:111], v213 src0_sel:WORD_1
	v_pk_fma_f32 v[112:113], v[108:109], v[226:227], v[112:113]
	v_pk_fma_f32 v[114:115], v[110:111], v[228:229], v[114:115]
	v_lshl_add_u32 v9, v9, 3, v230
	v_pk_add_f32 v[112:113], v[112:113], v[114:115]
	global_load_dwordx4 v[210:213], v9, s[98:99]
	v_add_f32_e32 v123, v112, v113
	v_add_f32_dpp v10, v116, v116 row_ror:8 row_mask:0xf bank_mask:0x3
	v_add_f32_dpp v11, v117, v117 row_ror:8 row_mask:0xf bank_mask:0x3
	v_add_f32_dpp v12, v118, v118 row_ror:8 row_mask:0xf bank_mask:0x3
	v_add_f32_dpp v124, v119, v119 row_ror:8 row_mask:0xf bank_mask:0x3
	v_add_f32_dpp v10, v120, v120 row_ror:8 row_mask:0xf bank_mask:0xc
	v_add_f32_dpp v11, v121, v121 row_ror:8 row_mask:0xf bank_mask:0xc
	v_add_f32_dpp v12, v122, v122 row_ror:8 row_mask:0xf bank_mask:0xc
	v_add_f32_dpp v124, v123, v123 row_ror:8 row_mask:0xf bank_mask:0xc
	s_nop 0
	v_add_f32_dpp v125, v10, v10 row_shl:4 row_mask:0xf bank_mask:0x5
	v_add_f32_dpp v246, v11, v11 row_shl:4 row_mask:0xf bank_mask:0x5
	v_add_f32_dpp v125, v12, v12 row_shr:4 row_mask:0xf bank_mask:0xa
	v_add_f32_dpp v246, v124, v124 row_shr:4 row_mask:0xf bank_mask:0xa
	s_nop 1
	v_add_f32_dpp v247, v125, v125 quad_perm:[2,3,0,1] row_mask:0xf bank_mask:0xf
	v_add_f32_dpp v249, v246, v246 quad_perm:[2,3,0,1] row_mask:0xf bank_mask:0xf
	s_nop 0
	v_cndmask_b32_e64 v252, v249, v247, s[2:3]
	s_nop 1
	v_add_f32_dpp v253, v252, v252 quad_perm:[1,0,3,2] row_mask:0xf bank_mask:0xf
	s_and_saveexec_b64 s[20:21], s[4:5]
	ds_add_f32 v251, v253 offset:2080
	s_mov_b64 exec, s[20:21]
	s_add_i32 s26, s26, 1
	s_add_i32 s27, s26, 1
	s_lshr_b32 s27, s27, 3
	s_add_i32 s27, s27, s83
	s_and_b32 s27, s27, 3
	s_lshl_b32 s27, s27, 8
	v_add_u32_e32 v230, s27, v250
	s_and_b32 s27, s26, 7
	s_lshl_b32 s27, s27, 6
	v_add_u32_e32 v251, s27, v231
	s_branch .Lgu_iter

; DEVI float gelu_exact(float x) { return 0.5f * x * (1.f + erff(x * 0.70710678118654752f)); }
; __device__ void phase_gather(const P& p, int vb, int nvb, char* smem) {
;     ...
;     for (int m = 0; m < 8; m++) {
;       const int bb = j + 16 * m;
;       const float d = mywl[bb] * (1.f / USCALE);
;       mywl[bb] = gpre[m] * gelu_exact(d) * (1.f / VSCALE);
;     }
;     asm volatile("s_waitcnt lgkmcnt(0)" ::: "memory");
;     f32x2 acc[32];
; #pragma unroll
;     for (int i = 0; i < 32; i++) acc[i] = f32x2{0.f, 0.f};
; #pragma unroll 8
;     for (int bb = 0; bb < 128; bb++) {
;       const uint32_t key = mykl[bb];
;       const int e = (int)(key >> 7);
;       const float wgt = mywl[bb];
;       const uint4* vp = (const uint4*)(V + (size_t)e * 1024 + 16 * j);
;       uint4 vv[4];
; #pragma unroll
;       for (int i = 0; i < 4; i++) vv[i] = vp[i * 16];
.LBB0_530:
	s_andn2_saveexec_b64 s[20:21], s[26:27]
	v_mul_f32_e32 v2, v1, v1
	v_fmamk_f32 v3, v2, 0xba1345e1, v145
	v_fmaak_f32 v3, v2, v3, 0xbcdac9b8
	v_fmaak_f32 v3, v2, v3, 0x3de703be
	v_fmaak_f32 v3, v2, v3, 0xbec09330
	v_fmaak_f32 v2, v2, v3, 0x3e0375d0
	v_fma_f32 v2, |v1|, v2, |v1|
	s_or_b64 exec, exec, s[20:21]
	v_bfi_b32 v1, s41, v2, v1
	v_mul_f32_e32 v0, 0.5, v0
	v_add_f32_e32 v1, 1.0, v1
	v_mul_f32_e32 v0, v0, v1
	v_mul_f32_e32 v0, v96, v0
	v_mul_f32_e32 v0, 0x3c800000, v0
	ds_write_b32 v144, v0 offset:2496
	s_waitcnt lgkmcnt(0)
	v_mov_b32_e32 v32, 0
	s_mov_b32 s20, 0
	v_mov_b32_e32 v33, v32
	v_mov_b32_e32 v34, v32
	v_mov_b32_e32 v35, v32
	v_mov_b32_e32 v36, v32
	v_mov_b32_e32 v37, v32
	v_mov_b32_e32 v38, v32
	v_mov_b32_e32 v39, v32
	v_mov_b32_e32 v40, v32
	v_mov_b32_e32 v41, v32
	v_mov_b32_e32 v42, v32
	v_mov_b32_e32 v43, v32
	v_mov_b32_e32 v44, v32
	v_mov_b32_e32 v45, v32
	v_mov_b32_e32 v46, v32
	v_mov_b32_e32 v47, v32
	v_mov_b32_e32 v48, v32
	v_mov_b32_e32 v49, v32
	v_mov_b32_e32 v50, v32
	v_mov_b32_e32 v51, v32
	v_mov_b32_e32 v52, v32
	v_mov_b32_e32 v53, v32
	v_mov_b32_e32 v54, v32
	v_mov_b32_e32 v55, v32
	v_mov_b32_e32 v56, v32
	v_mov_b32_e32 v57, v32
	v_mov_b32_e32 v58, v32
	v_mov_b32_e32 v59, v32
	v_mov_b32_e32 v60, v32
	v_mov_b32_e32 v61, v32
	v_mov_b32_e32 v64, v32
	v_mov_b32_e32 v65, v32
	v_mov_b32_e32 v62, v32
	v_mov_b32_e32 v63, v32
	v_mov_b32_e32 v66, v32
	v_mov_b32_e32 v67, v32
	v_mov_b32_e32 v68, v32
	v_mov_b32_e32 v69, v32
	v_mov_b32_e32 v70, v32
	v_mov_b32_e32 v71, v32
	v_mov_b32_e32 v72, v32
	v_mov_b32_e32 v73, v32
	v_mov_b32_e32 v74, v32
	v_mov_b32_e32 v75, v32
	v_mov_b32_e32 v76, v32
	v_mov_b32_e32 v77, v32
	v_mov_b32_e32 v78, v32
	v_mov_b32_e32 v79, v32
	v_mov_b32_e32 v80, v32
	v_mov_b32_e32 v81, v32
	v_mov_b32_e32 v82, v32
	v_mov_b32_e32 v83, v32
	v_mov_b32_e32 v84, v32
	v_mov_b32_e32 v85, v32
	v_mov_b32_e32 v86, v32
	v_mov_b32_e32 v87, v32
	v_mov_b32_e32 v88, v32
	v_mov_b32_e32 v89, v32
	v_mov_b32_e32 v90, v32
	v_mov_b32_e32 v91, v32
	v_mov_b32_e32 v92, v32
	v_mov_b32_e32 v93, v32
	v_mov_b32_e32 v94, v32
	v_mov_b32_e32 v95, v32
	v_lshlrev_b32_e32 v250, 1, v132
	s_lshl_b32 s27, s83, 8
	v_add_u32_e32 v230, s27, v250
	ds_read_b128 v[0:3], v133
	ds_read_b128 v[4:7], v133 offset:16
	v_add_u32_e32 v254, 64, v133
	v_mov_b32_e32 v255, v133
	s_mov_b32 s20, 0
	v_mov_b32_e32 v214, 0
	v_mov_b32_e32 v215, 0
	v_mov_b32_e32 v216, 0
	v_mov_b32_e32 v217, 0
	v_mov_b32_e32 v218, 0
	v_mov_b32_e32 v219, 0
	v_mov_b32_e32 v220, 0
	v_mov_b32_e32 v221, 0
	v_mov_b32_e32 v222, 0
	v_mov_b32_e32 v223, 0
	v_mov_b32_e32 v224, 0
	v_mov_b32_e32 v225, 0
	v_mov_b32_e32 v226, 0
	v_mov_b32_e32 v227, 0
	v_mov_b32_e32 v228, 0
	v_mov_b32_e32 v229, 0
	s_waitcnt lgkmcnt(0)
	v_and_b32_e32 v8, 0xffffff80, v0
	v_lshl_add_u32 v8, v8, 3, v230
	global_load_dwordx4 v[150:153], v8, s[100:101]
	v_and_b32_e32 v9, 0xffffff80, v1
	v_lshl_add_u32 v9, v9, 3, v230
	global_load_dwordx4 v[154:157], v9, s[100:101]
	v_and_b32_e32 v8, 0xffffff80, v2
	v_lshl_add_u32 v8, v8, 3, v230
	global_load_dwordx4 v[158:161], v8, s[100:101]
	v_and_b32_e32 v9, 0xffffff80, v3
	v_lshl_add_u32 v9, v9, 3, v230
	global_load_dwordx4 v[162:165], v9, s[100:101]
	v_and_b32_e32 v8, 0xffffff80, v4
	v_lshl_add_u32 v8, v8, 3, v230
	global_load_dwordx4 v[166:169], v8, s[100:101]
	v_and_b32_e32 v9, 0xffffff80, v5
	v_lshl_add_u32 v9, v9, 3, v230
	global_load_dwordx4 v[170:173], v9, s[100:101]
	v_and_b32_e32 v8, 0xffffff80, v6
	v_lshl_add_u32 v8, v8, 3, v230
	global_load_dwordx4 v[174:177], v8, s[100:101]
	v_and_b32_e32 v9, 0xffffff80, v7
	v_lshl_add_u32 v9, v9, 3, v230
	global_load_dwordx4 v[178:181], v9, s[100:101]
	ds_read_b128 v[0:3], v133 offset:32
	ds_read_b128 v[4:7], v133 offset:48
	s_waitcnt lgkmcnt(0)
	v_and_b32_e32 v8, 0xffffff80, v0
	v_lshl_add_u32 v8, v8, 3, v230
	global_load_dwordx4 v[182:185], v8, s[100:101]
	v_and_b32_e32 v9, 0xffffff80, v1
	v_lshl_add_u32 v9, v9, 3, v230
	global_load_dwordx4 v[186:189], v9, s[100:101]
	v_and_b32_e32 v8, 0xffffff80, v2
	v_lshl_add_u32 v8, v8, 3, v230
	global_load_dwordx4 v[190:193], v8, s[100:101]
	v_and_b32_e32 v9, 0xffffff80, v3
	v_lshl_add_u32 v9, v9, 3, v230
	global_load_dwordx4 v[194:197], v9, s[100:101]
	v_and_b32_e32 v8, 0xffffff80, v4
	v_lshl_add_u32 v8, v8, 3, v230
	global_load_dwordx4 v[198:201], v8, s[100:101]
	v_and_b32_e32 v9, 0xffffff80, v5
	v_lshl_add_u32 v9, v9, 3, v230
	global_load_dwordx4 v[202:205], v9, s[100:101]
	v_and_b32_e32 v8, 0xffffff80, v6
	v_lshl_add_u32 v8, v8, 3, v230
	global_load_dwordx4 v[206:209], v8, s[100:101]
	v_and_b32_e32 v9, 0xffffff80, v7
	v_lshl_add_u32 v9, v9, 3, v230
	global_load_dwordx4 v[210:213], v9, s[100:101]
	ds_read_b128 v[0:3], v133 offset:64
	ds_read_b128 v[96:99], v133 offset:2048
; __device__ void phase_gather(const P& p, int vb, int nvb, char* smem) {
;     ...
;     for (int bb = 0; bb < 128; bb++) {
;       const uint32_t key = mykl[bb];
;       const int e = (int)(key >> 7);
;       const float wgt = mywl[bb];
;       const uint4* vp = (const uint4*)(V + (size_t)e * 1024 + 16 * j);
;       uint4 vv[4];
; #pragma unroll
;       for (int i = 0; i < 4; i++) vv[i] = vp[i * 16];
;       const f32x2 w2 = f32x2{wgt, wgt};
; #pragma unroll
;       for (int i = 0; i < 4; i++) {
;         const uint32_t w[4] = {vv[i].x, vv[i].y, vv[i].z, vv[i].w};
; #pragma unroll
;         for (int q = 0; q < 4; q++) {
;           acc[i * 8 + q * 2 + 0] += w2 * __builtin_amdgcn_cvt_pk_f32_fp8((int)w[q], false);
;           acc[i * 8 + q * 2 + 1] += w2 * __builtin_amdgcn_cvt_pk_f32_fp8((int)w[q], true);
;         }
;       }
;     }
.Lgv_body:
	s_cmp_eq_u32 s20, 31
	s_cbranch_scc1 .Lgv_last
	s_waitcnt lgkmcnt(0)
	v_and_b32_e32 v8, 0xffffff80, v0
	v_lshl_add_u32 v8, v8, 3, v230
	s_waitcnt vmcnt(15)
	v_cvt_pk_f32_fp8_e32 v[104:105], v150
	v_cvt_pk_f32_fp8_sdwa v[106:107], v150 src0_sel:WORD_1
	v_pk_fma_f32 v[214:215], v[96:97], v[104:105], v[214:215] op_sel_hi:[0,1,1]
	v_pk_fma_f32 v[216:217], v[96:97], v[106:107], v[216:217] op_sel_hi:[0,1,1]
	v_cvt_pk_f32_fp8_e32 v[108:109], v151
	v_cvt_pk_f32_fp8_sdwa v[110:111], v151 src0_sel:WORD_1
	v_pk_fma_f32 v[218:219], v[96:97], v[108:109], v[218:219] op_sel_hi:[0,1,1]
	v_pk_fma_f32 v[220:221], v[96:97], v[110:111], v[220:221] op_sel_hi:[0,1,1]
	v_cvt_pk_f32_fp8_e32 v[104:105], v152
	v_cvt_pk_f32_fp8_sdwa v[106:107], v152 src0_sel:WORD_1
	v_pk_fma_f32 v[222:223], v[96:97], v[104:105], v[222:223] op_sel_hi:[0,1,1]
	v_pk_fma_f32 v[224:225], v[96:97], v[106:107], v[224:225] op_sel_hi:[0,1,1]
	v_cvt_pk_f32_fp8_e32 v[108:109], v153
	v_cvt_pk_f32_fp8_sdwa v[110:111], v153 src0_sel:WORD_1
	v_pk_fma_f32 v[226:227], v[96:97], v[108:109], v[226:227] op_sel_hi:[0,1,1]
	v_pk_fma_f32 v[228:229], v[96:97], v[110:111], v[228:229] op_sel_hi:[0,1,1]
	global_load_dwordx4 v[150:153], v8, s[100:101]
	v_and_b32_e32 v9, 0xffffff80, v1
	v_lshl_add_u32 v9, v9, 3, v230
	s_waitcnt vmcnt(15)
	v_cvt_pk_f32_fp8_e32 v[104:105], v154
	v_cvt_pk_f32_fp8_sdwa v[106:107], v154 src0_sel:WORD_1
	v_pk_fma_f32 v[214:215], v[96:97], v[104:105], v[214:215] op_sel:[1,0,0]
	v_pk_fma_f32 v[216:217], v[96:97], v[106:107], v[216:217] op_sel:[1,0,0]
	v_cvt_pk_f32_fp8_e32 v[108:109], v155
	v_cvt_pk_f32_fp8_sdwa v[110:111], v155 src0_sel:WORD_1
	v_pk_fma_f32 v[218:219], v[96:97], v[108:109], v[218:219] op_sel:[1,0,0]
	v_pk_fma_f32 v[220:221], v[96:97], v[110:111], v[220:221] op_sel:[1,0,0]
	v_cvt_pk_f32_fp8_e32 v[104:105], v156
	v_cvt_pk_f32_fp8_sdwa v[106:107], v156 src0_sel:WORD_1
	v_pk_fma_f32 v[222:223], v[96:97], v[104:105], v[222:223] op_sel:[1,0,0]
	v_pk_fma_f32 v[224:225], v[96:97], v[106:107], v[224:225] op_sel:[1,0,0]
	v_cvt_pk_f32_fp8_e32 v[108:109], v157
	v_cvt_pk_f32_fp8_sdwa v[110:111], v157 src0_sel:WORD_1
	v_pk_fma_f32 v[226:227], v[96:97], v[108:109], v[226:227] op_sel:[1,0,0]
	v_pk_fma_f32 v[228:229], v[96:97], v[110:111], v[228:229] op_sel:[1,0,0]
	global_load_dwordx4 v[154:157], v9, s[100:101]
	ds_read_b128 v[4:7], v254 offset:16
	ds_read_b128 v[100:103], v255 offset:2064
	v_and_b32_e32 v8, 0xffffff80, v2
	v_lshl_add_u32 v8, v8, 3, v230
	s_waitcnt vmcnt(15)
	v_cvt_pk_f32_fp8_e32 v[104:105], v158
	v_cvt_pk_f32_fp8_sdwa v[106:107], v158 src0_sel:WORD_1
	v_pk_fma_f32 v[214:215], v[98:99], v[104:105], v[214:215] op_sel_hi:[0,1,1]
	v_pk_fma_f32 v[216:217], v[98:99], v[106:107], v[216:217] op_sel_hi:[0,1,1]
	v_cvt_pk_f32_fp8_e32 v[108:109], v159
	v_cvt_pk_f32_fp8_sdwa v[110:111], v159 src0_sel:WORD_1
	v_pk_fma_f32 v[218:219], v[98:99], v[108:109], v[218:219] op_sel_hi:[0,1,1]
	v_pk_fma_f32 v[220:221], v[98:99], v[110:111], v[220:221] op_sel_hi:[0,1,1]
	v_cvt_pk_f32_fp8_e32 v[104:105], v160
	v_cvt_pk_f32_fp8_sdwa v[106:107], v160 src0_sel:WORD_1
	v_pk_fma_f32 v[222:223], v[98:99], v[104:105], v[222:223] op_sel_hi:[0,1,1]
	v_pk_fma_f32 v[224:225], v[98:99], v[106:107], v[224:225] op_sel_hi:[0,1,1]
	v_cvt_pk_f32_fp8_e32 v[108:109], v161
	v_cvt_pk_f32_fp8_sdwa v[110:111], v161 src0_sel:WORD_1
	v_pk_fma_f32 v[226:227], v[98:99], v[108:109], v[226:227] op_sel_hi:[0,1,1]
	v_pk_fma_f32 v[228:229], v[98:99], v[110:111], v[228:229] op_sel_hi:[0,1,1]
	global_load_dwordx4 v[158:161], v8, s[100:101]
	v_and_b32_e32 v9, 0xffffff80, v3
	v_lshl_add_u32 v9, v9, 3, v230
	s_waitcnt vmcnt(15)
	v_cvt_pk_f32_fp8_e32 v[104:105], v162
	v_cvt_pk_f32_fp8_sdwa v[106:107], v162 src0_sel:WORD_1
	v_pk_fma_f32 v[214:215], v[98:99], v[104:105], v[214:215] op_sel:[1,0,0]
	v_pk_fma_f32 v[216:217], v[98:99], v[106:107], v[216:217] op_sel:[1,0,0]
	v_cvt_pk_f32_fp8_e32 v[108:109], v163
	v_cvt_pk_f32_fp8_sdwa v[110:111], v163 src0_sel:WORD_1
	v_pk_fma_f32 v[218:219], v[98:99], v[108:109], v[218:219] op_sel:[1,0,0]
	v_pk_fma_f32 v[220:221], v[98:99], v[110:111], v[220:221] op_sel:[1,0,0]
	v_cvt_pk_f32_fp8_e32 v[104:105], v164
	v_cvt_pk_f32_fp8_sdwa v[106:107], v164 src0_sel:WORD_1
	v_pk_fma_f32 v[222:223], v[98:99], v[104:105], v[222:223] op_sel:[1,0,0]
	v_pk_fma_f32 v[224:225], v[98:99], v[106:107], v[224:225] op_sel:[1,0,0]
	v_cvt_pk_f32_fp8_e32 v[108:109], v165
	v_cvt_pk_f32_fp8_sdwa v[110:111], v165 src0_sel:WORD_1
	v_pk_fma_f32 v[226:227], v[98:99], v[108:109], v[226:227] op_sel:[1,0,0]
	v_pk_fma_f32 v[228:229], v[98:99], v[110:111], v[228:229] op_sel:[1,0,0]
	global_load_dwordx4 v[162:165], v9, s[100:101]
	s_waitcnt lgkmcnt(0)
	v_and_b32_e32 v8, 0xffffff80, v4
	v_lshl_add_u32 v8, v8, 3, v230
	s_waitcnt vmcnt(15)
	v_cvt_pk_f32_fp8_e32 v[104:105], v166
	v_cvt_pk_f32_fp8_sdwa v[106:107], v166 src0_sel:WORD_1
	v_pk_fma_f32 v[214:215], v[100:101], v[104:105], v[214:215] op_sel_hi:[0,1,1]
	v_pk_fma_f32 v[216:217], v[100:101], v[106:107], v[216:217] op_sel_hi:[0,1,1]
	v_cvt_pk_f32_fp8_e32 v[108:109], v167
	v_cvt_pk_f32_fp8_sdwa v[110:111], v167 src0_sel:WORD_1
	v_pk_fma_f32 v[218:219], v[100:101], v[108:109], v[218:219] op_sel_hi:[0,1,1]
	v_pk_fma_f32 v[220:221], v[100:101], v[110:111], v[220:221] op_sel_hi:[0,1,1]
	v_cvt_pk_f32_fp8_e32 v[104:105], v168
	v_cvt_pk_f32_fp8_sdwa v[106:107], v168 src0_sel:WORD_1
	v_pk_fma_f32 v[222:223], v[100:101], v[104:105], v[222:223] op_sel_hi:[0,1,1]
	v_pk_fma_f32 v[224:225], v[100:101], v[106:107], v[224:225] op_sel_hi:[0,1,1]
	v_cvt_pk_f32_fp8_e32 v[108:109], v169
	v_cvt_pk_f32_fp8_sdwa v[110:111], v169 src0_sel:WORD_1
	v_pk_fma_f32 v[226:227], v[100:101], v[108:109], v[226:227] op_sel_hi:[0,1,1]
	v_pk_fma_f32 v[228:229], v[100:101], v[110:111], v[228:229] op_sel_hi:[0,1,1]
	global_load_dwordx4 v[166:169], v8, s[100:101]
	v_and_b32_e32 v9, 0xffffff80, v5
	v_lshl_add_u32 v9, v9, 3, v230
	s_waitcnt vmcnt(15)
; __device__ void phase_gather(const P& p, int vb, int nvb, char* smem) {
;     ...
;     for (int bb = 0; bb < 128; bb++) {
;       const uint32_t key = mykl[bb];
;       const int e = (int)(key >> 7);
;       const float wgt = mywl[bb];
;       const uint4* vp = (const uint4*)(V + (size_t)e * 1024 + 16 * j);
;       uint4 vv[4];
; #pragma unroll
;       for (int i = 0; i < 4; i++) vv[i] = vp[i * 16];
;       const f32x2 w2 = f32x2{wgt, wgt};
; #pragma unroll
;       for (int i = 0; i < 4; i++) {
;         const uint32_t w[4] = {vv[i].x, vv[i].y, vv[i].z, vv[i].w};
; #pragma unroll
;         for (int q = 0; q < 4; q++) {
;           acc[i * 8 + q * 2 + 0] += w2 * __builtin_amdgcn_cvt_pk_f32_fp8((int)w[q], false);
;           acc[i * 8 + q * 2 + 1] += w2 * __builtin_amdgcn_cvt_pk_f32_fp8((int)w[q], true);
;         }
;       }
;     }
	v_cvt_pk_f32_fp8_e32 v[104:105], v170
	v_cvt_pk_f32_fp8_sdwa v[106:107], v170 src0_sel:WORD_1
	v_pk_fma_f32 v[214:215], v[100:101], v[104:105], v[214:215] op_sel:[1,0,0]
	v_pk_fma_f32 v[216:217], v[100:101], v[106:107], v[216:217] op_sel:[1,0,0]
	v_cvt_pk_f32_fp8_e32 v[108:109], v171
	v_cvt_pk_f32_fp8_sdwa v[110:111], v171 src0_sel:WORD_1
	v_pk_fma_f32 v[218:219], v[100:101], v[108:109], v[218:219] op_sel:[1,0,0]
	v_pk_fma_f32 v[220:221], v[100:101], v[110:111], v[220:221] op_sel:[1,0,0]
	v_cvt_pk_f32_fp8_e32 v[104:105], v172
	v_cvt_pk_f32_fp8_sdwa v[106:107], v172 src0_sel:WORD_1
	v_pk_fma_f32 v[222:223], v[100:101], v[104:105], v[222:223] op_sel:[1,0,0]
	v_pk_fma_f32 v[224:225], v[100:101], v[106:107], v[224:225] op_sel:[1,0,0]
	v_cvt_pk_f32_fp8_e32 v[108:109], v173
	v_cvt_pk_f32_fp8_sdwa v[110:111], v173 src0_sel:WORD_1
	v_pk_fma_f32 v[226:227], v[100:101], v[108:109], v[226:227] op_sel:[1,0,0]
	v_pk_fma_f32 v[228:229], v[100:101], v[110:111], v[228:229] op_sel:[1,0,0]
	global_load_dwordx4 v[170:173], v9, s[100:101]
	ds_read_b128 v[0:3], v254 offset:32
	ds_read_b128 v[96:99], v255 offset:2080
	v_and_b32_e32 v8, 0xffffff80, v6
	v_lshl_add_u32 v8, v8, 3, v230
	s_waitcnt vmcnt(15)
	v_cvt_pk_f32_fp8_e32 v[104:105], v174
	v_cvt_pk_f32_fp8_sdwa v[106:107], v174 src0_sel:WORD_1
	v_pk_fma_f32 v[214:215], v[102:103], v[104:105], v[214:215] op_sel_hi:[0,1,1]
	v_pk_fma_f32 v[216:217], v[102:103], v[106:107], v[216:217] op_sel_hi:[0,1,1]
	v_cvt_pk_f32_fp8_e32 v[108:109], v175
	v_cvt_pk_f32_fp8_sdwa v[110:111], v175 src0_sel:WORD_1
	v_pk_fma_f32 v[218:219], v[102:103], v[108:109], v[218:219] op_sel_hi:[0,1,1]
	v_pk_fma_f32 v[220:221], v[102:103], v[110:111], v[220:221] op_sel_hi:[0,1,1]
	v_cvt_pk_f32_fp8_e32 v[104:105], v176
	v_cvt_pk_f32_fp8_sdwa v[106:107], v176 src0_sel:WORD_1
	v_pk_fma_f32 v[222:223], v[102:103], v[104:105], v[222:223] op_sel_hi:[0,1,1]
	v_pk_fma_f32 v[224:225], v[102:103], v[106:107], v[224:225] op_sel_hi:[0,1,1]
	v_cvt_pk_f32_fp8_e32 v[108:109], v177
	v_cvt_pk_f32_fp8_sdwa v[110:111], v177 src0_sel:WORD_1
	v_pk_fma_f32 v[226:227], v[102:103], v[108:109], v[226:227] op_sel_hi:[0,1,1]
	v_pk_fma_f32 v[228:229], v[102:103], v[110:111], v[228:229] op_sel_hi:[0,1,1]
	global_load_dwordx4 v[174:177], v8, s[100:101]
	v_and_b32_e32 v9, 0xffffff80, v7
	v_lshl_add_u32 v9, v9, 3, v230
	s_waitcnt vmcnt(15)
	v_cvt_pk_f32_fp8_e32 v[104:105], v178
	v_cvt_pk_f32_fp8_sdwa v[106:107], v178 src0_sel:WORD_1
	v_pk_fma_f32 v[214:215], v[102:103], v[104:105], v[214:215] op_sel:[1,0,0]
	v_pk_fma_f32 v[216:217], v[102:103], v[106:107], v[216:217] op_sel:[1,0,0]
	v_cvt_pk_f32_fp8_e32 v[108:109], v179
	v_cvt_pk_f32_fp8_sdwa v[110:111], v179 src0_sel:WORD_1
	v_pk_fma_f32 v[218:219], v[102:103], v[108:109], v[218:219] op_sel:[1,0,0]
	v_pk_fma_f32 v[220:221], v[102:103], v[110:111], v[220:221] op_sel:[1,0,0]
	v_cvt_pk_f32_fp8_e32 v[104:105], v180
	v_cvt_pk_f32_fp8_sdwa v[106:107], v180 src0_sel:WORD_1
	v_pk_fma_f32 v[222:223], v[102:103], v[104:105], v[222:223] op_sel:[1,0,0]
	v_pk_fma_f32 v[224:225], v[102:103], v[106:107], v[224:225] op_sel:[1,0,0]
	v_cvt_pk_f32_fp8_e32 v[108:109], v181
	v_cvt_pk_f32_fp8_sdwa v[110:111], v181 src0_sel:WORD_1
	v_pk_fma_f32 v[226:227], v[102:103], v[108:109], v[226:227] op_sel:[1,0,0]
	v_pk_fma_f32 v[228:229], v[102:103], v[110:111], v[228:229] op_sel:[1,0,0]
	global_load_dwordx4 v[178:181], v9, s[100:101]
	s_waitcnt lgkmcnt(0)
	v_and_b32_e32 v8, 0xffffff80, v0
	v_lshl_add_u32 v8, v8, 3, v230
	s_waitcnt vmcnt(15)
	v_cvt_pk_f32_fp8_e32 v[104:105], v182
	v_cvt_pk_f32_fp8_sdwa v[106:107], v182 src0_sel:WORD_1
	v_pk_fma_f32 v[214:215], v[96:97], v[104:105], v[214:215] op_sel_hi:[0,1,1]
	v_pk_fma_f32 v[216:217], v[96:97], v[106:107], v[216:217] op_sel_hi:[0,1,1]
	v_cvt_pk_f32_fp8_e32 v[108:109], v183
	v_cvt_pk_f32_fp8_sdwa v[110:111], v183 src0_sel:WORD_1
	v_pk_fma_f32 v[218:219], v[96:97], v[108:109], v[218:219] op_sel_hi:[0,1,1]
	v_pk_fma_f32 v[220:221], v[96:97], v[110:111], v[220:221] op_sel_hi:[0,1,1]
	v_cvt_pk_f32_fp8_e32 v[104:105], v184
	v_cvt_pk_f32_fp8_sdwa v[106:107], v184 src0_sel:WORD_1
	v_pk_fma_f32 v[222:223], v[96:97], v[104:105], v[222:223] op_sel_hi:[0,1,1]
	v_pk_fma_f32 v[224:225], v[96:97], v[106:107], v[224:225] op_sel_hi:[0,1,1]
	v_cvt_pk_f32_fp8_e32 v[108:109], v185
	v_cvt_pk_f32_fp8_sdwa v[110:111], v185 src0_sel:WORD_1
	v_pk_fma_f32 v[226:227], v[96:97], v[108:109], v[226:227] op_sel_hi:[0,1,1]
	v_pk_fma_f32 v[228:229], v[96:97], v[110:111], v[228:229] op_sel_hi:[0,1,1]
	global_load_dwordx4 v[182:185], v8, s[100:101]
	v_and_b32_e32 v9, 0xffffff80, v1
	v_lshl_add_u32 v9, v9, 3, v230
	s_waitcnt vmcnt(15)
	v_cvt_pk_f32_fp8_e32 v[104:105], v186
	v_cvt_pk_f32_fp8_sdwa v[106:107], v186 src0_sel:WORD_1
	v_pk_fma_f32 v[214:215], v[96:97], v[104:105], v[214:215] op_sel:[1,0,0]
	v_pk_fma_f32 v[216:217], v[96:97], v[106:107], v[216:217] op_sel:[1,0,0]
	v_cvt_pk_f32_fp8_e32 v[108:109], v187
	v_cvt_pk_f32_fp8_sdwa v[110:111], v187 src0_sel:WORD_1
	v_pk_fma_f32 v[218:219], v[96:97], v[108:109], v[218:219] op_sel:[1,0,0]
	v_pk_fma_f32 v[220:221], v[96:97], v[110:111], v[220:221] op_sel:[1,0,0]
	v_cvt_pk_f32_fp8_e32 v[104:105], v188
	v_cvt_pk_f32_fp8_sdwa v[106:107], v188 src0_sel:WORD_1
	v_pk_fma_f32 v[222:223], v[96:97], v[104:105], v[222:223] op_sel:[1,0,0]
	v_pk_fma_f32 v[224:225], v[96:97], v[106:107], v[224:225] op_sel:[1,0,0]
	v_cvt_pk_f32_fp8_e32 v[108:109], v189
	v_cvt_pk_f32_fp8_sdwa v[110:111], v189 src0_sel:WORD_1
	v_pk_fma_f32 v[226:227], v[96:97], v[108:109], v[226:227] op_sel:[1,0,0]
	v_pk_fma_f32 v[228:229], v[96:97], v[110:111], v[228:229] op_sel:[1,0,0]
	global_load_dwordx4 v[186:189], v9, s[100:101]
	ds_read_b128 v[4:7], v254 offset:48
	ds_read_b128 v[100:103], v255 offset:2096
	v_and_b32_e32 v8, 0xffffff80, v2
	v_lshl_add_u32 v8, v8, 3, v230
	s_waitcnt vmcnt(15)
; __device__ void phase_gather(const P& p, int vb, int nvb, char* smem) {
;     ...
;     for (int bb = 0; bb < 128; bb++) {
;       const uint32_t key = mykl[bb];
;       const int e = (int)(key >> 7);
;       const float wgt = mywl[bb];
;       const uint4* vp = (const uint4*)(V + (size_t)e * 1024 + 16 * j);
;       uint4 vv[4];
; #pragma unroll
;       for (int i = 0; i < 4; i++) vv[i] = vp[i * 16];
;       const f32x2 w2 = f32x2{wgt, wgt};
; #pragma unroll
;       for (int i = 0; i < 4; i++) {
;         const uint32_t w[4] = {vv[i].x, vv[i].y, vv[i].z, vv[i].w};
; #pragma unroll
;         for (int q = 0; q < 4; q++) {
;           acc[i * 8 + q * 2 + 0] += w2 * __builtin_amdgcn_cvt_pk_f32_fp8((int)w[q], false);
;           acc[i * 8 + q * 2 + 1] += w2 * __builtin_amdgcn_cvt_pk_f32_fp8((int)w[q], true);
;         }
;       }
;     }
	v_cvt_pk_f32_fp8_e32 v[104:105], v190
	v_cvt_pk_f32_fp8_sdwa v[106:107], v190 src0_sel:WORD_1
	v_pk_fma_f32 v[214:215], v[98:99], v[104:105], v[214:215] op_sel_hi:[0,1,1]
	v_pk_fma_f32 v[216:217], v[98:99], v[106:107], v[216:217] op_sel_hi:[0,1,1]
	v_cvt_pk_f32_fp8_e32 v[108:109], v191
	v_cvt_pk_f32_fp8_sdwa v[110:111], v191 src0_sel:WORD_1
	v_pk_fma_f32 v[218:219], v[98:99], v[108:109], v[218:219] op_sel_hi:[0,1,1]
	v_pk_fma_f32 v[220:221], v[98:99], v[110:111], v[220:221] op_sel_hi:[0,1,1]
	v_cvt_pk_f32_fp8_e32 v[104:105], v192
	v_cvt_pk_f32_fp8_sdwa v[106:107], v192 src0_sel:WORD_1
	v_pk_fma_f32 v[222:223], v[98:99], v[104:105], v[222:223] op_sel_hi:[0,1,1]
	v_pk_fma_f32 v[224:225], v[98:99], v[106:107], v[224:225] op_sel_hi:[0,1,1]
	v_cvt_pk_f32_fp8_e32 v[108:109], v193
	v_cvt_pk_f32_fp8_sdwa v[110:111], v193 src0_sel:WORD_1
	v_pk_fma_f32 v[226:227], v[98:99], v[108:109], v[226:227] op_sel_hi:[0,1,1]
	v_pk_fma_f32 v[228:229], v[98:99], v[110:111], v[228:229] op_sel_hi:[0,1,1]
	global_load_dwordx4 v[190:193], v8, s[100:101]
	v_and_b32_e32 v9, 0xffffff80, v3
	v_lshl_add_u32 v9, v9, 3, v230
	s_waitcnt vmcnt(15)
	v_cvt_pk_f32_fp8_e32 v[104:105], v194
	v_cvt_pk_f32_fp8_sdwa v[106:107], v194 src0_sel:WORD_1
	v_pk_fma_f32 v[214:215], v[98:99], v[104:105], v[214:215] op_sel:[1,0,0]
	v_pk_fma_f32 v[216:217], v[98:99], v[106:107], v[216:217] op_sel:[1,0,0]
	v_cvt_pk_f32_fp8_e32 v[108:109], v195
	v_cvt_pk_f32_fp8_sdwa v[110:111], v195 src0_sel:WORD_1
	v_pk_fma_f32 v[218:219], v[98:99], v[108:109], v[218:219] op_sel:[1,0,0]
	v_pk_fma_f32 v[220:221], v[98:99], v[110:111], v[220:221] op_sel:[1,0,0]
	v_cvt_pk_f32_fp8_e32 v[104:105], v196
	v_cvt_pk_f32_fp8_sdwa v[106:107], v196 src0_sel:WORD_1
	v_pk_fma_f32 v[222:223], v[98:99], v[104:105], v[222:223] op_sel:[1,0,0]
	v_pk_fma_f32 v[224:225], v[98:99], v[106:107], v[224:225] op_sel:[1,0,0]
	v_cvt_pk_f32_fp8_e32 v[108:109], v197
	v_cvt_pk_f32_fp8_sdwa v[110:111], v197 src0_sel:WORD_1
	v_pk_fma_f32 v[226:227], v[98:99], v[108:109], v[226:227] op_sel:[1,0,0]
	v_pk_fma_f32 v[228:229], v[98:99], v[110:111], v[228:229] op_sel:[1,0,0]
	global_load_dwordx4 v[194:197], v9, s[100:101]
	s_waitcnt lgkmcnt(0)
	v_and_b32_e32 v8, 0xffffff80, v4
	v_lshl_add_u32 v8, v8, 3, v230
	s_waitcnt vmcnt(15)
	v_cvt_pk_f32_fp8_e32 v[104:105], v198
	v_cvt_pk_f32_fp8_sdwa v[106:107], v198 src0_sel:WORD_1
	v_pk_fma_f32 v[214:215], v[100:101], v[104:105], v[214:215] op_sel_hi:[0,1,1]
	v_pk_fma_f32 v[216:217], v[100:101], v[106:107], v[216:217] op_sel_hi:[0,1,1]
	v_cvt_pk_f32_fp8_e32 v[108:109], v199
	v_cvt_pk_f32_fp8_sdwa v[110:111], v199 src0_sel:WORD_1
	v_pk_fma_f32 v[218:219], v[100:101], v[108:109], v[218:219] op_sel_hi:[0,1,1]
	v_pk_fma_f32 v[220:221], v[100:101], v[110:111], v[220:221] op_sel_hi:[0,1,1]
	v_cvt_pk_f32_fp8_e32 v[104:105], v200
	v_cvt_pk_f32_fp8_sdwa v[106:107], v200 src0_sel:WORD_1
	v_pk_fma_f32 v[222:223], v[100:101], v[104:105], v[222:223] op_sel_hi:[0,1,1]
	v_pk_fma_f32 v[224:225], v[100:101], v[106:107], v[224:225] op_sel_hi:[0,1,1]
	v_cvt_pk_f32_fp8_e32 v[108:109], v201
	v_cvt_pk_f32_fp8_sdwa v[110:111], v201 src0_sel:WORD_1
	v_pk_fma_f32 v[226:227], v[100:101], v[108:109], v[226:227] op_sel_hi:[0,1,1]
	v_pk_fma_f32 v[228:229], v[100:101], v[110:111], v[228:229] op_sel_hi:[0,1,1]
	global_load_dwordx4 v[198:201], v8, s[100:101]
	s_add_i32 s27, s20, 2
	s_and_b32 s27, s27, 7
	s_lshl_b32 s27, s27, 6
	v_add_u32_e32 v254, s27, v133
	s_add_i32 s27, s20, 1
	s_and_b32 s27, s27, 7
	s_lshl_b32 s27, s27, 6
	v_add_u32_e32 v255, s27, v133
	v_and_b32_e32 v9, 0xffffff80, v5
	v_lshl_add_u32 v9, v9, 3, v230
	s_waitcnt vmcnt(15)
; __device__ void phase_gather(const P& p, int vb, int nvb, char* smem) {
;     ...
;     for (int bb = 0; bb < 128; bb++) {
;       const uint32_t key = mykl[bb];
;       const int e = (int)(key >> 7);
;       const float wgt = mywl[bb];
;       const uint4* vp = (const uint4*)(V + (size_t)e * 1024 + 16 * j);
;       uint4 vv[4];
; #pragma unroll
;       for (int i = 0; i < 4; i++) vv[i] = vp[i * 16];
;       const f32x2 w2 = f32x2{wgt, wgt};
; #pragma unroll
;       for (int i = 0; i < 4; i++) {
;         const uint32_t w[4] = {vv[i].x, vv[i].y, vv[i].z, vv[i].w};
; #pragma unroll
;         for (int q = 0; q < 4; q++) {
;           acc[i * 8 + q * 2 + 0] += w2 * __builtin_amdgcn_cvt_pk_f32_fp8((int)w[q], false);
;           acc[i * 8 + q * 2 + 1] += w2 * __builtin_amdgcn_cvt_pk_f32_fp8((int)w[q], true);
;         }
;       }
;     }
	v_cvt_pk_f32_fp8_e32 v[104:105], v202
	v_cvt_pk_f32_fp8_sdwa v[106:107], v202 src0_sel:WORD_1
	v_pk_fma_f32 v[214:215], v[100:101], v[104:105], v[214:215] op_sel:[1,0,0]
	v_pk_fma_f32 v[216:217], v[100:101], v[106:107], v[216:217] op_sel:[1,0,0]
	v_cvt_pk_f32_fp8_e32 v[108:109], v203
	v_cvt_pk_f32_fp8_sdwa v[110:111], v203 src0_sel:WORD_1
	v_pk_fma_f32 v[218:219], v[100:101], v[108:109], v[218:219] op_sel:[1,0,0]
	v_pk_fma_f32 v[220:221], v[100:101], v[110:111], v[220:221] op_sel:[1,0,0]
	v_cvt_pk_f32_fp8_e32 v[104:105], v204
	v_cvt_pk_f32_fp8_sdwa v[106:107], v204 src0_sel:WORD_1
	v_pk_fma_f32 v[222:223], v[100:101], v[104:105], v[222:223] op_sel:[1,0,0]
	v_pk_fma_f32 v[224:225], v[100:101], v[106:107], v[224:225] op_sel:[1,0,0]
	v_cvt_pk_f32_fp8_e32 v[108:109], v205
	v_cvt_pk_f32_fp8_sdwa v[110:111], v205 src0_sel:WORD_1
	v_pk_fma_f32 v[226:227], v[100:101], v[108:109], v[226:227] op_sel:[1,0,0]
	v_pk_fma_f32 v[228:229], v[100:101], v[110:111], v[228:229] op_sel:[1,0,0]
	global_load_dwordx4 v[202:205], v9, s[100:101]
	ds_read_b128 v[0:3], v254
	ds_read_b128 v[96:99], v255 offset:2048
	v_and_b32_e32 v8, 0xffffff80, v6
	v_lshl_add_u32 v8, v8, 3, v230
	s_waitcnt vmcnt(15)
	v_cvt_pk_f32_fp8_e32 v[104:105], v206
	v_cvt_pk_f32_fp8_sdwa v[106:107], v206 src0_sel:WORD_1
	v_pk_fma_f32 v[214:215], v[102:103], v[104:105], v[214:215] op_sel_hi:[0,1,1]
	v_pk_fma_f32 v[216:217], v[102:103], v[106:107], v[216:217] op_sel_hi:[0,1,1]
	v_cvt_pk_f32_fp8_e32 v[108:109], v207
	v_cvt_pk_f32_fp8_sdwa v[110:111], v207 src0_sel:WORD_1
	v_pk_fma_f32 v[218:219], v[102:103], v[108:109], v[218:219] op_sel_hi:[0,1,1]
	v_pk_fma_f32 v[220:221], v[102:103], v[110:111], v[220:221] op_sel_hi:[0,1,1]
	v_cvt_pk_f32_fp8_e32 v[104:105], v208
	v_cvt_pk_f32_fp8_sdwa v[106:107], v208 src0_sel:WORD_1
	v_pk_fma_f32 v[222:223], v[102:103], v[104:105], v[222:223] op_sel_hi:[0,1,1]
	v_pk_fma_f32 v[224:225], v[102:103], v[106:107], v[224:225] op_sel_hi:[0,1,1]
	v_cvt_pk_f32_fp8_e32 v[108:109], v209
	v_cvt_pk_f32_fp8_sdwa v[110:111], v209 src0_sel:WORD_1
	v_pk_fma_f32 v[226:227], v[102:103], v[108:109], v[226:227] op_sel_hi:[0,1,1]
	v_pk_fma_f32 v[228:229], v[102:103], v[110:111], v[228:229] op_sel_hi:[0,1,1]
	global_load_dwordx4 v[206:209], v8, s[100:101]
	v_and_b32_e32 v9, 0xffffff80, v7
	v_lshl_add_u32 v9, v9, 3, v230
	s_waitcnt vmcnt(15)
	v_cvt_pk_f32_fp8_e32 v[104:105], v210
	v_cvt_pk_f32_fp8_sdwa v[106:107], v210 src0_sel:WORD_1
	v_pk_fma_f32 v[214:215], v[102:103], v[104:105], v[214:215] op_sel:[1,0,0]
	v_pk_fma_f32 v[216:217], v[102:103], v[106:107], v[216:217] op_sel:[1,0,0]
	v_cvt_pk_f32_fp8_e32 v[108:109], v211
	v_cvt_pk_f32_fp8_sdwa v[110:111], v211 src0_sel:WORD_1
	v_pk_fma_f32 v[218:219], v[102:103], v[108:109], v[218:219] op_sel:[1,0,0]
	v_pk_fma_f32 v[220:221], v[102:103], v[110:111], v[220:221] op_sel:[1,0,0]
	v_cvt_pk_f32_fp8_e32 v[104:105], v212
	v_cvt_pk_f32_fp8_sdwa v[106:107], v212 src0_sel:WORD_1
	v_pk_fma_f32 v[222:223], v[102:103], v[104:105], v[222:223] op_sel:[1,0,0]
	v_pk_fma_f32 v[224:225], v[102:103], v[106:107], v[224:225] op_sel:[1,0,0]
	v_cvt_pk_f32_fp8_e32 v[108:109], v213
	v_cvt_pk_f32_fp8_sdwa v[110:111], v213 src0_sel:WORD_1
	v_pk_fma_f32 v[226:227], v[102:103], v[108:109], v[226:227] op_sel:[1,0,0]
	v_pk_fma_f32 v[228:229], v[102:103], v[110:111], v[228:229] op_sel:[1,0,0]
	global_load_dwordx4 v[210:213], v9, s[100:101]
	s_add_i32 s20, s20, 1
	s_add_i32 s27, s20, 1
	s_lshr_b32 s27, s27, 3
	s_add_i32 s27, s27, s83
	s_and_b32 s27, s27, 3
	s_lshl_b32 s27, s27, 8
	v_add_u32_e32 v230, s27, v250
	s_and_b32 s27, s20, 7
	s_cmp_lg_u32 s27, 0
	s_cbranch_scc1 .Lgv_body
	s_lshr_b32 s27, s20, 3
	s_add_i32 s27, s27, s83
	s_add_i32 s27, s27, 3
	s_and_b32 s27, s27, 3
	s_cmp_eq_u32 s27, 0
	s_cbranch_scc1 .Lgv_s_0
	s_cmp_eq_u32 s27, 1
	s_cbranch_scc1 .Lgv_s_1
	s_cmp_eq_u32 s27, 2
	s_cbranch_scc1 .Lgv_s_2
	v_mov_b32_e32 v46, v214
	v_mov_b32_e32 v47, v215
	v_mov_b32_e32 v44, v216
	v_mov_b32_e32 v45, v217
	v_mov_b32_e32 v42, v218
	v_mov_b32_e32 v43, v219
	v_mov_b32_e32 v40, v220
	v_mov_b32_e32 v41, v221
	v_mov_b32_e32 v38, v222
	v_mov_b32_e32 v39, v223
	v_mov_b32_e32 v36, v224
	v_mov_b32_e32 v37, v225
	v_mov_b32_e32 v34, v226
	v_mov_b32_e32 v35, v227
	v_mov_b32_e32 v32, v228
	v_mov_b32_e32 v33, v229
	s_branch .Lgv_s_x

; __device__ void phase_gather(const P& p, int vb, int nvb, char* smem) {
;     ...
;     for (int bb = 0; bb < 128; bb++) {
;       const uint32_t key = mykl[bb];
;       const int e = (int)(key >> 7);
;       const float wgt = mywl[bb];
;       const uint4* vp = (const uint4*)(V + (size_t)e * 1024 + 16 * j);
;       uint4 vv[4];
; #pragma unroll
;       for (int i = 0; i < 4; i++) vv[i] = vp[i * 16];
;       const f32x2 w2 = f32x2{wgt, wgt};
; #pragma unroll
;       for (int i = 0; i < 4; i++) {
;         const uint32_t w[4] = {vv[i].x, vv[i].y, vv[i].z, vv[i].w};
; #pragma unroll
;         for (int q = 0; q < 4; q++) {
;           acc[i * 8 + q * 2 + 0] += w2 * __builtin_amdgcn_cvt_pk_f32_fp8((int)w[q], false);
;           acc[i * 8 + q * 2 + 1] += w2 * __builtin_amdgcn_cvt_pk_f32_fp8((int)w[q], true);
;         }
;       }
;     }
.Lgv_s_1:
	v_mov_b32_e32 v78, v214
	v_mov_b32_e32 v79, v215
	v_mov_b32_e32 v76, v216
	v_mov_b32_e32 v77, v217
	v_mov_b32_e32 v74, v218
	v_mov_b32_e32 v75, v219
	v_mov_b32_e32 v72, v220
	v_mov_b32_e32 v73, v221
	v_mov_b32_e32 v70, v222
	v_mov_b32_e32 v71, v223
	v_mov_b32_e32 v68, v224
	v_mov_b32_e32 v69, v225
	v_mov_b32_e32 v66, v226
	v_mov_b32_e32 v67, v227
	v_mov_b32_e32 v62, v228
	v_mov_b32_e32 v63, v229
	s_branch .Lgv_s_x
.Lgv_s_2:
	v_mov_b32_e32 v64, v214
	v_mov_b32_e32 v65, v215
	v_mov_b32_e32 v60, v216
	v_mov_b32_e32 v61, v217
	v_mov_b32_e32 v58, v218
	v_mov_b32_e32 v59, v219
	v_mov_b32_e32 v56, v220
	v_mov_b32_e32 v57, v221
	v_mov_b32_e32 v54, v222
	v_mov_b32_e32 v55, v223
	v_mov_b32_e32 v52, v224
	v_mov_b32_e32 v53, v225
	v_mov_b32_e32 v50, v226
	v_mov_b32_e32 v51, v227
	v_mov_b32_e32 v48, v228
	v_mov_b32_e32 v49, v229

; __device__ void phase_gather(const P& p, int vb, int nvb, char* smem) {
;     ...
;     for (int bb = 0; bb < 128; bb++) {
;       const uint32_t key = mykl[bb];
;       const int e = (int)(key >> 7);
;       const float wgt = mywl[bb];
;       const uint4* vp = (const uint4*)(V + (size_t)e * 1024 + 16 * j);
;       uint4 vv[4];
; #pragma unroll
;       for (int i = 0; i < 4; i++) vv[i] = vp[i * 16];
;       const f32x2 w2 = f32x2{wgt, wgt};
; #pragma unroll
;       for (int i = 0; i < 4; i++) {
;         const uint32_t w[4] = {vv[i].x, vv[i].y, vv[i].z, vv[i].w};
; #pragma unroll
;         for (int q = 0; q < 4; q++) {
;           acc[i * 8 + q * 2 + 0] += w2 * __builtin_amdgcn_cvt_pk_f32_fp8((int)w[q], false);
;           acc[i * 8 + q * 2 + 1] += w2 * __builtin_amdgcn_cvt_pk_f32_fp8((int)w[q], true);
;         }
;       }
;     }
.Lgv_last:
	s_waitcnt lgkmcnt(0)
	s_waitcnt vmcnt(15)
	v_cvt_pk_f32_fp8_e32 v[104:105], v150
	v_cvt_pk_f32_fp8_sdwa v[106:107], v150 src0_sel:WORD_1
	v_pk_fma_f32 v[214:215], v[96:97], v[104:105], v[214:215] op_sel_hi:[0,1,1]
	v_pk_fma_f32 v[216:217], v[96:97], v[106:107], v[216:217] op_sel_hi:[0,1,1]
	v_cvt_pk_f32_fp8_e32 v[108:109], v151
	v_cvt_pk_f32_fp8_sdwa v[110:111], v151 src0_sel:WORD_1
	v_pk_fma_f32 v[218:219], v[96:97], v[108:109], v[218:219] op_sel_hi:[0,1,1]
	v_pk_fma_f32 v[220:221], v[96:97], v[110:111], v[220:221] op_sel_hi:[0,1,1]
	v_cvt_pk_f32_fp8_e32 v[104:105], v152
	v_cvt_pk_f32_fp8_sdwa v[106:107], v152 src0_sel:WORD_1
	v_pk_fma_f32 v[222:223], v[96:97], v[104:105], v[222:223] op_sel_hi:[0,1,1]
	v_pk_fma_f32 v[224:225], v[96:97], v[106:107], v[224:225] op_sel_hi:[0,1,1]
	v_cvt_pk_f32_fp8_e32 v[108:109], v153
	v_cvt_pk_f32_fp8_sdwa v[110:111], v153 src0_sel:WORD_1
	v_pk_fma_f32 v[226:227], v[96:97], v[108:109], v[226:227] op_sel_hi:[0,1,1]
	v_pk_fma_f32 v[228:229], v[96:97], v[110:111], v[228:229] op_sel_hi:[0,1,1]
	s_waitcnt vmcnt(14)
	v_cvt_pk_f32_fp8_e32 v[104:105], v154
	v_cvt_pk_f32_fp8_sdwa v[106:107], v154 src0_sel:WORD_1
	v_pk_fma_f32 v[214:215], v[96:97], v[104:105], v[214:215] op_sel:[1,0,0]
	v_pk_fma_f32 v[216:217], v[96:97], v[106:107], v[216:217] op_sel:[1,0,0]
	v_cvt_pk_f32_fp8_e32 v[108:109], v155
	v_cvt_pk_f32_fp8_sdwa v[110:111], v155 src0_sel:WORD_1
	v_pk_fma_f32 v[218:219], v[96:97], v[108:109], v[218:219] op_sel:[1,0,0]
	v_pk_fma_f32 v[220:221], v[96:97], v[110:111], v[220:221] op_sel:[1,0,0]
	v_cvt_pk_f32_fp8_e32 v[104:105], v156
	v_cvt_pk_f32_fp8_sdwa v[106:107], v156 src0_sel:WORD_1
	v_pk_fma_f32 v[222:223], v[96:97], v[104:105], v[222:223] op_sel:[1,0,0]
	v_pk_fma_f32 v[224:225], v[96:97], v[106:107], v[224:225] op_sel:[1,0,0]
	v_cvt_pk_f32_fp8_e32 v[108:109], v157
	v_cvt_pk_f32_fp8_sdwa v[110:111], v157 src0_sel:WORD_1
	v_pk_fma_f32 v[226:227], v[96:97], v[108:109], v[226:227] op_sel:[1,0,0]
	v_pk_fma_f32 v[228:229], v[96:97], v[110:111], v[228:229] op_sel:[1,0,0]
	ds_read_b128 v[100:103], v255 offset:2064
	s_waitcnt vmcnt(13)
	v_cvt_pk_f32_fp8_e32 v[104:105], v158
	v_cvt_pk_f32_fp8_sdwa v[106:107], v158 src0_sel:WORD_1
	v_pk_fma_f32 v[214:215], v[98:99], v[104:105], v[214:215] op_sel_hi:[0,1,1]
	v_pk_fma_f32 v[216:217], v[98:99], v[106:107], v[216:217] op_sel_hi:[0,1,1]
	v_cvt_pk_f32_fp8_e32 v[108:109], v159
	v_cvt_pk_f32_fp8_sdwa v[110:111], v159 src0_sel:WORD_1
	v_pk_fma_f32 v[218:219], v[98:99], v[108:109], v[218:219] op_sel_hi:[0,1,1]
	v_pk_fma_f32 v[220:221], v[98:99], v[110:111], v[220:221] op_sel_hi:[0,1,1]
	v_cvt_pk_f32_fp8_e32 v[104:105], v160
	v_cvt_pk_f32_fp8_sdwa v[106:107], v160 src0_sel:WORD_1
	v_pk_fma_f32 v[222:223], v[98:99], v[104:105], v[222:223] op_sel_hi:[0,1,1]
	v_pk_fma_f32 v[224:225], v[98:99], v[106:107], v[224:225] op_sel_hi:[0,1,1]
	v_cvt_pk_f32_fp8_e32 v[108:109], v161
	v_cvt_pk_f32_fp8_sdwa v[110:111], v161 src0_sel:WORD_1
	v_pk_fma_f32 v[226:227], v[98:99], v[108:109], v[226:227] op_sel_hi:[0,1,1]
	v_pk_fma_f32 v[228:229], v[98:99], v[110:111], v[228:229] op_sel_hi:[0,1,1]
	s_waitcnt vmcnt(12)
	v_cvt_pk_f32_fp8_e32 v[104:105], v162
	v_cvt_pk_f32_fp8_sdwa v[106:107], v162 src0_sel:WORD_1
	v_pk_fma_f32 v[214:215], v[98:99], v[104:105], v[214:215] op_sel:[1,0,0]
	v_pk_fma_f32 v[216:217], v[98:99], v[106:107], v[216:217] op_sel:[1,0,0]
	v_cvt_pk_f32_fp8_e32 v[108:109], v163
	v_cvt_pk_f32_fp8_sdwa v[110:111], v163 src0_sel:WORD_1
	v_pk_fma_f32 v[218:219], v[98:99], v[108:109], v[218:219] op_sel:[1,0,0]
	v_pk_fma_f32 v[220:221], v[98:99], v[110:111], v[220:221] op_sel:[1,0,0]
	v_cvt_pk_f32_fp8_e32 v[104:105], v164
	v_cvt_pk_f32_fp8_sdwa v[106:107], v164 src0_sel:WORD_1
	v_pk_fma_f32 v[222:223], v[98:99], v[104:105], v[222:223] op_sel:[1,0,0]
	v_pk_fma_f32 v[224:225], v[98:99], v[106:107], v[224:225] op_sel:[1,0,0]
	v_cvt_pk_f32_fp8_e32 v[108:109], v165
	v_cvt_pk_f32_fp8_sdwa v[110:111], v165 src0_sel:WORD_1
	v_pk_fma_f32 v[226:227], v[98:99], v[108:109], v[226:227] op_sel:[1,0,0]
	v_pk_fma_f32 v[228:229], v[98:99], v[110:111], v[228:229] op_sel:[1,0,0]
	s_waitcnt lgkmcnt(0)
	s_waitcnt vmcnt(11)
	v_cvt_pk_f32_fp8_e32 v[104:105], v166
	v_cvt_pk_f32_fp8_sdwa v[106:107], v166 src0_sel:WORD_1
	v_pk_fma_f32 v[214:215], v[100:101], v[104:105], v[214:215] op_sel_hi:[0,1,1]
	v_pk_fma_f32 v[216:217], v[100:101], v[106:107], v[216:217] op_sel_hi:[0,1,1]
	v_cvt_pk_f32_fp8_e32 v[108:109], v167
	v_cvt_pk_f32_fp8_sdwa v[110:111], v167 src0_sel:WORD_1
	v_pk_fma_f32 v[218:219], v[100:101], v[108:109], v[218:219] op_sel_hi:[0,1,1]
	v_pk_fma_f32 v[220:221], v[100:101], v[110:111], v[220:221] op_sel_hi:[0,1,1]
	v_cvt_pk_f32_fp8_e32 v[104:105], v168
	v_cvt_pk_f32_fp8_sdwa v[106:107], v168 src0_sel:WORD_1
	v_pk_fma_f32 v[222:223], v[100:101], v[104:105], v[222:223] op_sel_hi:[0,1,1]
	v_pk_fma_f32 v[224:225], v[100:101], v[106:107], v[224:225] op_sel_hi:[0,1,1]
	v_cvt_pk_f32_fp8_e32 v[108:109], v169
	v_cvt_pk_f32_fp8_sdwa v[110:111], v169 src0_sel:WORD_1
	v_pk_fma_f32 v[226:227], v[100:101], v[108:109], v[226:227] op_sel_hi:[0,1,1]
	v_pk_fma_f32 v[228:229], v[100:101], v[110:111], v[228:229] op_sel_hi:[0,1,1]
	s_waitcnt vmcnt(10)
; __device__ void phase_gather(const P& p, int vb, int nvb, char* smem) {
;     ...
;     for (int bb = 0; bb < 128; bb++) {
;       const uint32_t key = mykl[bb];
;       const int e = (int)(key >> 7);
;       const float wgt = mywl[bb];
;       const uint4* vp = (const uint4*)(V + (size_t)e * 1024 + 16 * j);
;       uint4 vv[4];
; #pragma unroll
;       for (int i = 0; i < 4; i++) vv[i] = vp[i * 16];
;       const f32x2 w2 = f32x2{wgt, wgt};
; #pragma unroll
;       for (int i = 0; i < 4; i++) {
;         const uint32_t w[4] = {vv[i].x, vv[i].y, vv[i].z, vv[i].w};
; #pragma unroll
;         for (int q = 0; q < 4; q++) {
;           acc[i * 8 + q * 2 + 0] += w2 * __builtin_amdgcn_cvt_pk_f32_fp8((int)w[q], false);
;           acc[i * 8 + q * 2 + 1] += w2 * __builtin_amdgcn_cvt_pk_f32_fp8((int)w[q], true);
;         }
;       }
;     }
	v_cvt_pk_f32_fp8_e32 v[104:105], v170
	v_cvt_pk_f32_fp8_sdwa v[106:107], v170 src0_sel:WORD_1
	v_pk_fma_f32 v[214:215], v[100:101], v[104:105], v[214:215] op_sel:[1,0,0]
	v_pk_fma_f32 v[216:217], v[100:101], v[106:107], v[216:217] op_sel:[1,0,0]
	v_cvt_pk_f32_fp8_e32 v[108:109], v171
	v_cvt_pk_f32_fp8_sdwa v[110:111], v171 src0_sel:WORD_1
	v_pk_fma_f32 v[218:219], v[100:101], v[108:109], v[218:219] op_sel:[1,0,0]
	v_pk_fma_f32 v[220:221], v[100:101], v[110:111], v[220:221] op_sel:[1,0,0]
	v_cvt_pk_f32_fp8_e32 v[104:105], v172
	v_cvt_pk_f32_fp8_sdwa v[106:107], v172 src0_sel:WORD_1
	v_pk_fma_f32 v[222:223], v[100:101], v[104:105], v[222:223] op_sel:[1,0,0]
	v_pk_fma_f32 v[224:225], v[100:101], v[106:107], v[224:225] op_sel:[1,0,0]
	v_cvt_pk_f32_fp8_e32 v[108:109], v173
	v_cvt_pk_f32_fp8_sdwa v[110:111], v173 src0_sel:WORD_1
	v_pk_fma_f32 v[226:227], v[100:101], v[108:109], v[226:227] op_sel:[1,0,0]
	v_pk_fma_f32 v[228:229], v[100:101], v[110:111], v[228:229] op_sel:[1,0,0]
	ds_read_b128 v[96:99], v255 offset:2080
	s_waitcnt vmcnt(9)
	v_cvt_pk_f32_fp8_e32 v[104:105], v174
	v_cvt_pk_f32_fp8_sdwa v[106:107], v174 src0_sel:WORD_1
	v_pk_fma_f32 v[214:215], v[102:103], v[104:105], v[214:215] op_sel_hi:[0,1,1]
	v_pk_fma_f32 v[216:217], v[102:103], v[106:107], v[216:217] op_sel_hi:[0,1,1]
	v_cvt_pk_f32_fp8_e32 v[108:109], v175
	v_cvt_pk_f32_fp8_sdwa v[110:111], v175 src0_sel:WORD_1
	v_pk_fma_f32 v[218:219], v[102:103], v[108:109], v[218:219] op_sel_hi:[0,1,1]
	v_pk_fma_f32 v[220:221], v[102:103], v[110:111], v[220:221] op_sel_hi:[0,1,1]
	v_cvt_pk_f32_fp8_e32 v[104:105], v176
	v_cvt_pk_f32_fp8_sdwa v[106:107], v176 src0_sel:WORD_1
	v_pk_fma_f32 v[222:223], v[102:103], v[104:105], v[222:223] op_sel_hi:[0,1,1]
	v_pk_fma_f32 v[224:225], v[102:103], v[106:107], v[224:225] op_sel_hi:[0,1,1]
	v_cvt_pk_f32_fp8_e32 v[108:109], v177
	v_cvt_pk_f32_fp8_sdwa v[110:111], v177 src0_sel:WORD_1
	v_pk_fma_f32 v[226:227], v[102:103], v[108:109], v[226:227] op_sel_hi:[0,1,1]
	v_pk_fma_f32 v[228:229], v[102:103], v[110:111], v[228:229] op_sel_hi:[0,1,1]
	s_waitcnt vmcnt(8)
	v_cvt_pk_f32_fp8_e32 v[104:105], v178
	v_cvt_pk_f32_fp8_sdwa v[106:107], v178 src0_sel:WORD_1
	v_pk_fma_f32 v[214:215], v[102:103], v[104:105], v[214:215] op_sel:[1,0,0]
	v_pk_fma_f32 v[216:217], v[102:103], v[106:107], v[216:217] op_sel:[1,0,0]
	v_cvt_pk_f32_fp8_e32 v[108:109], v179
	v_cvt_pk_f32_fp8_sdwa v[110:111], v179 src0_sel:WORD_1
	v_pk_fma_f32 v[218:219], v[102:103], v[108:109], v[218:219] op_sel:[1,0,0]
	v_pk_fma_f32 v[220:221], v[102:103], v[110:111], v[220:221] op_sel:[1,0,0]
	v_cvt_pk_f32_fp8_e32 v[104:105], v180
	v_cvt_pk_f32_fp8_sdwa v[106:107], v180 src0_sel:WORD_1
	v_pk_fma_f32 v[222:223], v[102:103], v[104:105], v[222:223] op_sel:[1,0,0]
	v_pk_fma_f32 v[224:225], v[102:103], v[106:107], v[224:225] op_sel:[1,0,0]
	v_cvt_pk_f32_fp8_e32 v[108:109], v181
	v_cvt_pk_f32_fp8_sdwa v[110:111], v181 src0_sel:WORD_1
	v_pk_fma_f32 v[226:227], v[102:103], v[108:109], v[226:227] op_sel:[1,0,0]
	v_pk_fma_f32 v[228:229], v[102:103], v[110:111], v[228:229] op_sel:[1,0,0]
	s_waitcnt lgkmcnt(0)
	s_waitcnt vmcnt(7)
	v_cvt_pk_f32_fp8_e32 v[104:105], v182
	v_cvt_pk_f32_fp8_sdwa v[106:107], v182 src0_sel:WORD_1
	v_pk_fma_f32 v[214:215], v[96:97], v[104:105], v[214:215] op_sel_hi:[0,1,1]
	v_pk_fma_f32 v[216:217], v[96:97], v[106:107], v[216:217] op_sel_hi:[0,1,1]
	v_cvt_pk_f32_fp8_e32 v[108:109], v183
	v_cvt_pk_f32_fp8_sdwa v[110:111], v183 src0_sel:WORD_1
	v_pk_fma_f32 v[218:219], v[96:97], v[108:109], v[218:219] op_sel_hi:[0,1,1]
	v_pk_fma_f32 v[220:221], v[96:97], v[110:111], v[220:221] op_sel_hi:[0,1,1]
	v_cvt_pk_f32_fp8_e32 v[104:105], v184
	v_cvt_pk_f32_fp8_sdwa v[106:107], v184 src0_sel:WORD_1
	v_pk_fma_f32 v[222:223], v[96:97], v[104:105], v[222:223] op_sel_hi:[0,1,1]
	v_pk_fma_f32 v[224:225], v[96:97], v[106:107], v[224:225] op_sel_hi:[0,1,1]
	v_cvt_pk_f32_fp8_e32 v[108:109], v185
	v_cvt_pk_f32_fp8_sdwa v[110:111], v185 src0_sel:WORD_1
	v_pk_fma_f32 v[226:227], v[96:97], v[108:109], v[226:227] op_sel_hi:[0,1,1]
	v_pk_fma_f32 v[228:229], v[96:97], v[110:111], v[228:229] op_sel_hi:[0,1,1]
	s_waitcnt vmcnt(6)
	v_cvt_pk_f32_fp8_e32 v[104:105], v186
	v_cvt_pk_f32_fp8_sdwa v[106:107], v186 src0_sel:WORD_1
	v_pk_fma_f32 v[214:215], v[96:97], v[104:105], v[214:215] op_sel:[1,0,0]
	v_pk_fma_f32 v[216:217], v[96:97], v[106:107], v[216:217] op_sel:[1,0,0]
	v_cvt_pk_f32_fp8_e32 v[108:109], v187
	v_cvt_pk_f32_fp8_sdwa v[110:111], v187 src0_sel:WORD_1
	v_pk_fma_f32 v[218:219], v[96:97], v[108:109], v[218:219] op_sel:[1,0,0]
	v_pk_fma_f32 v[220:221], v[96:97], v[110:111], v[220:221] op_sel:[1,0,0]
	v_cvt_pk_f32_fp8_e32 v[104:105], v188
	v_cvt_pk_f32_fp8_sdwa v[106:107], v188 src0_sel:WORD_1
	v_pk_fma_f32 v[222:223], v[96:97], v[104:105], v[222:223] op_sel:[1,0,0]
	v_pk_fma_f32 v[224:225], v[96:97], v[106:107], v[224:225] op_sel:[1,0,0]
	v_cvt_pk_f32_fp8_e32 v[108:109], v189
	v_cvt_pk_f32_fp8_sdwa v[110:111], v189 src0_sel:WORD_1
	v_pk_fma_f32 v[226:227], v[96:97], v[108:109], v[226:227] op_sel:[1,0,0]
	v_pk_fma_f32 v[228:229], v[96:97], v[110:111], v[228:229] op_sel:[1,0,0]
	ds_read_b128 v[100:103], v255 offset:2096
	s_waitcnt vmcnt(5)
; __device__ void phase_gather(const P& p, int vb, int nvb, char* smem) {
;     ...
;     for (int bb = 0; bb < 128; bb++) {
;       const uint32_t key = mykl[bb];
;       const int e = (int)(key >> 7);
;       const float wgt = mywl[bb];
;       const uint4* vp = (const uint4*)(V + (size_t)e * 1024 + 16 * j);
;       uint4 vv[4];
; #pragma unroll
;       for (int i = 0; i < 4; i++) vv[i] = vp[i * 16];
;       const f32x2 w2 = f32x2{wgt, wgt};
; #pragma unroll
;       for (int i = 0; i < 4; i++) {
;         const uint32_t w[4] = {vv[i].x, vv[i].y, vv[i].z, vv[i].w};
; #pragma unroll
;         for (int q = 0; q < 4; q++) {
;           acc[i * 8 + q * 2 + 0] += w2 * __builtin_amdgcn_cvt_pk_f32_fp8((int)w[q], false);
;           acc[i * 8 + q * 2 + 1] += w2 * __builtin_amdgcn_cvt_pk_f32_fp8((int)w[q], true);
;         }
;       }
;     }
	v_cvt_pk_f32_fp8_e32 v[104:105], v190
	v_cvt_pk_f32_fp8_sdwa v[106:107], v190 src0_sel:WORD_1
	v_pk_fma_f32 v[214:215], v[98:99], v[104:105], v[214:215] op_sel_hi:[0,1,1]
	v_pk_fma_f32 v[216:217], v[98:99], v[106:107], v[216:217] op_sel_hi:[0,1,1]
	v_cvt_pk_f32_fp8_e32 v[108:109], v191
	v_cvt_pk_f32_fp8_sdwa v[110:111], v191 src0_sel:WORD_1
	v_pk_fma_f32 v[218:219], v[98:99], v[108:109], v[218:219] op_sel_hi:[0,1,1]
	v_pk_fma_f32 v[220:221], v[98:99], v[110:111], v[220:221] op_sel_hi:[0,1,1]
	v_cvt_pk_f32_fp8_e32 v[104:105], v192
	v_cvt_pk_f32_fp8_sdwa v[106:107], v192 src0_sel:WORD_1
	v_pk_fma_f32 v[222:223], v[98:99], v[104:105], v[222:223] op_sel_hi:[0,1,1]
	v_pk_fma_f32 v[224:225], v[98:99], v[106:107], v[224:225] op_sel_hi:[0,1,1]
	v_cvt_pk_f32_fp8_e32 v[108:109], v193
	v_cvt_pk_f32_fp8_sdwa v[110:111], v193 src0_sel:WORD_1
	v_pk_fma_f32 v[226:227], v[98:99], v[108:109], v[226:227] op_sel_hi:[0,1,1]
	v_pk_fma_f32 v[228:229], v[98:99], v[110:111], v[228:229] op_sel_hi:[0,1,1]
	s_waitcnt vmcnt(4)
	v_cvt_pk_f32_fp8_e32 v[104:105], v194
	v_cvt_pk_f32_fp8_sdwa v[106:107], v194 src0_sel:WORD_1
	v_pk_fma_f32 v[214:215], v[98:99], v[104:105], v[214:215] op_sel:[1,0,0]
	v_pk_fma_f32 v[216:217], v[98:99], v[106:107], v[216:217] op_sel:[1,0,0]
	v_cvt_pk_f32_fp8_e32 v[108:109], v195
	v_cvt_pk_f32_fp8_sdwa v[110:111], v195 src0_sel:WORD_1
	v_pk_fma_f32 v[218:219], v[98:99], v[108:109], v[218:219] op_sel:[1,0,0]
	v_pk_fma_f32 v[220:221], v[98:99], v[110:111], v[220:221] op_sel:[1,0,0]
	v_cvt_pk_f32_fp8_e32 v[104:105], v196
	v_cvt_pk_f32_fp8_sdwa v[106:107], v196 src0_sel:WORD_1
	v_pk_fma_f32 v[222:223], v[98:99], v[104:105], v[222:223] op_sel:[1,0,0]
	v_pk_fma_f32 v[224:225], v[98:99], v[106:107], v[224:225] op_sel:[1,0,0]
	v_cvt_pk_f32_fp8_e32 v[108:109], v197
	v_cvt_pk_f32_fp8_sdwa v[110:111], v197 src0_sel:WORD_1
	v_pk_fma_f32 v[226:227], v[98:99], v[108:109], v[226:227] op_sel:[1,0,0]
	v_pk_fma_f32 v[228:229], v[98:99], v[110:111], v[228:229] op_sel:[1,0,0]
	s_waitcnt lgkmcnt(0)
	s_waitcnt vmcnt(3)
	v_cvt_pk_f32_fp8_e32 v[104:105], v198
	v_cvt_pk_f32_fp8_sdwa v[106:107], v198 src0_sel:WORD_1
	v_pk_fma_f32 v[214:215], v[100:101], v[104:105], v[214:215] op_sel_hi:[0,1,1]
	v_pk_fma_f32 v[216:217], v[100:101], v[106:107], v[216:217] op_sel_hi:[0,1,1]
	v_cvt_pk_f32_fp8_e32 v[108:109], v199
	v_cvt_pk_f32_fp8_sdwa v[110:111], v199 src0_sel:WORD_1
	v_pk_fma_f32 v[218:219], v[100:101], v[108:109], v[218:219] op_sel_hi:[0,1,1]
	v_pk_fma_f32 v[220:221], v[100:101], v[110:111], v[220:221] op_sel_hi:[0,1,1]
	v_cvt_pk_f32_fp8_e32 v[104:105], v200
	v_cvt_pk_f32_fp8_sdwa v[106:107], v200 src0_sel:WORD_1
	v_pk_fma_f32 v[222:223], v[100:101], v[104:105], v[222:223] op_sel_hi:[0,1,1]
	v_pk_fma_f32 v[224:225], v[100:101], v[106:107], v[224:225] op_sel_hi:[0,1,1]
	v_cvt_pk_f32_fp8_e32 v[108:109], v201
	v_cvt_pk_f32_fp8_sdwa v[110:111], v201 src0_sel:WORD_1
	v_pk_fma_f32 v[226:227], v[100:101], v[108:109], v[226:227] op_sel_hi:[0,1,1]
	v_pk_fma_f32 v[228:229], v[100:101], v[110:111], v[228:229] op_sel_hi:[0,1,1]
	s_waitcnt vmcnt(2)
	v_cvt_pk_f32_fp8_e32 v[104:105], v202
	v_cvt_pk_f32_fp8_sdwa v[106:107], v202 src0_sel:WORD_1
	v_pk_fma_f32 v[214:215], v[100:101], v[104:105], v[214:215] op_sel:[1,0,0]
	v_pk_fma_f32 v[216:217], v[100:101], v[106:107], v[216:217] op_sel:[1,0,0]
	v_cvt_pk_f32_fp8_e32 v[108:109], v203
	v_cvt_pk_f32_fp8_sdwa v[110:111], v203 src0_sel:WORD_1
	v_pk_fma_f32 v[218:219], v[100:101], v[108:109], v[218:219] op_sel:[1,0,0]
	v_pk_fma_f32 v[220:221], v[100:101], v[110:111], v[220:221] op_sel:[1,0,0]
	v_cvt_pk_f32_fp8_e32 v[104:105], v204
	v_cvt_pk_f32_fp8_sdwa v[106:107], v204 src0_sel:WORD_1
	v_pk_fma_f32 v[222:223], v[100:101], v[104:105], v[222:223] op_sel:[1,0,0]
	v_pk_fma_f32 v[224:225], v[100:101], v[106:107], v[224:225] op_sel:[1,0,0]
	v_cvt_pk_f32_fp8_e32 v[108:109], v205
	v_cvt_pk_f32_fp8_sdwa v[110:111], v205 src0_sel:WORD_1
	v_pk_fma_f32 v[226:227], v[100:101], v[108:109], v[226:227] op_sel:[1,0,0]
	v_pk_fma_f32 v[228:229], v[100:101], v[110:111], v[228:229] op_sel:[1,0,0]
	s_waitcnt vmcnt(1)
	v_cvt_pk_f32_fp8_e32 v[104:105], v206
	v_cvt_pk_f32_fp8_sdwa v[106:107], v206 src0_sel:WORD_1
	v_pk_fma_f32 v[214:215], v[102:103], v[104:105], v[214:215] op_sel_hi:[0,1,1]
	v_pk_fma_f32 v[216:217], v[102:103], v[106:107], v[216:217] op_sel_hi:[0,1,1]
	v_cvt_pk_f32_fp8_e32 v[108:109], v207
	v_cvt_pk_f32_fp8_sdwa v[110:111], v207 src0_sel:WORD_1
	v_pk_fma_f32 v[218:219], v[102:103], v[108:109], v[218:219] op_sel_hi:[0,1,1]
	v_pk_fma_f32 v[220:221], v[102:103], v[110:111], v[220:221] op_sel_hi:[0,1,1]
	v_cvt_pk_f32_fp8_e32 v[104:105], v208
	v_cvt_pk_f32_fp8_sdwa v[106:107], v208 src0_sel:WORD_1
	v_pk_fma_f32 v[222:223], v[102:103], v[104:105], v[222:223] op_sel_hi:[0,1,1]
	v_pk_fma_f32 v[224:225], v[102:103], v[106:107], v[224:225] op_sel_hi:[0,1,1]
	v_cvt_pk_f32_fp8_e32 v[108:109], v209
	v_cvt_pk_f32_fp8_sdwa v[110:111], v209 src0_sel:WORD_1
	v_pk_fma_f32 v[226:227], v[102:103], v[108:109], v[226:227] op_sel_hi:[0,1,1]
	v_pk_fma_f32 v[228:229], v[102:103], v[110:111], v[228:229] op_sel_hi:[0,1,1]
	s_waitcnt vmcnt(0)
	v_cvt_pk_f32_fp8_e32 v[104:105], v210
	v_cvt_pk_f32_fp8_sdwa v[106:107], v210 src0_sel:WORD_1
	v_pk_fma_f32 v[214:215], v[102:103], v[104:105], v[214:215] op_sel:[1,0,0]
	v_pk_fma_f32 v[216:217], v[102:103], v[106:107], v[216:217] op_sel:[1,0,0]
	v_cvt_pk_f32_fp8_e32 v[108:109], v211
	v_cvt_pk_f32_fp8_sdwa v[110:111], v211 src0_sel:WORD_1
	v_pk_fma_f32 v[218:219], v[102:103], v[108:109], v[218:219] op_sel:[1,0,0]
	v_pk_fma_f32 v[220:221], v[102:103], v[110:111], v[220:221] op_sel:[1,0,0]
	v_cvt_pk_f32_fp8_e32 v[104:105], v212
	v_cvt_pk_f32_fp8_sdwa v[106:107], v212 src0_sel:WORD_1
	v_pk_fma_f32 v[222:223], v[102:103], v[104:105], v[222:223] op_sel:[1,0,0]
	v_pk_fma_f32 v[224:225], v[102:103], v[106:107], v[224:225] op_sel:[1,0,0]
	v_cvt_pk_f32_fp8_e32 v[108:109], v213
	v_cvt_pk_f32_fp8_sdwa v[110:111], v213 src0_sel:WORD_1
	v_pk_fma_f32 v[226:227], v[102:103], v[108:109], v[226:227] op_sel:[1,0,0]
	v_pk_fma_f32 v[228:229], v[102:103], v[110:111], v[228:229] op_sel:[1,0,0]
	s_add_i32 s27, s83, 3
	s_and_b32 s27, s27, 3
	s_cmp_eq_u32 s27, 0
	s_cbranch_scc1 .Lgv_f_0
	s_cmp_eq_u32 s27, 1
	s_cbranch_scc1 .Lgv_f_1
	s_cmp_eq_u32 s27, 2
	s_cbranch_scc1 .Lgv_f_2
	v_mov_b32_e32 v46, v214
	v_mov_b32_e32 v47, v215
	v_mov_b32_e32 v44, v216
	v_mov_b32_e32 v45, v217
	v_mov_b32_e32 v42, v218
	v_mov_b32_e32 v43, v219
	v_mov_b32_e32 v40, v220
	v_mov_b32_e32 v41, v221
	v_mov_b32_e32 v38, v222
	v_mov_b32_e32 v39, v223
	v_mov_b32_e32 v36, v224
	v_mov_b32_e32 v37, v225
	v_mov_b32_e32 v34, v226
	v_mov_b32_e32 v35, v227
	v_mov_b32_e32 v32, v228
	v_mov_b32_e32 v33, v229
	s_branch .Lgv_f_x

; DEVI float4 ldbf4(const uint16_t* p) { const uint2 v = *(const uint2*)p; return make_float4(bflo(v.x), bfhi(v.x), bflo(v.y), bfhi(v.y)); }
; __device__ void phase_gather(const P& p, int vb, int nvb, char* smem) {
;     ...
;     asm volatile("" ::: "memory");
;     float ss = 0.f;
; #pragma unroll
;     for (int i = 0; i < 4; i++) {
; #pragma unroll
;       for (int q = 0; q < 4; q++) {
;         const float4 a = ldbf4(hr + i * 256 + 16 * j + 4 * q);
;         const float v0 = acc[i * 8 + q * 2].x + a.x, v1 = acc[i * 8 + q * 2].y + a.y, v2 = acc[i * 8 + q * 2 + 1].x + a.z, v3 = acc[i * 8 + q * 2 + 1].y + a.w;
;         acc[i * 8 + q * 2] = f32x2{v0, v1}; acc[i * 8 + q * 2 + 1] = f32x2{v2, v3};
;         ss += v0 * v0 + v1 * v1 + v2 * v2 + v3 * v3;
;       }
;       __builtin_amdgcn_sched_barrier(0);
;     }
.Lgv_f_x:
	global_load_dwordx4 v[0:3], v[28:29], off
	global_load_dwordx4 v[4:7], v[28:29], off offset:16
	s_waitcnt vmcnt(1)
	v_lshlrev_b32_e32 v8, 16, v0
	v_and_b32_e32 v9, 0xffff0000, v0
	v_lshlrev_b32_e32 v10, 16, v1
	v_and_b32_e32 v11, 0xffff0000, v1
	v_lshlrev_b32_e32 v98, 16, v2
	v_and_b32_e32 v99, 0xffff0000, v2
	v_lshlrev_b32_e32 v100, 16, v3
	v_and_b32_e32 v101, 0xffff0000, v3
	s_waitcnt vmcnt(0)
	v_lshlrev_b32_e32 v102, 16, v4
	v_and_b32_e32 v103, 0xffff0000, v4
	v_lshlrev_b32_e32 v104, 16, v5
	v_and_b32_e32 v105, 0xffff0000, v5
	v_lshlrev_b32_e32 v106, 16, v6
	v_and_b32_e32 v107, 0xffff0000, v6
	v_lshlrev_b32_e32 v108, 16, v7
	v_and_b32_e32 v109, 0xffff0000, v7
	global_load_dwordx4 v[0:3], v[28:29], off offset:512
	global_load_dwordx4 v[4:7], v[28:29], off offset:528
	s_waitcnt vmcnt(1)
	v_lshlrev_b32_e32 v110, 16, v0
	v_and_b32_e32 v111, 0xffff0000, v0
	v_lshlrev_b32_e32 v112, 16, v1
	v_and_b32_e32 v113, 0xffff0000, v1
	v_lshlrev_b32_e32 v114, 16, v2
	v_and_b32_e32 v115, 0xffff0000, v2
	v_lshlrev_b32_e32 v116, 16, v3
	v_and_b32_e32 v117, 0xffff0000, v3
	s_waitcnt vmcnt(0)
	v_lshlrev_b32_e32 v118, 16, v4
	v_and_b32_e32 v119, 0xffff0000, v4
	v_lshlrev_b32_e32 v120, 16, v5
	v_and_b32_e32 v121, 0xffff0000, v5
	v_lshlrev_b32_e32 v122, 16, v6
	v_and_b32_e32 v123, 0xffff0000, v6
	v_lshlrev_b32_e32 v124, 16, v7
	v_and_b32_e32 v125, 0xffff0000, v7
	global_load_dwordx4 v[0:3], v[28:29], off offset:1024
	global_load_dwordx4 v[4:7], v[28:29], off offset:1040
	s_waitcnt vmcnt(1)
	v_lshlrev_b32_e32 v150, 16, v0
	v_and_b32_e32 v151, 0xffff0000, v0
	v_lshlrev_b32_e32 v152, 16, v1
	v_and_b32_e32 v153, 0xffff0000, v1
	v_lshlrev_b32_e32 v154, 16, v2
	v_and_b32_e32 v155, 0xffff0000, v2
	v_lshlrev_b32_e32 v156, 16, v3
	v_and_b32_e32 v157, 0xffff0000, v3
	s_waitcnt vmcnt(0)
	v_lshlrev_b32_e32 v158, 16, v4
	v_and_b32_e32 v159, 0xffff0000, v4
	v_lshlrev_b32_e32 v160, 16, v5
	v_and_b32_e32 v161, 0xffff0000, v5
	v_lshlrev_b32_e32 v162, 16, v6
	v_and_b32_e32 v163, 0xffff0000, v6
	v_lshlrev_b32_e32 v164, 16, v7
	v_and_b32_e32 v165, 0xffff0000, v7
	global_load_dwordx4 v[0:3], v[28:29], off offset:1536
	global_load_dwordx4 v[4:7], v[28:29], off offset:1552
	s_waitcnt vmcnt(1)
	v_lshlrev_b32_e32 v166, 16, v0
	v_and_b32_e32 v167, 0xffff0000, v0
	v_lshlrev_b32_e32 v168, 16, v1
	v_and_b32_e32 v169, 0xffff0000, v1
	v_lshlrev_b32_e32 v170, 16, v2
	v_and_b32_e32 v171, 0xffff0000, v2
	v_lshlrev_b32_e32 v172, 16, v3
	v_and_b32_e32 v173, 0xffff0000, v3
	s_waitcnt vmcnt(0)
	v_lshlrev_b32_e32 v174, 16, v4
	v_and_b32_e32 v175, 0xffff0000, v4
	v_lshlrev_b32_e32 v176, 16, v5
	v_and_b32_e32 v177, 0xffff0000, v5
	v_lshlrev_b32_e32 v178, 16, v6
	v_and_b32_e32 v179, 0xffff0000, v6
	v_lshlrev_b32_e32 v180, 16, v7
	v_and_b32_e32 v181, 0xffff0000, v7
	v_pk_add_f32 v[28:29], v[54:55], v[158:159]
	v_pk_add_f32 v[0:1], v[50:51], v[162:163]
	v_mov_b32_e32 v6, v29
	v_mov_b32_e32 v7, v1
	v_pk_add_f32 v[182:183], v[94:95], v[8:9]
	global_load_dwordx4 v[94:97], v[22:23], off
	v_pk_add_f32 v[52:53], v[52:53], v[160:161]
	v_pk_add_f32 v[2:3], v[48:49], v[164:165]
	v_mov_b32_e32 v4, v28
	v_mov_b32_e32 v5, v0
	v_pk_mul_f32 v[6:7], v[6:7], v[6:7]
	v_mov_b32_e32 v8, v53
	v_pk_fma_f32 v[4:5], v[4:5], v[4:5], v[6:7]
	v_mov_b32_e32 v6, v52
	v_mov_b32_e32 v7, v2
	v_mov_b32_e32 v9, v3
	v_pk_fma_f32 v[4:5], v[6:7], v[6:7], v[4:5]
	v_pk_add_f32 v[46:47], v[46:47], v[166:167]
	v_pk_fma_f32 v[48:49], v[8:9], v[8:9], v[4:5]
	v_pk_add_f32 v[4:5], v[42:43], v[170:171]
	v_pk_add_f32 v[92:93], v[92:93], v[10:11]
	v_mov_b32_e32 v10, v47
	v_mov_b32_e32 v11, v5
	v_pk_add_f32 v[44:45], v[44:45], v[168:169]
	v_pk_add_f32 v[6:7], v[40:41], v[172:173]
	v_mov_b32_e32 v8, v46
	v_mov_b32_e32 v9, v4
	v_pk_mul_f32 v[10:11], v[10:11], v[10:11]
	v_mov_b32_e32 v40, v45
	v_pk_fma_f32 v[8:9], v[8:9], v[8:9], v[10:11]
	v_mov_b32_e32 v10, v44
	v_mov_b32_e32 v11, v6
	v_mov_b32_e32 v41, v7
	v_pk_fma_f32 v[8:9], v[10:11], v[10:11], v[8:9]
	v_pk_add_f32 v[38:39], v[38:39], v[174:175]
	v_pk_fma_f32 v[40:41], v[40:41], v[40:41], v[8:9]
	v_pk_add_f32 v[8:9], v[34:35], v[178:179]
	v_mov_b32_e32 v34, v39
	v_mov_b32_e32 v35, v9
	v_pk_add_f32 v[90:91], v[90:91], v[98:99]
	v_pk_add_f32 v[36:37], v[36:37], v[176:177]
	v_pk_add_f32 v[10:11], v[32:33], v[180:181]
	v_mov_b32_e32 v32, v38
	v_mov_b32_e32 v33, v8
	v_pk_mul_f32 v[34:35], v[34:35], v[34:35]
	v_pk_mul_f32 v[184:185], v[182:183], v[182:183]
	v_pk_mul_f32 v[98:99], v[90:91], v[90:91]
	v_pk_add_f32 v[88:89], v[88:89], v[100:101]
	v_pk_fma_f32 v[32:33], v[32:33], v[32:33], v[34:35]
	v_mov_b32_e32 v34, v36
	v_mov_b32_e32 v35, v10
	v_pk_mul_f32 v[186:187], v[92:93], v[92:93]
	v_pk_mul_f32 v[100:101], v[88:89], v[88:89]
	v_pk_fma_f32 v[32:33], v[34:35], v[34:35], v[32:33]
	v_add_f32_e32 v12, v98, v99
	v_add_f32_e32 v34, v184, v185
	v_pk_add_f32 v[86:87], v[86:87], v[102:103]
	v_add_f32_e32 v12, v12, v100
	v_add_f32_e32 v34, v34, v186
	v_pk_mul_f32 v[102:103], v[86:87], v[86:87]
	v_pk_add_f32 v[84:85], v[84:85], v[104:105]
	v_add_f32_e32 v12, v101, v12
	v_add_f32_e32 v34, v187, v34
	v_pk_mul_f32 v[104:105], v[84:85], v[84:85]
	v_add_f32_e32 v12, v34, v12
	v_add_f32_e32 v34, v102, v103
	v_pk_add_f32 v[82:83], v[82:83], v[106:107]
	v_add_f32_e32 v34, v34, v104
	v_pk_mul_f32 v[106:107], v[82:83], v[82:83]
	v_pk_add_f32 v[80:81], v[80:81], v[108:109]
	v_add_f32_e32 v34, v105, v34
	v_pk_mul_f32 v[108:109], v[80:81], v[80:81]
	v_add_f32_e32 v12, v12, v34
	v_add_f32_e32 v34, v106, v107
	v_pk_add_f32 v[78:79], v[78:79], v[110:111]
	v_add_f32_e32 v34, v34, v108
	v_pk_mul_f32 v[110:111], v[78:79], v[78:79]
	v_pk_add_f32 v[76:77], v[76:77], v[112:113]
	v_add_f32_e32 v34, v109, v34
; __device__ void phase_gather(const P& p, int vb, int nvb, char* smem) {
;     ...
;     const float rstd = rsqrtf(wsum16(ss) * (1.f / 1024.f) + EPS);
;     float* orow = p.out + (size_t)rr * DM;
; #pragma unroll
;     for (int i = 0; i < 4; i++) {
; #pragma unroll
;       for (int q = 0; q < 4; q++) {
;         const float4 ga = *(const float4*)(gfin + i * 256 + 16 * j + 4 * q);
;         *(float4*)(orow + i * 256 + 16 * j + 4 * q) =
;             make_float4(acc[i * 8 + q * 2].x * rstd * ga.x, acc[i * 8 + q * 2].y * rstd * ga.y, acc[i * 8 + q * 2 + 1].x * rstd * ga.z, acc[i * 8 + q * 2 + 1].y * rstd * ga.w);
;       }
;       __builtin_amdgcn_sched_barrier(0);
;     }
	v_pk_mul_f32 v[112:113], v[76:77], v[76:77]
	v_add_f32_e32 v12, v12, v34
	v_add_f32_e32 v34, v110, v111
	v_pk_add_f32 v[74:75], v[74:75], v[114:115]
	v_add_f32_e32 v34, v34, v112
	v_pk_mul_f32 v[114:115], v[74:75], v[74:75]
	v_pk_add_f32 v[72:73], v[72:73], v[116:117]
	v_add_f32_e32 v34, v113, v34
	v_pk_mul_f32 v[116:117], v[72:73], v[72:73]
	v_add_f32_e32 v12, v12, v34
	v_add_f32_e32 v34, v114, v115
	v_pk_add_f32 v[70:71], v[70:71], v[118:119]
	v_add_f32_e32 v34, v34, v116
	v_pk_mul_f32 v[118:119], v[70:71], v[70:71]
	v_pk_add_f32 v[120:121], v[68:69], v[120:121]
	v_add_f32_e32 v34, v117, v34
	v_pk_mul_f32 v[188:189], v[120:121], v[120:121]
	v_add_f32_e32 v12, v12, v34
	v_add_f32_e32 v34, v118, v119
	v_pk_add_f32 v[66:67], v[66:67], v[122:123]
	v_add_f32_e32 v34, v34, v188
	v_pk_mul_f32 v[122:123], v[66:67], v[66:67]
	v_pk_add_f32 v[68:69], v[62:63], v[124:125]
	v_add_f32_e32 v34, v189, v34
	v_pk_mul_f32 v[124:125], v[68:69], v[68:69]
	v_add_f32_e32 v12, v12, v34
	v_add_f32_e32 v34, v122, v123
	v_pk_add_f32 v[62:63], v[64:65], v[150:151]
	v_add_f32_e32 v34, v34, v124
	v_pk_mul_f32 v[64:65], v[62:63], v[62:63]
	v_pk_add_f32 v[60:61], v[60:61], v[152:153]
	v_add_f32_e32 v34, v125, v34
	v_pk_mul_f32 v[150:151], v[60:61], v[60:61]
	v_add_f32_e32 v12, v12, v34
	v_add_f32_e32 v34, v64, v65
	v_pk_add_f32 v[58:59], v[58:59], v[154:155]
	v_add_f32_e32 v34, v34, v150
	v_pk_mul_f32 v[152:153], v[58:59], v[58:59]
	v_pk_add_f32 v[56:57], v[56:57], v[156:157]
	v_add_f32_e32 v34, v151, v34
	v_pk_mul_f32 v[154:155], v[56:57], v[56:57]
	v_add_f32_e32 v12, v12, v34
	v_add_f32_e32 v34, v152, v153
	v_add_f32_e32 v34, v34, v154
	v_add_f32_e32 v34, v155, v34
	v_add_f32_e32 v12, v12, v34
	v_add_f32_e32 v12, v12, v48
	v_add_f32_e32 v12, v12, v49
	v_mov_b32_e32 v42, v37
	v_mov_b32_e32 v43, v11
	v_add_f32_e32 v12, v12, v40
	v_pk_fma_f32 v[32:33], v[42:43], v[42:43], v[32:33]
	v_add_f32_e32 v12, v12, v41
	v_add_f32_e32 v12, v12, v32
	v_add_f32_e32 v12, v12, v33
	ds_bpermute_b32 v32, v128, v12
	v_lshl_add_u64 v[34:35], v[30:31], 2, v[26:27]
	s_waitcnt lgkmcnt(0)
	v_add_f32_e32 v12, v12, v32
	ds_bpermute_b32 v32, v129, v12
	s_waitcnt lgkmcnt(0)
	v_add_f32_e32 v12, v12, v32
	ds_bpermute_b32 v32, v130, v12
	s_waitcnt lgkmcnt(0)
	v_add_f32_e32 v12, v12, v32
	ds_bpermute_b32 v32, v131, v12
	s_waitcnt lgkmcnt(0)
	v_add_f32_e32 v12, v12, v32
	v_fmamk_f32 v12, v12, 0x3a800000, v143
	v_mul_f32_e32 v32, 0x4b800000, v12
	v_cmp_gt_f32_e64 s[20:21], s29, v12
	s_nop 1
	v_cndmask_b32_e64 v12, v12, v32, s[20:21]
	v_rsq_f32_e32 v12, v12
	s_nop 0
	v_mul_f32_e32 v30, 0x45800000, v12
	v_cndmask_b32_e64 v12, v12, v30, s[20:21]
	v_pk_mul_f32 v[30:31], v[182:183], v[12:13] op_sel_hi:[1,0]
	v_pk_mul_f32 v[32:33], v[92:93], v[12:13] op_sel_hi:[1,0]
	s_waitcnt vmcnt(0)
	v_pk_mul_f32 v[30:31], v[94:95], v[30:31]
	v_pk_mul_f32 v[32:33], v[96:97], v[32:33]
	global_store_dwordx4 v[34:35], v[30:33], off
	global_load_dwordx4 v[30:33], v[22:23], off offset:16
	v_pk_mul_f32 v[40:41], v[90:91], v[12:13] op_sel_hi:[1,0]
	v_pk_mul_f32 v[42:43], v[88:89], v[12:13] op_sel_hi:[1,0]
	s_waitcnt vmcnt(0)
	v_pk_mul_f32 v[30:31], v[30:31], v[40:41]
	v_pk_mul_f32 v[32:33], v[32:33], v[42:43]
	global_store_dwordx4 v[34:35], v[30:33], off offset:16
	global_load_dwordx4 v[30:33], v[22:23], off offset:32
	v_pk_mul_f32 v[40:41], v[86:87], v[12:13] op_sel_hi:[1,0]
	v_pk_mul_f32 v[42:43], v[84:85], v[12:13] op_sel_hi:[1,0]
	s_waitcnt vmcnt(0)
	v_pk_mul_f32 v[30:31], v[40:41], v[30:31]
	v_pk_mul_f32 v[32:33], v[42:43], v[32:33]
	global_store_dwordx4 v[34:35], v[30:33], off offset:32
	global_load_dwordx4 v[30:33], v[22:23], off offset:48
	v_pk_mul_f32 v[40:41], v[82:83], v[12:13] op_sel_hi:[1,0]
	v_pk_mul_f32 v[42:43], v[80:81], v[12:13] op_sel_hi:[1,0]
	s_waitcnt vmcnt(0)
	v_pk_mul_f32 v[30:31], v[40:41], v[30:31]
	v_pk_mul_f32 v[32:33], v[42:43], v[32:33]
	global_store_dwordx4 v[34:35], v[30:33], off offset:48
	global_load_dwordx4 v[30:33], v[22:23], off offset:1024
	v_pk_mul_f32 v[40:41], v[78:79], v[12:13] op_sel_hi:[1,0]
	v_pk_mul_f32 v[42:43], v[76:77], v[12:13] op_sel_hi:[1,0]
	s_waitcnt vmcnt(0)
; __device__ void phase_gather(const P& p, int vb, int nvb, char* smem) {
;     ...
;     const float rstd = rsqrtf(wsum16(ss) * (1.f / 1024.f) + EPS);
;     float* orow = p.out + (size_t)rr * DM;
; #pragma unroll
;     for (int i = 0; i < 4; i++) {
; #pragma unroll
;       for (int q = 0; q < 4; q++) {
;         const float4 ga = *(const float4*)(gfin + i * 256 + 16 * j + 4 * q);
;         *(float4*)(orow + i * 256 + 16 * j + 4 * q) =
;             make_float4(acc[i * 8 + q * 2].x * rstd * ga.x, acc[i * 8 + q * 2].y * rstd * ga.y, acc[i * 8 + q * 2 + 1].x * rstd * ga.z, acc[i * 8 + q * 2 + 1].y * rstd * ga.w);
;       }
;       __builtin_amdgcn_sched_barrier(0);
;     }
;   }
	v_pk_mul_f32 v[30:31], v[40:41], v[30:31]
	v_pk_mul_f32 v[32:33], v[42:43], v[32:33]
	global_store_dwordx4 v[34:35], v[30:33], off offset:1024
	global_load_dwordx4 v[30:33], v[22:23], off offset:1040
	v_pk_mul_f32 v[40:41], v[74:75], v[12:13] op_sel_hi:[1,0]
	v_pk_mul_f32 v[42:43], v[72:73], v[12:13] op_sel_hi:[1,0]
	s_waitcnt vmcnt(0)
	v_pk_mul_f32 v[30:31], v[40:41], v[30:31]
	v_pk_mul_f32 v[32:33], v[42:43], v[32:33]
	global_store_dwordx4 v[34:35], v[30:33], off offset:1040
	global_load_dwordx4 v[30:33], v[22:23], off offset:1056
	v_pk_mul_f32 v[40:41], v[70:71], v[12:13] op_sel_hi:[1,0]
	v_pk_mul_f32 v[42:43], v[120:121], v[12:13] op_sel_hi:[1,0]
	s_waitcnt vmcnt(0)
	v_pk_mul_f32 v[30:31], v[40:41], v[30:31]
	v_pk_mul_f32 v[32:33], v[42:43], v[32:33]
	global_store_dwordx4 v[34:35], v[30:33], off offset:1056
	global_load_dwordx4 v[30:33], v[22:23], off offset:1072
	v_pk_mul_f32 v[40:41], v[66:67], v[12:13] op_sel_hi:[1,0]
	v_pk_mul_f32 v[42:43], v[68:69], v[12:13] op_sel_hi:[1,0]
	s_waitcnt vmcnt(0)
	v_pk_mul_f32 v[30:31], v[40:41], v[30:31]
	v_pk_mul_f32 v[32:33], v[42:43], v[32:33]
	global_store_dwordx4 v[34:35], v[30:33], off offset:1072
	global_load_dwordx4 v[30:33], v[22:23], off offset:2048
	v_pk_mul_f32 v[40:41], v[62:63], v[12:13] op_sel_hi:[1,0]
	v_pk_mul_f32 v[42:43], v[60:61], v[12:13] op_sel_hi:[1,0]
	v_pk_mul_f32 v[28:29], v[28:29], v[12:13] op_sel_hi:[1,0]
	v_pk_mul_f32 v[0:1], v[0:1], v[12:13] op_sel_hi:[1,0]
	v_pk_mul_f32 v[2:3], v[2:3], v[12:13] op_sel_hi:[1,0]
	s_waitcnt vmcnt(0)
	v_pk_mul_f32 v[30:31], v[40:41], v[30:31]
	v_pk_mul_f32 v[32:33], v[42:43], v[32:33]
	global_store_dwordx4 v[34:35], v[30:33], off offset:2048
	global_load_dwordx4 v[30:33], v[22:23], off offset:2064
	v_pk_mul_f32 v[40:41], v[58:59], v[12:13] op_sel_hi:[1,0]
	v_pk_mul_f32 v[42:43], v[56:57], v[12:13] op_sel_hi:[1,0]
	s_waitcnt vmcnt(0)
	v_pk_mul_f32 v[30:31], v[40:41], v[30:31]
	v_pk_mul_f32 v[32:33], v[42:43], v[32:33]
	global_store_dwordx4 v[34:35], v[30:33], off offset:2064
	global_load_dwordx4 v[30:33], v[22:23], off offset:2080
	v_pk_mul_f32 v[40:41], v[52:53], v[12:13] op_sel_hi:[1,0]
	s_waitcnt vmcnt(0)
	v_pk_mul_f32 v[28:29], v[28:29], v[30:31]
	v_pk_mul_f32 v[30:31], v[40:41], v[32:33]
	global_store_dwordx4 v[34:35], v[28:31], off offset:2080
	global_load_dwordx4 v[28:31], v[22:23], off offset:2096
	s_waitcnt vmcnt(0)
	v_pk_mul_f32 v[0:1], v[0:1], v[28:29]
	v_pk_mul_f32 v[2:3], v[2:3], v[30:31]
	global_store_dwordx4 v[34:35], v[0:3], off offset:2096
	global_load_dwordx4 v[0:3], v[22:23], off offset:3072
	v_pk_mul_f32 v[28:29], v[46:47], v[12:13] op_sel_hi:[1,0]
	v_pk_mul_f32 v[30:31], v[44:45], v[12:13] op_sel_hi:[1,0]
	v_pk_mul_f32 v[4:5], v[4:5], v[12:13] op_sel_hi:[1,0]
	v_pk_mul_f32 v[6:7], v[6:7], v[12:13] op_sel_hi:[1,0]
	s_waitcnt vmcnt(0)
	v_pk_mul_f32 v[0:1], v[28:29], v[0:1]
	v_pk_mul_f32 v[2:3], v[30:31], v[2:3]
	global_store_dwordx4 v[34:35], v[0:3], off offset:3072
	global_load_dwordx4 v[0:3], v[22:23], off offset:3088
	s_waitcnt vmcnt(0)
	v_pk_mul_f32 v[0:1], v[4:5], v[0:1]
	v_pk_mul_f32 v[2:3], v[6:7], v[2:3]
	global_store_dwordx4 v[34:35], v[0:3], off offset:3088
	global_load_dwordx4 v[0:3], v[22:23], off offset:3104
	v_pk_mul_f32 v[4:5], v[38:39], v[12:13] op_sel_hi:[1,0]
	v_pk_mul_f32 v[6:7], v[36:37], v[12:13] op_sel_hi:[1,0]
	s_waitcnt vmcnt(0)
	v_pk_mul_f32 v[0:1], v[4:5], v[0:1]
	v_pk_mul_f32 v[2:3], v[6:7], v[2:3]
	global_store_dwordx4 v[34:35], v[0:3], off offset:3104
	global_load_dwordx4 v[0:3], v[22:23], off offset:3120
	v_pk_mul_f32 v[4:5], v[8:9], v[12:13] op_sel_hi:[1,0]
	v_pk_mul_f32 v[6:7], v[10:11], v[12:13] op_sel_hi:[1,0]
	s_waitcnt vmcnt(0)
	v_pk_mul_f32 v[0:1], v[4:5], v[0:1]
	v_pk_mul_f32 v[2:3], v[6:7], v[2:3]
	global_store_dwordx4 v[34:35], v[0:3], off offset:3120
	v_add_u32_e32 v126, s28, v126
	v_cmp_lt_i32_e64 s[20:21], s30, v126
	s_or_b64 s[24:25], s[20:21], s[24:25]
	s_andn2_b64 exec, exec, s[24:25]
	s_cbranch_execnz .LBB0_496
